# plus nontemporal loads: gate reads in the merge-projection epilogue and residual-stream reads of the second norm
# baseline (speedup 1.0000x reference)
; __device__ __forceinline__ float bf_lo(unsigned w) { return __uint_as_float(w << 16); }
; __device__ __forceinline__ float bf_hi(unsigned w) { return __uint_as_float(w & 0xffff0000u); }
; __device__ __forceinline__ u32x4 pack8(const f32x4 v0, const f32x4 v1) { u32x4 w; w.x = cvt_pk_bf16(v0[0], v0[1]); w.y = cvt_pk_bf16(v0[2], v0[3]); w.z = cvt_pk_bf16(v1[0], v1[1]); w.w = cvt_pk_bf16(v1[2], v1[3]); return w; }
;     __device__ __forceinline__ void operator()(f32x4 (&acc)[2][2][4][2], const Unit& u, int wr, int wc, int fr, int fq) const {
;     ...
;             for (int m = 0; m < 4; ++m) { const size_t row = (size_t)(row0 + ai * HALF + m * 16);
; #pragma unroll
;                 for (int bj = 0; bj < 2; ++bj) {
;                     const u32x4 gb = *(const u32x4*)(QKG + row * QKG_LD + C_SB + col0 + bj * HALF);
;                     f32x4 s0 = (f32x4){bf_lo(gb.x), bf_hi(gb.x), bf_lo(gb.y), bf_hi(gb.y)}, s1 = (f32x4){bf_lo(gb.z), bf_hi(gb.z), bf_lo(gb.w), bf_hi(gb.w)};
;                     if (u.kind == 0) {
;                         const u32x4 ga = *(const u32x4*)(QKG + row * QKG_LD + C_SA + col0 + bj * HALF);
; #pragma unroll
;                         for (int e = 0; e < 4; ++e) { s0[e] = __builtin_amdgcn_rcpf(s0[e]); s1[e] = __builtin_amdgcn_rcpf(s1[e]); }
;                         s0 = s0 * (f32x4){bf_lo(ga.x), bf_hi(ga.x), bf_lo(ga.y), bf_hi(ga.y)}; s1 = s1 * (f32x4){bf_lo(ga.z), bf_hi(ga.z), bf_lo(ga.w), bf_hi(ga.w)};
;                         acc[ai][bj][m][0] = acc[ai][bj][m][0] * s0; acc[ai][bj][m][1] = acc[ai][bj][m][1] * s1;
;                     } else *(u32x4*)(MRG + row * DM + col0 + bj * HALF) = pack8(acc[ai][bj][m][0] * s0, acc[ai][bj][m][1] * s1); }
;                 if (m & 1) asm volatile("" ::: "memory"); }
.LBB0_688:
	v_lshl_or_b32 v2, s25, 8, v151
	v_lshl_add_u32 v132, s51, 8, v150
	v_mov_b64_e32 v[134:135], s[84:85]
	v_ashrrev_i32_e32 v3, 31, v2
	v_mad_i64_i32 v[134:135], s[0:1], v132, s88, v[134:135]
	v_lshl_add_u64 v[134:135], v[2:3], 1, v[134:135]
	v_add_co_u32_e32 v136, vcc, 0x2000, v134
	v_ashrrev_i32_e32 v133, 31, v132
	s_nop 0
	v_addc_co_u32_e32 v137, vcc, 0, v135, vcc
	global_load_dwordx4 v[154:157], v[136:137], off offset:2560 nt
	s_cmp_lg_u32 s24, 0
	v_lshlrev_b64 v[136:137], 12, v[132:133]
	s_cselect_b64 s[24:25], -1, 0
	v_lshl_add_u64 v[136:137], s[92:93], 0, v[136:137]
	s_and_b64 vcc, exec, s[24:25]
	v_lshl_add_u64 v[136:137], v[2:3], 1, v[136:137]
	s_mov_b64 s[52:53], 0x1d0000
	s_waitcnt vmcnt(0)
	v_lshlrev_b32_e32 v140, 16, v154
	v_and_b32_e32 v141, 0xffff0000, v154
	v_lshlrev_b32_e32 v138, 16, v155
	v_and_b32_e32 v139, 0xffff0000, v155
	v_lshlrev_b32_e32 v144, 16, v156
	v_and_b32_e32 v145, 0xffff0000, v156
	v_lshlrev_b32_e32 v142, 16, v157
	v_and_b32_e32 v143, 0xffff0000, v157
	s_cbranch_vccz .LBB0_741
	v_pk_mul_f32 v[156:157], v[130:131], v[138:139]
	v_pk_mul_f32 v[154:155], v[128:129], v[140:141]
	v_pk_mul_f32 v[158:159], v[126:127], v[142:143]
	v_pk_mul_f32 v[160:161], v[124:125], v[144:145]
	v_cvt_pk_bf16_f32 v154, v154, v155
	v_cvt_pk_bf16_f32 v155, v156, v157
	s_nop 0
	v_cvt_pk_bf16_f32 v156, v160, v161
	v_cvt_pk_bf16_f32 v157, v158, v159
	global_store_dwordx4 v[136:137], v[154:157], off
	s_cbranch_execnz .LBB0_691
.LBB0_690:
	s_nop 0
	v_add_co_u32_e32 v154, vcc, 0x1000, v134
	v_rcp_f32_e32 v138, v138
	s_nop 0
	v_addc_co_u32_e32 v155, vcc, 0, v135, vcc
	global_load_dwordx4 v[154:157], v[154:155], off offset:2560 nt
	v_rcp_f32_e32 v139, v139
	v_rcp_f32_e32 v140, v140
	v_rcp_f32_e32 v144, v144
	v_rcp_f32_e32 v141, v141
	v_rcp_f32_e32 v145, v145
	v_rcp_f32_e32 v142, v142
	v_rcp_f32_e32 v143, v143
	s_waitcnt vmcnt(0)
	v_lshlrev_b32_e32 v158, 16, v154
	v_and_b32_e32 v159, 0xffff0000, v154
	v_lshlrev_b32_e32 v154, 16, v155
	v_and_b32_e32 v155, 0xffff0000, v155
	v_pk_mul_f32 v[138:139], v[138:139], v[154:155]
	v_lshlrev_b32_e32 v154, 16, v156
	v_and_b32_e32 v155, 0xffff0000, v156
	v_lshlrev_b32_e32 v156, 16, v157
	v_and_b32_e32 v157, 0xffff0000, v157
	v_pk_mul_f32 v[140:141], v[140:141], v[158:159]
	v_pk_mul_f32 v[144:145], v[144:145], v[154:155]
	v_pk_mul_f32 v[142:143], v[142:143], v[156:157]
	v_pk_mul_f32 v[130:131], v[130:131], v[138:139]
	v_pk_mul_f32 v[128:129], v[128:129], v[140:141]
	v_pk_mul_f32 v[126:127], v[126:127], v[142:143]
	v_pk_mul_f32 v[124:125], v[124:125], v[144:145]
.LBB0_691:
	v_add_co_u32_e32 v138, vcc, 0x2000, v134
	v_cndmask_b32_e64 v0, 0, 1, s[24:25]
	s_nop 0
	v_addc_co_u32_e32 v139, vcc, 0, v135, vcc
	global_load_dwordx4 v[154:157], v[138:139], off offset:2816 nt
	v_cmp_ne_u32_e64 s[0:1], 1, v0
	s_andn2_b64 vcc, exec, s[24:25]
	s_waitcnt vmcnt(0)
	v_lshlrev_b32_e32 v140, 16, v154
	v_and_b32_e32 v141, 0xffff0000, v154
	v_lshlrev_b32_e32 v138, 16, v155
	v_and_b32_e32 v139, 0xffff0000, v155
	v_lshlrev_b32_e32 v144, 16, v156
	v_and_b32_e32 v145, 0xffff0000, v156
	v_lshlrev_b32_e32 v142, 16, v157
	v_and_b32_e32 v143, 0xffff0000, v157
	s_cbranch_vccnz .LBB0_742
	v_pk_mul_f32 v[156:157], v[98:99], v[138:139]
	v_pk_mul_f32 v[154:155], v[96:97], v[140:141]
	v_pk_mul_f32 v[158:159], v[94:95], v[142:143]
	v_pk_mul_f32 v[160:161], v[92:93], v[144:145]
	v_cvt_pk_bf16_f32 v154, v154, v155
	v_cvt_pk_bf16_f32 v155, v156, v157
	s_nop 0
	v_cvt_pk_bf16_f32 v156, v160, v161
	v_cvt_pk_bf16_f32 v157, v158, v159
	global_store_dwordx4 v[136:137], v[154:157], off offset:256
	s_cbranch_execnz .LBB0_694
.LBB0_693:
	v_add_co_u32_e32 v134, vcc, 0x1000, v134
	v_rcp_f32_e32 v138, v138
	s_nop 0
	v_addc_co_u32_e32 v135, vcc, 0, v135, vcc
	global_load_dwordx4 v[134:137], v[134:135], off offset:2816 nt
	v_rcp_f32_e32 v139, v139
	v_rcp_f32_e32 v140, v140
	v_rcp_f32_e32 v144, v144
	v_rcp_f32_e32 v141, v141
	v_rcp_f32_e32 v145, v145
	v_rcp_f32_e32 v142, v142
	v_rcp_f32_e32 v143, v143
	s_waitcnt vmcnt(0)
	v_lshlrev_b32_e32 v154, 16, v134
	v_and_b32_e32 v155, 0xffff0000, v134
	v_lshlrev_b32_e32 v134, 16, v135
	v_and_b32_e32 v135, 0xffff0000, v135
	v_pk_mul_f32 v[134:135], v[138:139], v[134:135]
	v_lshlrev_b32_e32 v138, 16, v136
	v_and_b32_e32 v139, 0xffff0000, v136
	v_lshlrev_b32_e32 v136, 16, v137
	v_and_b32_e32 v137, 0xffff0000, v137
	v_pk_mul_f32 v[140:141], v[140:141], v[154:155]
	v_pk_mul_f32 v[138:139], v[144:145], v[138:139]
	v_pk_mul_f32 v[136:137], v[142:143], v[136:137]
	v_pk_mul_f32 v[98:99], v[98:99], v[134:135]
	v_pk_mul_f32 v[96:97], v[96:97], v[140:141]
	v_pk_mul_f32 v[94:95], v[94:95], v[136:137]
	v_pk_mul_f32 v[92:93], v[92:93], v[138:139]
.LBB0_694:
	v_or_b32_e32 v136, 16, v132
	v_mov_b64_e32 v[134:135], s[84:85]
	v_mad_i64_i32 v[134:135], s[24:25], v136, s88, v[134:135]
	v_lshl_add_u64 v[134:135], v[2:3], 1, v[134:135]
	v_add_co_u32_e32 v138, vcc, 0x2000, v134
	v_ashrrev_i32_e32 v137, 31, v136
	s_nop 0
	v_addc_co_u32_e32 v139, vcc, 0, v135, vcc
	global_load_dwordx4 v[154:157], v[138:139], off offset:2560 nt
	v_lshlrev_b64 v[136:137], 12, v[136:137]
	v_lshl_add_u64 v[136:137], s[92:93], 0, v[136:137]
	s_and_b64 vcc, exec, s[0:1]
	v_lshl_add_u64 v[136:137], v[2:3], 1, v[136:137]
	s_waitcnt vmcnt(0)
	v_lshlrev_b32_e32 v140, 16, v154
	v_and_b32_e32 v141, 0xffff0000, v154
	v_lshlrev_b32_e32 v138, 16, v155
	v_and_b32_e32 v139, 0xffff0000, v155
	v_lshlrev_b32_e32 v144, 16, v156
	v_and_b32_e32 v145, 0xffff0000, v156
	v_lshlrev_b32_e32 v142, 16, v157
	v_and_b32_e32 v143, 0xffff0000, v157
	s_cbranch_vccnz .LBB0_743
	v_pk_mul_f32 v[156:157], v[122:123], v[138:139]
	v_pk_mul_f32 v[154:155], v[120:121], v[140:141]
	v_pk_mul_f32 v[158:159], v[118:119], v[142:143]
	v_pk_mul_f32 v[160:161], v[116:117], v[144:145]
	v_cvt_pk_bf16_f32 v154, v154, v155
	v_cvt_pk_bf16_f32 v155, v156, v157
	s_nop 0
	v_cvt_pk_bf16_f32 v156, v160, v161
	v_cvt_pk_bf16_f32 v157, v158, v159
	global_store_dwordx4 v[136:137], v[154:157], off
	s_cbranch_execnz .LBB0_697
; __device__ __forceinline__ float bf_lo(unsigned w) { return __uint_as_float(w << 16); }
; __device__ __forceinline__ float bf_hi(unsigned w) { return __uint_as_float(w & 0xffff0000u); }
; __device__ __forceinline__ u32x4 pack8(const f32x4 v0, const f32x4 v1) { u32x4 w; w.x = cvt_pk_bf16(v0[0], v0[1]); w.y = cvt_pk_bf16(v0[2], v0[3]); w.z = cvt_pk_bf16(v1[0], v1[1]); w.w = cvt_pk_bf16(v1[2], v1[3]); return w; }
;     __device__ __forceinline__ void operator()(f32x4 (&acc)[2][2][4][2], const Unit& u, int wr, int wc, int fr, int fq) const {
;     ...
;             for (int m = 0; m < 4; ++m) { const size_t row = (size_t)(row0 + ai * HALF + m * 16);
; #pragma unroll
;                 for (int bj = 0; bj < 2; ++bj) {
;                     const u32x4 gb = *(const u32x4*)(QKG + row * QKG_LD + C_SB + col0 + bj * HALF);
;                     f32x4 s0 = (f32x4){bf_lo(gb.x), bf_hi(gb.x), bf_lo(gb.y), bf_hi(gb.y)}, s1 = (f32x4){bf_lo(gb.z), bf_hi(gb.z), bf_lo(gb.w), bf_hi(gb.w)};
;                     if (u.kind == 0) {
;                         const u32x4 ga = *(const u32x4*)(QKG + row * QKG_LD + C_SA + col0 + bj * HALF);
; #pragma unroll
;                         for (int e = 0; e < 4; ++e) { s0[e] = __builtin_amdgcn_rcpf(s0[e]); s1[e] = __builtin_amdgcn_rcpf(s1[e]); }
;                         s0 = s0 * (f32x4){bf_lo(ga.x), bf_hi(ga.x), bf_lo(ga.y), bf_hi(ga.y)}; s1 = s1 * (f32x4){bf_lo(ga.z), bf_hi(ga.z), bf_lo(ga.w), bf_hi(ga.w)};
;                         acc[ai][bj][m][0] = acc[ai][bj][m][0] * s0; acc[ai][bj][m][1] = acc[ai][bj][m][1] * s1;
;                     } else *(u32x4*)(MRG + row * DM + col0 + bj * HALF) = pack8(acc[ai][bj][m][0] * s0, acc[ai][bj][m][1] * s1); }
;                 if (m & 1) asm volatile("" ::: "memory"); }
.LBB0_696:
	s_nop 0
	v_add_co_u32_e32 v154, vcc, 0x1000, v134
	v_rcp_f32_e32 v138, v138
	s_nop 0
	v_addc_co_u32_e32 v155, vcc, 0, v135, vcc
	global_load_dwordx4 v[154:157], v[154:155], off offset:2560 nt
	v_rcp_f32_e32 v139, v139
	v_rcp_f32_e32 v140, v140
	v_rcp_f32_e32 v144, v144
	v_rcp_f32_e32 v141, v141
	v_rcp_f32_e32 v145, v145
	v_rcp_f32_e32 v142, v142
	v_rcp_f32_e32 v143, v143
	s_waitcnt vmcnt(0)
	v_lshlrev_b32_e32 v158, 16, v154
	v_and_b32_e32 v159, 0xffff0000, v154
	v_lshlrev_b32_e32 v154, 16, v155
	v_and_b32_e32 v155, 0xffff0000, v155
	v_pk_mul_f32 v[138:139], v[138:139], v[154:155]
	v_lshlrev_b32_e32 v154, 16, v156
	v_and_b32_e32 v155, 0xffff0000, v156
	v_lshlrev_b32_e32 v156, 16, v157
	v_and_b32_e32 v157, 0xffff0000, v157
	v_pk_mul_f32 v[140:141], v[140:141], v[158:159]
	v_pk_mul_f32 v[144:145], v[144:145], v[154:155]
	v_pk_mul_f32 v[142:143], v[142:143], v[156:157]
	v_pk_mul_f32 v[122:123], v[122:123], v[138:139]
	v_pk_mul_f32 v[120:121], v[120:121], v[140:141]
	v_pk_mul_f32 v[118:119], v[118:119], v[142:143]
	v_pk_mul_f32 v[116:117], v[116:117], v[144:145]
.LBB0_697:
	v_add_co_u32_e32 v138, vcc, 0x2000, v134
	s_nop 1
	v_addc_co_u32_e32 v139, vcc, 0, v135, vcc
	global_load_dwordx4 v[154:157], v[138:139], off offset:2816 nt
	s_and_b64 vcc, exec, s[0:1]
	s_waitcnt vmcnt(0)
	v_lshlrev_b32_e32 v140, 16, v154
	v_and_b32_e32 v141, 0xffff0000, v154
	v_lshlrev_b32_e32 v138, 16, v155
	v_and_b32_e32 v139, 0xffff0000, v155
	v_lshlrev_b32_e32 v144, 16, v156
	v_and_b32_e32 v145, 0xffff0000, v156
	v_lshlrev_b32_e32 v142, 16, v157
	v_and_b32_e32 v143, 0xffff0000, v157
	s_cbranch_vccnz .LBB0_744
	v_pk_mul_f32 v[156:157], v[90:91], v[138:139]
	v_pk_mul_f32 v[154:155], v[88:89], v[140:141]
	v_pk_mul_f32 v[158:159], v[86:87], v[142:143]
	v_pk_mul_f32 v[160:161], v[84:85], v[144:145]
	v_cvt_pk_bf16_f32 v154, v154, v155
	v_cvt_pk_bf16_f32 v155, v156, v157
	s_nop 0
	v_cvt_pk_bf16_f32 v156, v160, v161
	v_cvt_pk_bf16_f32 v157, v158, v159
	global_store_dwordx4 v[136:137], v[154:157], off offset:256
	s_cbranch_execnz .LBB0_700
.LBB0_699:
	v_add_co_u32_e32 v134, vcc, 0x1000, v134
	v_rcp_f32_e32 v138, v138
	s_nop 0
	v_addc_co_u32_e32 v135, vcc, 0, v135, vcc
	global_load_dwordx4 v[134:137], v[134:135], off offset:2816 nt
	v_rcp_f32_e32 v139, v139
	v_rcp_f32_e32 v140, v140
	v_rcp_f32_e32 v144, v144
	v_rcp_f32_e32 v141, v141
	v_rcp_f32_e32 v145, v145
	v_rcp_f32_e32 v142, v142
	v_rcp_f32_e32 v143, v143
	s_waitcnt vmcnt(0)
	v_lshlrev_b32_e32 v154, 16, v134
	v_and_b32_e32 v155, 0xffff0000, v134
	v_lshlrev_b32_e32 v134, 16, v135
	v_and_b32_e32 v135, 0xffff0000, v135
	v_pk_mul_f32 v[134:135], v[138:139], v[134:135]
	v_lshlrev_b32_e32 v138, 16, v136
	v_and_b32_e32 v139, 0xffff0000, v136
	v_lshlrev_b32_e32 v136, 16, v137
	v_and_b32_e32 v137, 0xffff0000, v137
	v_pk_mul_f32 v[140:141], v[140:141], v[154:155]
	v_pk_mul_f32 v[138:139], v[144:145], v[138:139]
	v_pk_mul_f32 v[136:137], v[142:143], v[136:137]
	v_pk_mul_f32 v[90:91], v[90:91], v[134:135]
	v_pk_mul_f32 v[88:89], v[88:89], v[140:141]
	v_pk_mul_f32 v[86:87], v[86:87], v[136:137]
	v_pk_mul_f32 v[84:85], v[84:85], v[138:139]
.LBB0_700:
	v_or_b32_e32 v136, 32, v132
	v_mov_b64_e32 v[134:135], s[84:85]
	v_mad_i64_i32 v[134:135], s[24:25], v136, s88, v[134:135]
	v_lshl_add_u64 v[134:135], v[2:3], 1, v[134:135]
	v_add_co_u32_e32 v138, vcc, 0x2000, v134
	v_ashrrev_i32_e32 v137, 31, v136
	s_nop 0
	v_addc_co_u32_e32 v139, vcc, 0, v135, vcc
	global_load_dwordx4 v[154:157], v[138:139], off offset:2560 nt
	v_lshlrev_b64 v[136:137], 12, v[136:137]
	v_lshl_add_u64 v[136:137], s[92:93], 0, v[136:137]
	s_and_b64 vcc, exec, s[0:1]
	v_lshl_add_u64 v[136:137], v[2:3], 1, v[136:137]
	s_waitcnt vmcnt(0)
	v_lshlrev_b32_e32 v140, 16, v154
	v_and_b32_e32 v141, 0xffff0000, v154
	v_lshlrev_b32_e32 v138, 16, v155
	v_and_b32_e32 v139, 0xffff0000, v155
	v_lshlrev_b32_e32 v144, 16, v156
	v_and_b32_e32 v145, 0xffff0000, v156
	v_lshlrev_b32_e32 v142, 16, v157
	v_and_b32_e32 v143, 0xffff0000, v157
	s_cbranch_vccnz .LBB0_745
	v_pk_mul_f32 v[156:157], v[114:115], v[138:139]
	v_pk_mul_f32 v[154:155], v[112:113], v[140:141]
	v_pk_mul_f32 v[158:159], v[110:111], v[142:143]
	v_pk_mul_f32 v[160:161], v[108:109], v[144:145]
	v_cvt_pk_bf16_f32 v154, v154, v155
	v_cvt_pk_bf16_f32 v155, v156, v157
	s_nop 0
	v_cvt_pk_bf16_f32 v156, v160, v161
	v_cvt_pk_bf16_f32 v157, v158, v159
	global_store_dwordx4 v[136:137], v[154:157], off
	s_cbranch_execnz .LBB0_703
.LBB0_702:
	s_nop 0
	v_add_co_u32_e32 v154, vcc, 0x1000, v134
	v_rcp_f32_e32 v138, v138
	s_nop 0
	v_addc_co_u32_e32 v155, vcc, 0, v135, vcc
	global_load_dwordx4 v[154:157], v[154:155], off offset:2560 nt
	v_rcp_f32_e32 v139, v139
	v_rcp_f32_e32 v140, v140
	v_rcp_f32_e32 v144, v144
	v_rcp_f32_e32 v141, v141
	v_rcp_f32_e32 v145, v145
	v_rcp_f32_e32 v142, v142
	v_rcp_f32_e32 v143, v143
	s_waitcnt vmcnt(0)
	v_lshlrev_b32_e32 v158, 16, v154
	v_and_b32_e32 v159, 0xffff0000, v154
	v_lshlrev_b32_e32 v154, 16, v155
	v_and_b32_e32 v155, 0xffff0000, v155
	v_pk_mul_f32 v[138:139], v[138:139], v[154:155]
	v_lshlrev_b32_e32 v154, 16, v156
	v_and_b32_e32 v155, 0xffff0000, v156
	v_lshlrev_b32_e32 v156, 16, v157
	v_and_b32_e32 v157, 0xffff0000, v157
	v_pk_mul_f32 v[140:141], v[140:141], v[158:159]
	v_pk_mul_f32 v[144:145], v[144:145], v[154:155]
	v_pk_mul_f32 v[142:143], v[142:143], v[156:157]
	v_pk_mul_f32 v[114:115], v[114:115], v[138:139]
	v_pk_mul_f32 v[112:113], v[112:113], v[140:141]
	v_pk_mul_f32 v[110:111], v[110:111], v[142:143]
	v_pk_mul_f32 v[108:109], v[108:109], v[144:145]
; __device__ __forceinline__ float bf_lo(unsigned w) { return __uint_as_float(w << 16); }
; __device__ __forceinline__ float bf_hi(unsigned w) { return __uint_as_float(w & 0xffff0000u); }
; __device__ __forceinline__ u32x4 pack8(const f32x4 v0, const f32x4 v1) { u32x4 w; w.x = cvt_pk_bf16(v0[0], v0[1]); w.y = cvt_pk_bf16(v0[2], v0[3]); w.z = cvt_pk_bf16(v1[0], v1[1]); w.w = cvt_pk_bf16(v1[2], v1[3]); return w; }
;     __device__ __forceinline__ void operator()(f32x4 (&acc)[2][2][4][2], const Unit& u, int wr, int wc, int fr, int fq) const {
;     ...
;             for (int m = 0; m < 4; ++m) { const size_t row = (size_t)(row0 + ai * HALF + m * 16);
; #pragma unroll
;                 for (int bj = 0; bj < 2; ++bj) {
;                     const u32x4 gb = *(const u32x4*)(QKG + row * QKG_LD + C_SB + col0 + bj * HALF);
;                     f32x4 s0 = (f32x4){bf_lo(gb.x), bf_hi(gb.x), bf_lo(gb.y), bf_hi(gb.y)}, s1 = (f32x4){bf_lo(gb.z), bf_hi(gb.z), bf_lo(gb.w), bf_hi(gb.w)};
;                     if (u.kind == 0) {
;                         const u32x4 ga = *(const u32x4*)(QKG + row * QKG_LD + C_SA + col0 + bj * HALF);
; #pragma unroll
;                         for (int e = 0; e < 4; ++e) { s0[e] = __builtin_amdgcn_rcpf(s0[e]); s1[e] = __builtin_amdgcn_rcpf(s1[e]); }
;                         s0 = s0 * (f32x4){bf_lo(ga.x), bf_hi(ga.x), bf_lo(ga.y), bf_hi(ga.y)}; s1 = s1 * (f32x4){bf_lo(ga.z), bf_hi(ga.z), bf_lo(ga.w), bf_hi(ga.w)};
;                         acc[ai][bj][m][0] = acc[ai][bj][m][0] * s0; acc[ai][bj][m][1] = acc[ai][bj][m][1] * s1;
;                     } else *(u32x4*)(MRG + row * DM + col0 + bj * HALF) = pack8(acc[ai][bj][m][0] * s0, acc[ai][bj][m][1] * s1); }
;                 if (m & 1) asm volatile("" ::: "memory"); }
.LBB0_703:
	v_add_co_u32_e32 v138, vcc, 0x2000, v134
	s_nop 1
	v_addc_co_u32_e32 v139, vcc, 0, v135, vcc
	global_load_dwordx4 v[154:157], v[138:139], off offset:2816 nt
	s_and_b64 vcc, exec, s[0:1]
	s_waitcnt vmcnt(0)
	v_lshlrev_b32_e32 v140, 16, v154
	v_and_b32_e32 v141, 0xffff0000, v154
	v_lshlrev_b32_e32 v138, 16, v155
	v_and_b32_e32 v139, 0xffff0000, v155
	v_lshlrev_b32_e32 v144, 16, v156
	v_and_b32_e32 v145, 0xffff0000, v156
	v_lshlrev_b32_e32 v142, 16, v157
	v_and_b32_e32 v143, 0xffff0000, v157
	s_cbranch_vccnz .LBB0_746
	v_pk_mul_f32 v[156:157], v[82:83], v[138:139]
	v_pk_mul_f32 v[154:155], v[80:81], v[140:141]
	v_pk_mul_f32 v[158:159], v[78:79], v[142:143]
	v_pk_mul_f32 v[160:161], v[76:77], v[144:145]
	v_cvt_pk_bf16_f32 v154, v154, v155
	v_cvt_pk_bf16_f32 v155, v156, v157
	s_nop 0
	v_cvt_pk_bf16_f32 v156, v160, v161
	v_cvt_pk_bf16_f32 v157, v158, v159
	global_store_dwordx4 v[136:137], v[154:157], off offset:256
	s_cbranch_execnz .LBB0_706
.LBB0_705:
	v_add_co_u32_e32 v134, vcc, 0x1000, v134
	v_rcp_f32_e32 v138, v138
	s_nop 0
	v_addc_co_u32_e32 v135, vcc, 0, v135, vcc
	global_load_dwordx4 v[134:137], v[134:135], off offset:2816 nt
	v_rcp_f32_e32 v139, v139
	v_rcp_f32_e32 v140, v140
	v_rcp_f32_e32 v144, v144
	v_rcp_f32_e32 v141, v141
	v_rcp_f32_e32 v145, v145
	v_rcp_f32_e32 v142, v142
	v_rcp_f32_e32 v143, v143
	s_waitcnt vmcnt(0)
	v_lshlrev_b32_e32 v154, 16, v134
	v_and_b32_e32 v155, 0xffff0000, v134
	v_lshlrev_b32_e32 v134, 16, v135
	v_and_b32_e32 v135, 0xffff0000, v135
	v_pk_mul_f32 v[134:135], v[138:139], v[134:135]
	v_lshlrev_b32_e32 v138, 16, v136
	v_and_b32_e32 v139, 0xffff0000, v136
	v_lshlrev_b32_e32 v136, 16, v137
	v_and_b32_e32 v137, 0xffff0000, v137
	v_pk_mul_f32 v[140:141], v[140:141], v[154:155]
	v_pk_mul_f32 v[138:139], v[144:145], v[138:139]
	v_pk_mul_f32 v[136:137], v[142:143], v[136:137]
	v_pk_mul_f32 v[82:83], v[82:83], v[134:135]
	v_pk_mul_f32 v[80:81], v[80:81], v[140:141]
	v_pk_mul_f32 v[78:79], v[78:79], v[136:137]
	v_pk_mul_f32 v[76:77], v[76:77], v[138:139]
.LBB0_706:
	v_or_b32_e32 v136, 48, v132
	v_mov_b64_e32 v[134:135], s[84:85]
	v_mad_i64_i32 v[134:135], s[24:25], v136, s88, v[134:135]
	v_lshl_add_u64 v[134:135], v[2:3], 1, v[134:135]
	v_add_co_u32_e32 v138, vcc, 0x2000, v134
	v_ashrrev_i32_e32 v137, 31, v136
	s_nop 0
	v_addc_co_u32_e32 v139, vcc, 0, v135, vcc
	global_load_dwordx4 v[154:157], v[138:139], off offset:2560 nt
	v_lshlrev_b64 v[136:137], 12, v[136:137]
	v_lshl_add_u64 v[136:137], s[92:93], 0, v[136:137]
	s_and_b64 vcc, exec, s[0:1]
	v_lshl_add_u64 v[136:137], v[2:3], 1, v[136:137]
	s_waitcnt vmcnt(0)
	v_lshlrev_b32_e32 v140, 16, v154
	v_and_b32_e32 v141, 0xffff0000, v154
	v_lshlrev_b32_e32 v138, 16, v155
	v_and_b32_e32 v139, 0xffff0000, v155
	v_lshlrev_b32_e32 v144, 16, v156
	v_and_b32_e32 v145, 0xffff0000, v156
	v_lshlrev_b32_e32 v142, 16, v157
	v_and_b32_e32 v143, 0xffff0000, v157
	s_cbranch_vccnz .LBB0_747
	v_pk_mul_f32 v[156:157], v[106:107], v[138:139]
	v_pk_mul_f32 v[154:155], v[104:105], v[140:141]
	v_pk_mul_f32 v[158:159], v[102:103], v[142:143]
	v_pk_mul_f32 v[160:161], v[100:101], v[144:145]
	v_cvt_pk_bf16_f32 v154, v154, v155
	v_cvt_pk_bf16_f32 v155, v156, v157
	s_nop 0
	v_cvt_pk_bf16_f32 v156, v160, v161
	v_cvt_pk_bf16_f32 v157, v158, v159
	global_store_dwordx4 v[136:137], v[154:157], off
	s_cbranch_execnz .LBB0_709
.LBB0_708:
	s_nop 0
	v_add_co_u32_e32 v154, vcc, 0x1000, v134
	v_rcp_f32_e32 v138, v138
	s_nop 0
	v_addc_co_u32_e32 v155, vcc, 0, v135, vcc
	global_load_dwordx4 v[154:157], v[154:155], off offset:2560 nt
	v_rcp_f32_e32 v139, v139
	v_rcp_f32_e32 v140, v140
	v_rcp_f32_e32 v144, v144
	v_rcp_f32_e32 v141, v141
	v_rcp_f32_e32 v145, v145
	v_rcp_f32_e32 v142, v142
	v_rcp_f32_e32 v143, v143
	s_waitcnt vmcnt(0)
	v_lshlrev_b32_e32 v158, 16, v154
	v_and_b32_e32 v159, 0xffff0000, v154
	v_lshlrev_b32_e32 v154, 16, v155
	v_and_b32_e32 v155, 0xffff0000, v155
	v_pk_mul_f32 v[138:139], v[138:139], v[154:155]
	v_lshlrev_b32_e32 v154, 16, v156
	v_and_b32_e32 v155, 0xffff0000, v156
	v_lshlrev_b32_e32 v156, 16, v157
	v_and_b32_e32 v157, 0xffff0000, v157
	v_pk_mul_f32 v[140:141], v[140:141], v[158:159]
	v_pk_mul_f32 v[144:145], v[144:145], v[154:155]
	v_pk_mul_f32 v[142:143], v[142:143], v[156:157]
	v_pk_mul_f32 v[106:107], v[106:107], v[138:139]
	v_pk_mul_f32 v[104:105], v[104:105], v[140:141]
	v_pk_mul_f32 v[102:103], v[102:103], v[142:143]
	v_pk_mul_f32 v[100:101], v[100:101], v[144:145]
.LBB0_709:
	v_add_co_u32_e32 v138, vcc, 0x2000, v134
	s_nop 1
	v_addc_co_u32_e32 v139, vcc, 0, v135, vcc
	global_load_dwordx4 v[154:157], v[138:139], off offset:2816 nt
	s_and_b64 vcc, exec, s[0:1]
	s_waitcnt vmcnt(0)
	v_lshlrev_b32_e32 v140, 16, v154
	v_and_b32_e32 v141, 0xffff0000, v154
	v_lshlrev_b32_e32 v138, 16, v155
	v_and_b32_e32 v139, 0xffff0000, v155
	v_lshlrev_b32_e32 v144, 16, v156
	v_and_b32_e32 v145, 0xffff0000, v156
	v_lshlrev_b32_e32 v142, 16, v157
	v_and_b32_e32 v143, 0xffff0000, v157
	s_cbranch_vccnz .LBB0_748
	v_pk_mul_f32 v[156:157], v[70:71], v[138:139]
	v_pk_mul_f32 v[154:155], v[68:69], v[140:141]
	v_pk_mul_f32 v[158:159], v[62:63], v[142:143]
	v_pk_mul_f32 v[160:161], v[60:61], v[144:145]
	v_cvt_pk_bf16_f32 v154, v154, v155
	v_cvt_pk_bf16_f32 v155, v156, v157
	s_nop 0
	v_cvt_pk_bf16_f32 v156, v160, v161
	v_cvt_pk_bf16_f32 v157, v158, v159
	global_store_dwordx4 v[136:137], v[154:157], off offset:256
	s_cbranch_execnz .LBB0_712
; __device__ __forceinline__ float bf_lo(unsigned w) { return __uint_as_float(w << 16); }
; __device__ __forceinline__ float bf_hi(unsigned w) { return __uint_as_float(w & 0xffff0000u); }
; __device__ __forceinline__ u32x4 pack8(const f32x4 v0, const f32x4 v1) { u32x4 w; w.x = cvt_pk_bf16(v0[0], v0[1]); w.y = cvt_pk_bf16(v0[2], v0[3]); w.z = cvt_pk_bf16(v1[0], v1[1]); w.w = cvt_pk_bf16(v1[2], v1[3]); return w; }
;     __device__ __forceinline__ void operator()(f32x4 (&acc)[2][2][4][2], const Unit& u, int wr, int wc, int fr, int fq) const {
;     ...
;             for (int m = 0; m < 4; ++m) { const size_t row = (size_t)(row0 + ai * HALF + m * 16);
; #pragma unroll
;                 for (int bj = 0; bj < 2; ++bj) {
;                     const u32x4 gb = *(const u32x4*)(QKG + row * QKG_LD + C_SB + col0 + bj * HALF);
;                     f32x4 s0 = (f32x4){bf_lo(gb.x), bf_hi(gb.x), bf_lo(gb.y), bf_hi(gb.y)}, s1 = (f32x4){bf_lo(gb.z), bf_hi(gb.z), bf_lo(gb.w), bf_hi(gb.w)};
;                     if (u.kind == 0) {
;                         const u32x4 ga = *(const u32x4*)(QKG + row * QKG_LD + C_SA + col0 + bj * HALF);
; #pragma unroll
;                         for (int e = 0; e < 4; ++e) { s0[e] = __builtin_amdgcn_rcpf(s0[e]); s1[e] = __builtin_amdgcn_rcpf(s1[e]); }
;                         s0 = s0 * (f32x4){bf_lo(ga.x), bf_hi(ga.x), bf_lo(ga.y), bf_hi(ga.y)}; s1 = s1 * (f32x4){bf_lo(ga.z), bf_hi(ga.z), bf_lo(ga.w), bf_hi(ga.w)};
;                         acc[ai][bj][m][0] = acc[ai][bj][m][0] * s0; acc[ai][bj][m][1] = acc[ai][bj][m][1] * s1;
;                     } else *(u32x4*)(MRG + row * DM + col0 + bj * HALF) = pack8(acc[ai][bj][m][0] * s0, acc[ai][bj][m][1] * s1); }
;                 if (m & 1) asm volatile("" ::: "memory"); }
.LBB0_711:
	v_add_co_u32_e32 v134, vcc, 0x1000, v134
	v_rcp_f32_e32 v138, v138
	s_nop 0
	v_addc_co_u32_e32 v135, vcc, 0, v135, vcc
	global_load_dwordx4 v[134:137], v[134:135], off offset:2816 nt
	v_rcp_f32_e32 v139, v139
	v_rcp_f32_e32 v140, v140
	v_rcp_f32_e32 v144, v144
	v_rcp_f32_e32 v141, v141
	v_rcp_f32_e32 v145, v145
	v_rcp_f32_e32 v142, v142
	v_rcp_f32_e32 v143, v143
	s_waitcnt vmcnt(0)
	v_lshlrev_b32_e32 v154, 16, v134
	v_and_b32_e32 v155, 0xffff0000, v134
	v_lshlrev_b32_e32 v134, 16, v135
	v_and_b32_e32 v135, 0xffff0000, v135
	v_pk_mul_f32 v[134:135], v[138:139], v[134:135]
	v_lshlrev_b32_e32 v138, 16, v136
	v_and_b32_e32 v139, 0xffff0000, v136
	v_lshlrev_b32_e32 v136, 16, v137
	v_and_b32_e32 v137, 0xffff0000, v137
	v_pk_mul_f32 v[140:141], v[140:141], v[154:155]
	v_pk_mul_f32 v[138:139], v[144:145], v[138:139]
	v_pk_mul_f32 v[136:137], v[142:143], v[136:137]
	v_pk_mul_f32 v[70:71], v[70:71], v[134:135]
	v_pk_mul_f32 v[68:69], v[68:69], v[140:141]
	v_pk_mul_f32 v[62:63], v[62:63], v[136:137]
	v_pk_mul_f32 v[60:61], v[60:61], v[138:139]
.LBB0_712:
	v_add_u32_e32 v136, 0x80, v132
	v_mov_b64_e32 v[134:135], s[84:85]
	v_mad_i64_i32 v[134:135], s[24:25], v136, s88, v[134:135]
	v_lshl_add_u64 v[134:135], v[2:3], 1, v[134:135]
	v_add_co_u32_e32 v138, vcc, 0x2000, v134
	v_ashrrev_i32_e32 v137, 31, v136
	s_nop 0
	v_addc_co_u32_e32 v139, vcc, 0, v135, vcc
	global_load_dwordx4 v[154:157], v[138:139], off offset:2560 nt
	v_lshlrev_b64 v[136:137], 12, v[136:137]
	v_lshl_add_u64 v[136:137], s[92:93], 0, v[136:137]
	s_and_b64 vcc, exec, s[0:1]
	v_lshl_add_u64 v[136:137], v[2:3], 1, v[136:137]
	s_waitcnt vmcnt(0)
	v_lshlrev_b32_e32 v140, 16, v154
	v_and_b32_e32 v141, 0xffff0000, v154
	v_lshlrev_b32_e32 v138, 16, v155
	v_and_b32_e32 v139, 0xffff0000, v155
	v_lshlrev_b32_e32 v144, 16, v156
	v_and_b32_e32 v145, 0xffff0000, v156
	v_lshlrev_b32_e32 v142, 16, v157
	v_and_b32_e32 v143, 0xffff0000, v157
	s_cbranch_vccnz .LBB0_749
	v_pk_mul_f32 v[156:157], v[74:75], v[138:139]
	v_pk_mul_f32 v[154:155], v[72:73], v[140:141]
	v_pk_mul_f32 v[158:159], v[66:67], v[142:143]
	v_pk_mul_f32 v[160:161], v[64:65], v[144:145]
	v_cvt_pk_bf16_f32 v154, v154, v155
	v_cvt_pk_bf16_f32 v155, v156, v157
	s_nop 0
	v_cvt_pk_bf16_f32 v156, v160, v161
	v_cvt_pk_bf16_f32 v157, v158, v159
	global_store_dwordx4 v[136:137], v[154:157], off
	s_cbranch_execnz .LBB0_715
.LBB0_714:
	s_nop 0
	v_add_co_u32_e32 v154, vcc, 0x1000, v134
	v_rcp_f32_e32 v138, v138
	s_nop 0
	v_addc_co_u32_e32 v155, vcc, 0, v135, vcc
	global_load_dwordx4 v[154:157], v[154:155], off offset:2560 nt
	v_rcp_f32_e32 v139, v139
	v_rcp_f32_e32 v140, v140
	v_rcp_f32_e32 v144, v144
	v_rcp_f32_e32 v141, v141
	v_rcp_f32_e32 v145, v145
	v_rcp_f32_e32 v142, v142
	v_rcp_f32_e32 v143, v143
	s_waitcnt vmcnt(0)
	v_lshlrev_b32_e32 v158, 16, v154
	v_and_b32_e32 v159, 0xffff0000, v154
	v_lshlrev_b32_e32 v154, 16, v155
	v_and_b32_e32 v155, 0xffff0000, v155
	v_pk_mul_f32 v[138:139], v[138:139], v[154:155]
	v_lshlrev_b32_e32 v154, 16, v156
	v_and_b32_e32 v155, 0xffff0000, v156
	v_lshlrev_b32_e32 v156, 16, v157
	v_and_b32_e32 v157, 0xffff0000, v157
	v_pk_mul_f32 v[140:141], v[140:141], v[158:159]
	v_pk_mul_f32 v[144:145], v[144:145], v[154:155]
	v_pk_mul_f32 v[142:143], v[142:143], v[156:157]
	v_pk_mul_f32 v[74:75], v[74:75], v[138:139]
	v_pk_mul_f32 v[72:73], v[72:73], v[140:141]
	v_pk_mul_f32 v[66:67], v[66:67], v[142:143]
	v_pk_mul_f32 v[64:65], v[64:65], v[144:145]
.LBB0_715:
	v_add_co_u32_e32 v138, vcc, 0x2000, v134
	s_nop 1
	v_addc_co_u32_e32 v139, vcc, 0, v135, vcc
	global_load_dwordx4 v[154:157], v[138:139], off offset:2816 nt
	s_and_b64 vcc, exec, s[0:1]
	s_waitcnt vmcnt(0)
	v_lshlrev_b32_e32 v140, 16, v154
	v_and_b32_e32 v141, 0xffff0000, v154
	v_lshlrev_b32_e32 v138, 16, v155
	v_and_b32_e32 v139, 0xffff0000, v155
	v_lshlrev_b32_e32 v144, 16, v156
	v_and_b32_e32 v145, 0xffff0000, v156
	v_lshlrev_b32_e32 v142, 16, v157
	v_and_b32_e32 v143, 0xffff0000, v157
	s_cbranch_vccnz .LBB0_750
	v_pk_mul_f32 v[156:157], v[34:35], v[138:139]
	v_pk_mul_f32 v[154:155], v[32:33], v[140:141]
	v_pk_mul_f32 v[158:159], v[30:31], v[142:143]
	v_pk_mul_f32 v[160:161], v[28:29], v[144:145]
	v_cvt_pk_bf16_f32 v154, v154, v155
	v_cvt_pk_bf16_f32 v155, v156, v157
	s_nop 0
	v_cvt_pk_bf16_f32 v156, v160, v161
	v_cvt_pk_bf16_f32 v157, v158, v159
	global_store_dwordx4 v[136:137], v[154:157], off offset:256
	s_cbranch_execnz .LBB0_718
.LBB0_717:
	v_add_co_u32_e32 v134, vcc, 0x1000, v134
	v_rcp_f32_e32 v138, v138
	s_nop 0
	v_addc_co_u32_e32 v135, vcc, 0, v135, vcc
	global_load_dwordx4 v[134:137], v[134:135], off offset:2816 nt
	v_rcp_f32_e32 v139, v139
	v_rcp_f32_e32 v140, v140
	v_rcp_f32_e32 v144, v144
	v_rcp_f32_e32 v141, v141
	v_rcp_f32_e32 v145, v145
	v_rcp_f32_e32 v142, v142
	v_rcp_f32_e32 v143, v143
	s_waitcnt vmcnt(0)
	v_lshlrev_b32_e32 v154, 16, v134
	v_and_b32_e32 v155, 0xffff0000, v134
	v_lshlrev_b32_e32 v134, 16, v135
	v_and_b32_e32 v135, 0xffff0000, v135
	v_pk_mul_f32 v[134:135], v[138:139], v[134:135]
	v_lshlrev_b32_e32 v138, 16, v136
	v_and_b32_e32 v139, 0xffff0000, v136
	v_lshlrev_b32_e32 v136, 16, v137
	v_and_b32_e32 v137, 0xffff0000, v137
	v_pk_mul_f32 v[140:141], v[140:141], v[154:155]
	v_pk_mul_f32 v[138:139], v[144:145], v[138:139]
	v_pk_mul_f32 v[136:137], v[142:143], v[136:137]
	v_pk_mul_f32 v[34:35], v[34:35], v[134:135]
	v_pk_mul_f32 v[32:33], v[32:33], v[140:141]
	v_pk_mul_f32 v[30:31], v[30:31], v[136:137]
	v_pk_mul_f32 v[28:29], v[28:29], v[138:139]
; __device__ __forceinline__ float bf_lo(unsigned w) { return __uint_as_float(w << 16); }
; __device__ __forceinline__ float bf_hi(unsigned w) { return __uint_as_float(w & 0xffff0000u); }
; __device__ __forceinline__ u32x4 pack8(const f32x4 v0, const f32x4 v1) { u32x4 w; w.x = cvt_pk_bf16(v0[0], v0[1]); w.y = cvt_pk_bf16(v0[2], v0[3]); w.z = cvt_pk_bf16(v1[0], v1[1]); w.w = cvt_pk_bf16(v1[2], v1[3]); return w; }
;     __device__ __forceinline__ void operator()(f32x4 (&acc)[2][2][4][2], const Unit& u, int wr, int wc, int fr, int fq) const {
;     ...
;             for (int m = 0; m < 4; ++m) { const size_t row = (size_t)(row0 + ai * HALF + m * 16);
; #pragma unroll
;                 for (int bj = 0; bj < 2; ++bj) {
;                     const u32x4 gb = *(const u32x4*)(QKG + row * QKG_LD + C_SB + col0 + bj * HALF);
;                     f32x4 s0 = (f32x4){bf_lo(gb.x), bf_hi(gb.x), bf_lo(gb.y), bf_hi(gb.y)}, s1 = (f32x4){bf_lo(gb.z), bf_hi(gb.z), bf_lo(gb.w), bf_hi(gb.w)};
;                     if (u.kind == 0) {
;                         const u32x4 ga = *(const u32x4*)(QKG + row * QKG_LD + C_SA + col0 + bj * HALF);
; #pragma unroll
;                         for (int e = 0; e < 4; ++e) { s0[e] = __builtin_amdgcn_rcpf(s0[e]); s1[e] = __builtin_amdgcn_rcpf(s1[e]); }
;                         s0 = s0 * (f32x4){bf_lo(ga.x), bf_hi(ga.x), bf_lo(ga.y), bf_hi(ga.y)}; s1 = s1 * (f32x4){bf_lo(ga.z), bf_hi(ga.z), bf_lo(ga.w), bf_hi(ga.w)};
;                         acc[ai][bj][m][0] = acc[ai][bj][m][0] * s0; acc[ai][bj][m][1] = acc[ai][bj][m][1] * s1;
;                     } else *(u32x4*)(MRG + row * DM + col0 + bj * HALF) = pack8(acc[ai][bj][m][0] * s0, acc[ai][bj][m][1] * s1); }
;                 if (m & 1) asm volatile("" ::: "memory"); }
.LBB0_718:
	v_add_u32_e32 v136, 0x90, v132
	v_mov_b64_e32 v[134:135], s[84:85]
	v_mad_i64_i32 v[134:135], s[24:25], v136, s88, v[134:135]
	v_lshl_add_u64 v[134:135], v[2:3], 1, v[134:135]
	v_add_co_u32_e32 v138, vcc, 0x2000, v134
	v_ashrrev_i32_e32 v137, 31, v136
	s_nop 0
	v_addc_co_u32_e32 v139, vcc, 0, v135, vcc
	global_load_dwordx4 v[154:157], v[138:139], off offset:2560 nt
	v_lshlrev_b64 v[136:137], 12, v[136:137]
	v_lshl_add_u64 v[136:137], s[92:93], 0, v[136:137]
	s_and_b64 vcc, exec, s[0:1]
	v_lshl_add_u64 v[136:137], v[2:3], 1, v[136:137]
	s_waitcnt vmcnt(0)
	v_lshlrev_b32_e32 v140, 16, v154
	v_and_b32_e32 v141, 0xffff0000, v154
	v_lshlrev_b32_e32 v138, 16, v155
	v_and_b32_e32 v139, 0xffff0000, v155
	v_lshlrev_b32_e32 v144, 16, v156
	v_and_b32_e32 v145, 0xffff0000, v156
	v_lshlrev_b32_e32 v142, 16, v157
	v_and_b32_e32 v143, 0xffff0000, v157
	s_cbranch_vccnz .LBB0_751
	v_pk_mul_f32 v[156:157], v[58:59], v[138:139]
	v_pk_mul_f32 v[154:155], v[56:57], v[140:141]
	v_pk_mul_f32 v[158:159], v[54:55], v[142:143]
	v_pk_mul_f32 v[160:161], v[52:53], v[144:145]
	v_cvt_pk_bf16_f32 v154, v154, v155
	v_cvt_pk_bf16_f32 v155, v156, v157
	s_nop 0
	v_cvt_pk_bf16_f32 v156, v160, v161
	v_cvt_pk_bf16_f32 v157, v158, v159
	global_store_dwordx4 v[136:137], v[154:157], off
	s_cbranch_execnz .LBB0_721
.LBB0_720:
	s_nop 0
	v_add_co_u32_e32 v154, vcc, 0x1000, v134
	v_rcp_f32_e32 v138, v138
	s_nop 0
	v_addc_co_u32_e32 v155, vcc, 0, v135, vcc
	global_load_dwordx4 v[154:157], v[154:155], off offset:2560 nt
	v_rcp_f32_e32 v139, v139
	v_rcp_f32_e32 v140, v140
	v_rcp_f32_e32 v144, v144
	v_rcp_f32_e32 v141, v141
	v_rcp_f32_e32 v145, v145
	v_rcp_f32_e32 v142, v142
	v_rcp_f32_e32 v143, v143
	s_waitcnt vmcnt(0)
	v_lshlrev_b32_e32 v158, 16, v154
	v_and_b32_e32 v159, 0xffff0000, v154
	v_lshlrev_b32_e32 v154, 16, v155
	v_and_b32_e32 v155, 0xffff0000, v155
	v_pk_mul_f32 v[138:139], v[138:139], v[154:155]
	v_lshlrev_b32_e32 v154, 16, v156
	v_and_b32_e32 v155, 0xffff0000, v156
	v_lshlrev_b32_e32 v156, 16, v157
	v_and_b32_e32 v157, 0xffff0000, v157
	v_pk_mul_f32 v[140:141], v[140:141], v[158:159]
	v_pk_mul_f32 v[144:145], v[144:145], v[154:155]
	v_pk_mul_f32 v[142:143], v[142:143], v[156:157]
	v_pk_mul_f32 v[58:59], v[58:59], v[138:139]
	v_pk_mul_f32 v[56:57], v[56:57], v[140:141]
	v_pk_mul_f32 v[54:55], v[54:55], v[142:143]
	v_pk_mul_f32 v[52:53], v[52:53], v[144:145]
.LBB0_721:
	v_add_co_u32_e32 v138, vcc, 0x2000, v134
	s_nop 1
	v_addc_co_u32_e32 v139, vcc, 0, v135, vcc
	global_load_dwordx4 v[154:157], v[138:139], off offset:2816 nt
	s_and_b64 vcc, exec, s[0:1]
	s_waitcnt vmcnt(0)
	v_lshlrev_b32_e32 v140, 16, v154
	v_and_b32_e32 v141, 0xffff0000, v154
	v_lshlrev_b32_e32 v138, 16, v155
	v_and_b32_e32 v139, 0xffff0000, v155
	v_lshlrev_b32_e32 v144, 16, v156
	v_and_b32_e32 v145, 0xffff0000, v156
	v_lshlrev_b32_e32 v142, 16, v157
	v_and_b32_e32 v143, 0xffff0000, v157
	s_cbranch_vccnz .LBB0_752
	v_pk_mul_f32 v[156:157], v[26:27], v[138:139]
	v_pk_mul_f32 v[154:155], v[24:25], v[140:141]
	v_pk_mul_f32 v[158:159], v[22:23], v[142:143]
	v_pk_mul_f32 v[160:161], v[20:21], v[144:145]
	v_cvt_pk_bf16_f32 v154, v154, v155
	v_cvt_pk_bf16_f32 v155, v156, v157
	s_nop 0
	v_cvt_pk_bf16_f32 v156, v160, v161
	v_cvt_pk_bf16_f32 v157, v158, v159
	global_store_dwordx4 v[136:137], v[154:157], off offset:256
	s_cbranch_execnz .LBB0_724
.LBB0_723:
	v_add_co_u32_e32 v134, vcc, 0x1000, v134
	v_rcp_f32_e32 v138, v138
	s_nop 0
	v_addc_co_u32_e32 v135, vcc, 0, v135, vcc
	global_load_dwordx4 v[134:137], v[134:135], off offset:2816 nt
	v_rcp_f32_e32 v139, v139
	v_rcp_f32_e32 v140, v140
	v_rcp_f32_e32 v144, v144
	v_rcp_f32_e32 v141, v141
	v_rcp_f32_e32 v145, v145
	v_rcp_f32_e32 v142, v142
	v_rcp_f32_e32 v143, v143
	s_waitcnt vmcnt(0)
	v_lshlrev_b32_e32 v154, 16, v134
	v_and_b32_e32 v155, 0xffff0000, v134
	v_lshlrev_b32_e32 v134, 16, v135
	v_and_b32_e32 v135, 0xffff0000, v135
	v_pk_mul_f32 v[134:135], v[138:139], v[134:135]
	v_lshlrev_b32_e32 v138, 16, v136
	v_and_b32_e32 v139, 0xffff0000, v136
	v_lshlrev_b32_e32 v136, 16, v137
	v_and_b32_e32 v137, 0xffff0000, v137
	v_pk_mul_f32 v[140:141], v[140:141], v[154:155]
	v_pk_mul_f32 v[138:139], v[144:145], v[138:139]
	v_pk_mul_f32 v[136:137], v[142:143], v[136:137]
	v_pk_mul_f32 v[26:27], v[26:27], v[134:135]
	v_pk_mul_f32 v[24:25], v[24:25], v[140:141]
	v_pk_mul_f32 v[22:23], v[22:23], v[136:137]
	v_pk_mul_f32 v[20:21], v[20:21], v[138:139]
.LBB0_724:
	v_add_u32_e32 v136, 0xa0, v132
	v_mov_b64_e32 v[134:135], s[84:85]
	v_mad_i64_i32 v[134:135], s[24:25], v136, s88, v[134:135]
	v_lshl_add_u64 v[134:135], v[2:3], 1, v[134:135]
	v_add_co_u32_e32 v138, vcc, 0x2000, v134
	v_ashrrev_i32_e32 v137, 31, v136
	s_nop 0
	v_addc_co_u32_e32 v139, vcc, 0, v135, vcc
	global_load_dwordx4 v[154:157], v[138:139], off offset:2560 nt
	v_lshlrev_b64 v[136:137], 12, v[136:137]
	v_lshl_add_u64 v[136:137], s[92:93], 0, v[136:137]
	s_and_b64 vcc, exec, s[0:1]
	v_lshl_add_u64 v[136:137], v[2:3], 1, v[136:137]
	s_waitcnt vmcnt(0)
	v_lshlrev_b32_e32 v140, 16, v154
	v_and_b32_e32 v141, 0xffff0000, v154
	v_lshlrev_b32_e32 v138, 16, v155
	v_and_b32_e32 v139, 0xffff0000, v155
	v_lshlrev_b32_e32 v144, 16, v156
	v_and_b32_e32 v145, 0xffff0000, v156
	v_lshlrev_b32_e32 v142, 16, v157
	v_and_b32_e32 v143, 0xffff0000, v157
	s_cbranch_vccnz .LBB0_753
	v_pk_mul_f32 v[156:157], v[50:51], v[138:139]
	v_pk_mul_f32 v[154:155], v[48:49], v[140:141]
	v_pk_mul_f32 v[158:159], v[46:47], v[142:143]
	v_pk_mul_f32 v[160:161], v[44:45], v[144:145]
	v_cvt_pk_bf16_f32 v154, v154, v155
	v_cvt_pk_bf16_f32 v155, v156, v157
	s_nop 0
	v_cvt_pk_bf16_f32 v156, v160, v161
	v_cvt_pk_bf16_f32 v157, v158, v159
	global_store_dwordx4 v[136:137], v[154:157], off
	s_cbranch_execnz .LBB0_727
; __device__ __forceinline__ float bf_lo(unsigned w) { return __uint_as_float(w << 16); }
; __device__ __forceinline__ float bf_hi(unsigned w) { return __uint_as_float(w & 0xffff0000u); }
; __device__ __forceinline__ u32x4 pack8(const f32x4 v0, const f32x4 v1) { u32x4 w; w.x = cvt_pk_bf16(v0[0], v0[1]); w.y = cvt_pk_bf16(v0[2], v0[3]); w.z = cvt_pk_bf16(v1[0], v1[1]); w.w = cvt_pk_bf16(v1[2], v1[3]); return w; }
;     __device__ __forceinline__ void operator()(f32x4 (&acc)[2][2][4][2], const Unit& u, int wr, int wc, int fr, int fq) const {
;     ...
;             for (int m = 0; m < 4; ++m) { const size_t row = (size_t)(row0 + ai * HALF + m * 16);
; #pragma unroll
;                 for (int bj = 0; bj < 2; ++bj) {
;                     const u32x4 gb = *(const u32x4*)(QKG + row * QKG_LD + C_SB + col0 + bj * HALF);
;                     f32x4 s0 = (f32x4){bf_lo(gb.x), bf_hi(gb.x), bf_lo(gb.y), bf_hi(gb.y)}, s1 = (f32x4){bf_lo(gb.z), bf_hi(gb.z), bf_lo(gb.w), bf_hi(gb.w)};
;                     if (u.kind == 0) {
;                         const u32x4 ga = *(const u32x4*)(QKG + row * QKG_LD + C_SA + col0 + bj * HALF);
; #pragma unroll
;                         for (int e = 0; e < 4; ++e) { s0[e] = __builtin_amdgcn_rcpf(s0[e]); s1[e] = __builtin_amdgcn_rcpf(s1[e]); }
;                         s0 = s0 * (f32x4){bf_lo(ga.x), bf_hi(ga.x), bf_lo(ga.y), bf_hi(ga.y)}; s1 = s1 * (f32x4){bf_lo(ga.z), bf_hi(ga.z), bf_lo(ga.w), bf_hi(ga.w)};
;                         acc[ai][bj][m][0] = acc[ai][bj][m][0] * s0; acc[ai][bj][m][1] = acc[ai][bj][m][1] * s1;
;                     } else *(u32x4*)(MRG + row * DM + col0 + bj * HALF) = pack8(acc[ai][bj][m][0] * s0, acc[ai][bj][m][1] * s1); }
;                 if (m & 1) asm volatile("" ::: "memory"); }
.LBB0_726:
	s_nop 0
	v_add_co_u32_e32 v154, vcc, 0x1000, v134
	v_rcp_f32_e32 v138, v138
	s_nop 0
	v_addc_co_u32_e32 v155, vcc, 0, v135, vcc
	global_load_dwordx4 v[154:157], v[154:155], off offset:2560 nt
	v_rcp_f32_e32 v139, v139
	v_rcp_f32_e32 v140, v140
	v_rcp_f32_e32 v144, v144
	v_rcp_f32_e32 v141, v141
	v_rcp_f32_e32 v145, v145
	v_rcp_f32_e32 v142, v142
	v_rcp_f32_e32 v143, v143
	s_waitcnt vmcnt(0)
	v_lshlrev_b32_e32 v158, 16, v154
	v_and_b32_e32 v159, 0xffff0000, v154
	v_lshlrev_b32_e32 v154, 16, v155
	v_and_b32_e32 v155, 0xffff0000, v155
	v_pk_mul_f32 v[138:139], v[138:139], v[154:155]
	v_lshlrev_b32_e32 v154, 16, v156
	v_and_b32_e32 v155, 0xffff0000, v156
	v_lshlrev_b32_e32 v156, 16, v157
	v_and_b32_e32 v157, 0xffff0000, v157
	v_pk_mul_f32 v[140:141], v[140:141], v[158:159]
	v_pk_mul_f32 v[144:145], v[144:145], v[154:155]
	v_pk_mul_f32 v[142:143], v[142:143], v[156:157]
	v_pk_mul_f32 v[50:51], v[50:51], v[138:139]
	v_pk_mul_f32 v[48:49], v[48:49], v[140:141]
	v_pk_mul_f32 v[46:47], v[46:47], v[142:143]
	v_pk_mul_f32 v[44:45], v[44:45], v[144:145]
.LBB0_727:
	v_add_co_u32_e32 v138, vcc, 0x2000, v134
	s_nop 1
	v_addc_co_u32_e32 v139, vcc, 0, v135, vcc
	global_load_dwordx4 v[154:157], v[138:139], off offset:2816 nt
	s_and_b64 vcc, exec, s[0:1]
	s_waitcnt vmcnt(0)
	v_lshlrev_b32_e32 v140, 16, v154
	v_and_b32_e32 v141, 0xffff0000, v154
	v_lshlrev_b32_e32 v138, 16, v155
	v_and_b32_e32 v139, 0xffff0000, v155
	v_lshlrev_b32_e32 v144, 16, v156
	v_and_b32_e32 v145, 0xffff0000, v156
	v_lshlrev_b32_e32 v142, 16, v157
	v_and_b32_e32 v143, 0xffff0000, v157
	s_cbranch_vccnz .LBB0_754
	v_pk_mul_f32 v[156:157], v[18:19], v[138:139]
	v_pk_mul_f32 v[154:155], v[16:17], v[140:141]
	v_pk_mul_f32 v[158:159], v[14:15], v[142:143]
	v_pk_mul_f32 v[160:161], v[12:13], v[144:145]
	v_cvt_pk_bf16_f32 v154, v154, v155
	v_cvt_pk_bf16_f32 v155, v156, v157
	s_nop 0
	v_cvt_pk_bf16_f32 v156, v160, v161
	v_cvt_pk_bf16_f32 v157, v158, v159
	global_store_dwordx4 v[136:137], v[154:157], off offset:256
	s_cbranch_execnz .LBB0_730
.LBB0_729:
	v_add_co_u32_e32 v134, vcc, 0x1000, v134
	v_rcp_f32_e32 v138, v138
	s_nop 0
	v_addc_co_u32_e32 v135, vcc, 0, v135, vcc
	global_load_dwordx4 v[134:137], v[134:135], off offset:2816 nt
	v_rcp_f32_e32 v139, v139
	v_rcp_f32_e32 v140, v140
	v_rcp_f32_e32 v144, v144
	v_rcp_f32_e32 v141, v141
	v_rcp_f32_e32 v145, v145
	v_rcp_f32_e32 v142, v142
	v_rcp_f32_e32 v143, v143
	s_waitcnt vmcnt(0)
	v_lshlrev_b32_e32 v154, 16, v134
	v_and_b32_e32 v155, 0xffff0000, v134
	v_lshlrev_b32_e32 v134, 16, v135
	v_and_b32_e32 v135, 0xffff0000, v135
	v_pk_mul_f32 v[134:135], v[138:139], v[134:135]
	v_lshlrev_b32_e32 v138, 16, v136
	v_and_b32_e32 v139, 0xffff0000, v136
	v_lshlrev_b32_e32 v136, 16, v137
	v_and_b32_e32 v137, 0xffff0000, v137
	v_pk_mul_f32 v[140:141], v[140:141], v[154:155]
	v_pk_mul_f32 v[138:139], v[144:145], v[138:139]
	v_pk_mul_f32 v[136:137], v[142:143], v[136:137]
	v_pk_mul_f32 v[18:19], v[18:19], v[134:135]
	v_pk_mul_f32 v[16:17], v[16:17], v[140:141]
	v_pk_mul_f32 v[14:15], v[14:15], v[136:137]
	v_pk_mul_f32 v[12:13], v[12:13], v[138:139]
; __device__ __forceinline__ float bf_lo(unsigned w) { return __uint_as_float(w << 16); }
; __device__ __forceinline__ float bf_hi(unsigned w) { return __uint_as_float(w & 0xffff0000u); }
; __device__ __forceinline__ u32x4 pack8(const f32x4 v0, const f32x4 v1) { u32x4 w; w.x = cvt_pk_bf16(v0[0], v0[1]); w.y = cvt_pk_bf16(v0[2], v0[3]); w.z = cvt_pk_bf16(v1[0], v1[1]); w.w = cvt_pk_bf16(v1[2], v1[3]); return w; }
;     __device__ __forceinline__ void operator()(f32x4 (&acc)[2][2][4][2], const Unit& u, int wr, int wc, int fr, int fq) const {
;     ...
;             for (int m = 0; m < 4; ++m) { const size_t row = (size_t)(row0 + ai * HALF + m * 16);
; #pragma unroll
;                 for (int bj = 0; bj < 2; ++bj) {
;                     const u32x4 gb = *(const u32x4*)(QKG + row * QKG_LD + C_SB + col0 + bj * HALF);
;                     f32x4 s0 = (f32x4){bf_lo(gb.x), bf_hi(gb.x), bf_lo(gb.y), bf_hi(gb.y)}, s1 = (f32x4){bf_lo(gb.z), bf_hi(gb.z), bf_lo(gb.w), bf_hi(gb.w)};
;                     if (u.kind == 0) {
;                         const u32x4 ga = *(const u32x4*)(QKG + row * QKG_LD + C_SA + col0 + bj * HALF);
; #pragma unroll
;                         for (int e = 0; e < 4; ++e) { s0[e] = __builtin_amdgcn_rcpf(s0[e]); s1[e] = __builtin_amdgcn_rcpf(s1[e]); }
;                         s0 = s0 * (f32x4){bf_lo(ga.x), bf_hi(ga.x), bf_lo(ga.y), bf_hi(ga.y)}; s1 = s1 * (f32x4){bf_lo(ga.z), bf_hi(ga.z), bf_lo(ga.w), bf_hi(ga.w)};
;                         acc[ai][bj][m][0] = acc[ai][bj][m][0] * s0; acc[ai][bj][m][1] = acc[ai][bj][m][1] * s1;
;                     } else *(u32x4*)(MRG + row * DM + col0 + bj * HALF) = pack8(acc[ai][bj][m][0] * s0, acc[ai][bj][m][1] * s1); }
;                 if (m & 1) asm volatile("" ::: "memory"); }
.LBB0_730:
	v_add_u32_e32 v134, 0xb0, v132
	v_mov_b64_e32 v[132:133], s[84:85]
	v_mad_i64_i32 v[132:133], s[24:25], v134, s88, v[132:133]
	v_lshl_add_u64 v[132:133], v[2:3], 1, v[132:133]
	v_add_co_u32_e32 v136, vcc, 0x2000, v132
	v_ashrrev_i32_e32 v135, 31, v134
	s_nop 0
	v_addc_co_u32_e32 v137, vcc, 0, v133, vcc
	global_load_dwordx4 v[140:143], v[136:137], off offset:2560 nt
	v_lshlrev_b64 v[134:135], 12, v[134:135]
	v_lshl_add_u64 v[144:145], s[92:93], 0, v[134:135]
	s_and_b64 vcc, exec, s[0:1]
	v_lshl_add_u64 v[2:3], v[2:3], 1, v[144:145]
	s_waitcnt vmcnt(0)
	v_lshlrev_b32_e32 v136, 16, v140
	v_and_b32_e32 v137, 0xffff0000, v140
	v_lshlrev_b32_e32 v134, 16, v141
	v_and_b32_e32 v135, 0xffff0000, v141
	v_lshlrev_b32_e32 v140, 16, v142
	v_and_b32_e32 v141, 0xffff0000, v142
	v_lshlrev_b32_e32 v138, 16, v143
	v_and_b32_e32 v139, 0xffff0000, v143
	s_cbranch_vccnz .LBB0_755
	v_pk_mul_f32 v[144:145], v[42:43], v[134:135]
	v_pk_mul_f32 v[142:143], v[40:41], v[136:137]
	v_pk_mul_f32 v[154:155], v[38:39], v[138:139]
	v_pk_mul_f32 v[156:157], v[36:37], v[140:141]
	v_cvt_pk_bf16_f32 v142, v142, v143
	v_cvt_pk_bf16_f32 v143, v144, v145
	s_nop 0
	v_cvt_pk_bf16_f32 v144, v156, v157
	v_cvt_pk_bf16_f32 v145, v154, v155
	global_store_dwordx4 v[2:3], v[142:145], off
	s_cbranch_execnz .LBB0_733
.LBB0_732:
	s_nop 0
	v_add_co_u32_e32 v142, vcc, 0x1000, v132
	v_rcp_f32_e32 v134, v134
	s_nop 0
	v_addc_co_u32_e32 v143, vcc, 0, v133, vcc
	global_load_dwordx4 v[142:145], v[142:143], off offset:2560 nt
	v_rcp_f32_e32 v135, v135
	v_rcp_f32_e32 v136, v136
	v_rcp_f32_e32 v140, v140
	v_rcp_f32_e32 v137, v137
	v_rcp_f32_e32 v141, v141
	v_rcp_f32_e32 v138, v138
	v_rcp_f32_e32 v139, v139
	s_waitcnt vmcnt(0)
	v_lshlrev_b32_e32 v154, 16, v142
	v_and_b32_e32 v155, 0xffff0000, v142
	v_lshlrev_b32_e32 v142, 16, v143
	v_and_b32_e32 v143, 0xffff0000, v143
	v_pk_mul_f32 v[134:135], v[134:135], v[142:143]
	v_lshlrev_b32_e32 v142, 16, v144
	v_and_b32_e32 v143, 0xffff0000, v144
	v_lshlrev_b32_e32 v144, 16, v145
	v_and_b32_e32 v145, 0xffff0000, v145
	v_pk_mul_f32 v[136:137], v[136:137], v[154:155]
	v_pk_mul_f32 v[140:141], v[140:141], v[142:143]
	v_pk_mul_f32 v[138:139], v[138:139], v[144:145]
	v_pk_mul_f32 v[42:43], v[42:43], v[134:135]
	v_pk_mul_f32 v[40:41], v[40:41], v[136:137]
	v_pk_mul_f32 v[38:39], v[38:39], v[138:139]
	v_pk_mul_f32 v[36:37], v[36:37], v[140:141]
.LBB0_733:
	v_add_co_u32_e32 v134, vcc, 0x2000, v132
	s_nop 1
	v_addc_co_u32_e32 v135, vcc, 0, v133, vcc
	global_load_dwordx4 v[140:143], v[134:135], off offset:2816 nt
	s_and_b64 vcc, exec, s[0:1]
	s_waitcnt vmcnt(0)
	v_lshlrev_b32_e32 v136, 16, v140
	v_and_b32_e32 v137, 0xffff0000, v140
	v_lshlrev_b32_e32 v134, 16, v141
	v_and_b32_e32 v135, 0xffff0000, v141
	v_lshlrev_b32_e32 v140, 16, v142
	v_and_b32_e32 v141, 0xffff0000, v142
	v_lshlrev_b32_e32 v138, 16, v143
	v_and_b32_e32 v139, 0xffff0000, v143
	s_cbranch_vccnz .LBB0_756
	v_pk_mul_f32 v[144:145], v[10:11], v[134:135]
	v_pk_mul_f32 v[142:143], v[8:9], v[136:137]
	v_pk_mul_f32 v[154:155], v[6:7], v[138:139]
	v_pk_mul_f32 v[156:157], v[4:5], v[140:141]
	v_cvt_pk_bf16_f32 v142, v142, v143
	v_cvt_pk_bf16_f32 v143, v144, v145
	s_nop 0
	v_cvt_pk_bf16_f32 v144, v156, v157
	v_cvt_pk_bf16_f32 v145, v154, v155
	global_store_dwordx4 v[2:3], v[142:145], off offset:256
	s_cbranch_execnz .LBB0_736
.LBB0_735:
	v_add_co_u32_e32 v2, vcc, 0x1000, v132
	v_rcp_f32_e32 v134, v134
	s_nop 0
	v_addc_co_u32_e32 v3, vcc, 0, v133, vcc
	global_load_dwordx4 v[142:145], v[2:3], off offset:2816 nt
	v_rcp_f32_e32 v2, v136
	v_rcp_f32_e32 v3, v137
	v_rcp_f32_e32 v135, v135
	v_rcp_f32_e32 v132, v140
	v_rcp_f32_e32 v133, v141
	v_rcp_f32_e32 v136, v138
	v_rcp_f32_e32 v137, v139
	s_waitcnt vmcnt(0)
	v_lshlrev_b32_e32 v138, 16, v142
	v_and_b32_e32 v139, 0xffff0000, v142
	v_lshlrev_b32_e32 v140, 16, v143
	v_and_b32_e32 v141, 0xffff0000, v143
	v_pk_mul_f32 v[2:3], v[2:3], v[138:139]
	v_pk_mul_f32 v[134:135], v[134:135], v[140:141]
	v_lshlrev_b32_e32 v138, 16, v144
	v_and_b32_e32 v139, 0xffff0000, v144
	v_lshlrev_b32_e32 v140, 16, v145
	v_and_b32_e32 v141, 0xffff0000, v145
	v_pk_mul_f32 v[132:133], v[132:133], v[138:139]
	v_pk_mul_f32 v[136:137], v[136:137], v[140:141]
	v_pk_mul_f32 v[10:11], v[10:11], v[134:135]
	v_pk_mul_f32 v[8:9], v[8:9], v[2:3]
	v_pk_mul_f32 v[6:7], v[6:7], v[136:137]
	v_pk_mul_f32 v[4:5], v[4:5], v[132:133]

; __device__ __forceinline__ unsigned cvt_pk_bf16(float lo, float hi) { unsigned r; asm volatile("v_cvt_pk_bf16_f32 %0, %1, %2" : "=v"(r) : "v"(lo), "v"(hi)); return r; }
; __device__ __forceinline__ void norm_rows(const float* x, bf16_t* H, const float* g, const float* modl, int sh_off, int sc_off, int gw, int NGW, int lane, bool stream) {
;     ...
;     for (int m = gw; m < MTOK; m += NGW) {
;         const int b = m >> 12;
;         const f32x4* xr = (const f32x4*)(x + (size_t)m * DM) + lane;
;         f32x4 v[8]; float s = 0.f;
; #pragma unroll
;         for (int j = 0; j < 8; ++j) { v[j] = xr[64 * j]; s += (v[j][0] * v[j][0] + v[j][1] * v[j][1]) + (v[j][2] * v[j][2] + v[j][3] * v[j][3]); }
;         const float rstd = 1.0f / sqrtf(wave_sum(s) * (1.0f / DM) + EPS);
;         u32x2* o8 = (u32x2*)(H + (size_t)m * DM) + lane;
; #pragma unroll
;         for (int j = 0; j < 8; ++j) { const int col = 4 * lane + 256 * j;
;             const f32x4 gv = *(const f32x4*)(g + col), scv = *(const f32x4*)(modl + b * MODW + sc_off + col), shv = *(const f32x4*)(modl + b * MODW + sh_off + col);
;             const f32x4 r = (v[j] * rstd * gv) * (scv + 1.0f) + shv;
;             u32x2 w; w.x = cvt_pk_bf16(r[0], r[1]); w.y = cvt_pk_bf16(r[2], r[3]); o8[64 * j] = w; }
;     }
.LBB0_878:
	global_load_dwordx4 v[30:33], v[52:53], off offset:-4096 nt
	global_load_dwordx4 v[2:5], v[52:53], off offset:-3072 nt
	global_load_dwordx4 v[14:17], v[52:53], off offset:-2048 nt
	s_lshr_b32 s5, s4, 12
	s_waitcnt vmcnt(2)
	v_mov_b32_e32 v8, v31
	s_waitcnt vmcnt(1)
	v_mov_b32_e32 v9, v3
	v_mov_b32_e32 v6, v30
	v_mov_b32_e32 v7, v2
	v_pk_mul_f32 v[8:9], v[8:9], v[8:9]
	v_mov_b32_e32 v10, v33
	v_mov_b32_e32 v11, v5
	v_pk_fma_f32 v[6:7], v[6:7], v[6:7], v[8:9]
	v_mov_b32_e32 v8, v32
	v_mov_b32_e32 v9, v4
	v_pk_mul_f32 v[10:11], v[10:11], v[10:11]
	s_nop 0
	v_pk_fma_f32 v[8:9], v[8:9], v[8:9], v[10:11]
	s_nop 0
	v_pk_add_f32 v[18:19], v[6:7], v[8:9]
	s_waitcnt vmcnt(0)
	v_pk_mul_f32 v[6:7], v[16:17], v[16:17]
	v_pk_mul_f32 v[8:9], v[14:15], v[14:15]
	v_pk_add_f32 v[18:19], v[18:19], v[18:19] op_sel:[0,1] op_sel_hi:[1,0]
	v_pk_mov_b32 v[10:11], v[8:9], v[6:7] op_sel:[1,0]
	v_mov_b32_e32 v9, v7
	v_pk_add_f32 v[20:21], v[10:11], v[8:9]
	global_load_dwordx4 v[6:9], v[52:53], off offset:-1024 nt
	global_load_dwordx4 v[10:13], v[52:53], off nt
	global_load_dwordx4 v[26:29], v[52:53], off offset:1024 nt
	v_pk_add_f32 v[20:21], v[20:21], v[20:21] op_sel:[0,1] op_sel_hi:[1,0]
	s_waitcnt vmcnt(1)
	v_mul_f32_e32 v0, v10, v10
	v_mul_f32_e32 v22, v11, v11
	v_mov_b32_e32 v19, v0
	v_mov_b32_e32 v21, v22
	v_mul_f32_e32 v0, v7, v7
	v_mul_f32_e32 v23, v12, v12
	v_pk_add_f32 v[18:19], v[18:19], v[20:21]
	v_pk_fma_f32 v[20:21], v[6:7], v[6:7], v[0:1] op_sel_hi:[1,1,0]
	v_mul_f32_e32 v0, v9, v9
	v_mul_f32_e32 v24, v13, v13
	v_mov_b32_e32 v21, v23
	v_pk_fma_f32 v[22:23], v[8:9], v[8:9], v[0:1] op_sel_hi:[1,1,0]
	s_nop 0
	v_mov_b32_e32 v23, v24
	v_pk_add_f32 v[20:21], v[20:21], v[22:23]
	s_nop 0
	v_pk_add_f32 v[34:35], v[18:19], v[20:21]
	s_waitcnt vmcnt(0)
	v_pk_mul_f32 v[18:19], v[28:29], v[28:29]
	v_pk_mul_f32 v[20:21], v[26:27], v[26:27]
	v_pk_add_f32 v[34:35], v[34:35], v[34:35] op_sel:[0,1] op_sel_hi:[1,0]
	v_pk_mov_b32 v[22:23], v[20:21], v[18:19] op_sel:[1,0]
	v_mov_b32_e32 v21, v19
	v_pk_add_f32 v[36:37], v[22:23], v[20:21]
	global_load_dwordx4 v[18:21], v[52:53], off offset:2048 nt
	global_load_dwordx4 v[22:25], v[52:53], off offset:3072 nt
	v_pk_add_f32 v[36:37], v[36:37], v[36:37] op_sel:[0,1] op_sel_hi:[1,0]
	v_lshl_add_u64 v[52:53], v[52:53], 0, s[46:47]
	s_waitcnt vmcnt(0)
	v_mul_f32_e32 v0, v22, v22
	v_mul_f32_e32 v38, v23, v23
	v_mov_b32_e32 v35, v0
	v_mov_b32_e32 v37, v38
	v_mul_f32_e32 v0, v19, v19
	v_mul_f32_e32 v39, v24, v24
	v_pk_add_f32 v[34:35], v[34:35], v[36:37]
	v_pk_fma_f32 v[36:37], v[18:19], v[18:19], v[0:1] op_sel_hi:[1,1,0]
	v_mul_f32_e32 v0, v21, v21
	v_mul_f32_e32 v40, v25, v25
	v_mov_b32_e32 v37, v39
	v_pk_fma_f32 v[38:39], v[20:21], v[20:21], v[0:1] op_sel_hi:[1,1,0]
	s_nop 0
	v_mov_b32_e32 v39, v40
	v_pk_add_f32 v[36:37], v[36:37], v[38:39]
	s_nop 0
	v_pk_add_f32 v[34:35], v[34:35], v[36:37]
	s_nop 0
	v_add_f32_e32 v0, v34, v35
	ds_swizzle_b32 v34, v0 offset:swizzle(SWAP,1)
	s_waitcnt lgkmcnt(0)
	v_add_f32_e32 v0, v0, v34
	ds_swizzle_b32 v34, v0 offset:swizzle(SWAP,2)
	s_waitcnt lgkmcnt(0)
	v_add_f32_e32 v0, v0, v34
	ds_swizzle_b32 v34, v0 offset:swizzle(SWAP,4)
	s_waitcnt lgkmcnt(0)
	v_add_f32_e32 v0, v0, v34
	ds_swizzle_b32 v34, v0 offset:swizzle(SWAP,8)
	s_waitcnt lgkmcnt(0)
	v_add_f32_e32 v0, v0, v34
	ds_swizzle_b32 v34, v0 offset:swizzle(SWAP,16)
	s_waitcnt lgkmcnt(0)
	v_add_f32_e32 v0, v0, v34
	ds_bpermute_b32 v34, v56, v0
	s_waitcnt lgkmcnt(0)
	v_add_f32_e32 v0, v0, v34
	v_fmamk_f32 v0, v0, 0x3a000000, v203
	v_cmp_gt_f32_e32 vcc, s91, v0
	v_mul_f32_e32 v34, 0x4f800000, v0
	s_nop 0
	v_cndmask_b32_e32 v0, v0, v34, vcc
	v_sqrt_f32_e32 v34, v0
	s_nop 0
	v_add_u32_e32 v35, -1, v34
	v_fma_f32 v36, -v35, v34, v0
	v_cmp_ge_f32_e64 s[0:1], 0, v36
	v_add_u32_e32 v36, 1, v34
	s_nop 0
	v_cndmask_b32_e64 v35, v34, v35, s[0:1]
	v_fma_f32 v34, -v36, v34, v0
	v_cmp_lt_f32_e64 s[0:1], 0, v34
	s_nop 1
	v_cndmask_b32_e64 v34, v35, v36, s[0:1]
	v_mul_f32_e32 v35, 0x37800000, v34
	v_cndmask_b32_e32 v34, v34, v35, vcc
	v_cmp_class_f32_e32 vcc, v0, v204
	s_nop 1
	v_cndmask_b32_e32 v0, v34, v0, vcc
	v_div_scale_f32 v34, s[0:1], v0, v0, 1.0
	v_rcp_f32_e32 v35, v34
	s_mul_i32 s0, s5, 0x3000
	s_ashr_i32 s1, s0, 31
	s_lshl_b64 s[0:1], s[0:1], 2
	v_fma_f32 v36, -v34, v35, 1.0
	v_fmac_f32_e32 v35, v36, v35
	v_div_scale_f32 v36, vcc, 1.0, v0, 1.0
	v_mul_f32_e32 v37, v36, v35
	s_add_u32 s5, s10, s0
	v_fma_f32 v38, -v34, v37, v36
	s_addc_u32 s6, s11, s1
	v_fmac_f32_e32 v37, v38, v35
	s_add_u32 s0, s5, 0x8000
	v_fma_f32 v34, -v34, v37, v36
	s_addc_u32 s1, s6, 0
	v_div_fmas_f32 v34, v34, v35, v37
	s_add_u32 s12, s5, 0x6000
	v_div_fixup_f32 v0, v34, v0, 1.0
	s_addc_u32 s13, s6, 0
	global_load_dwordx4 v[66:69], v[42:43], off nt
	global_load_dwordx4 v[38:41], v57, s[0:1]
	global_load_dwordx4 v[34:37], v57, s[12:13]
	v_pk_mul_f32 v[30:31], v[30:31], v[0:1] op_sel_hi:[1,0]
	v_pk_mul_f32 v[32:33], v[32:33], v[0:1] op_sel_hi:[1,0]
	v_pk_mul_f32 v[4:5], v[4:5], v[0:1] op_sel_hi:[1,0]
	v_pk_mul_f32 v[2:3], v[2:3], v[0:1] op_sel_hi:[1,0]
	v_pk_mul_f32 v[16:17], v[16:17], v[0:1] op_sel_hi:[1,0]
	v_pk_mul_f32 v[14:15], v[14:15], v[0:1] op_sel_hi:[1,0]
	v_pk_mul_f32 v[8:9], v[8:9], v[0:1] op_sel_hi:[1,0]
	v_pk_mul_f32 v[6:7], v[6:7], v[0:1] op_sel_hi:[1,0]
	v_pk_mul_f32 v[10:11], v[10:11], v[0:1] op_sel_hi:[1,0]
	v_pk_mul_f32 v[12:13], v[12:13], v[0:1] op_sel_hi:[1,0]
	s_add_i32 s4, s4, s78
	s_cmpk_lt_i32 s4, 0x4000
	s_waitcnt vmcnt(2)
; __device__ __forceinline__ unsigned cvt_pk_bf16(float lo, float hi) { unsigned r; asm volatile("v_cvt_pk_bf16_f32 %0, %1, %2" : "=v"(r) : "v"(lo), "v"(hi)); return r; }
; __device__ __forceinline__ void norm_rows(const float* x, bf16_t* H, const float* g, const float* modl, int sh_off, int sc_off, int gw, int NGW, int lane, bool stream) {
;     ...
; #pragma unroll
;         for (int j = 0; j < 8; ++j) { const int col = 4 * lane + 256 * j;
;             const f32x4 gv = *(const f32x4*)(g + col), scv = *(const f32x4*)(modl + b * MODW + sc_off + col), shv = *(const f32x4*)(modl + b * MODW + sh_off + col);
;             const f32x4 r = (v[j] * rstd * gv) * (scv + 1.0f) + shv;
;             u32x2 w; w.x = cvt_pk_bf16(r[0], r[1]); w.y = cvt_pk_bf16(r[2], r[3]); o8[64 * j] = w; }
	v_pk_mul_f32 v[30:31], v[66:67], v[30:31]
	s_waitcnt vmcnt(1)
	v_pk_add_f32 v[38:39], v[38:39], 1.0 op_sel_hi:[1,0]
	v_pk_mul_f32 v[32:33], v[68:69], v[32:33]
	v_pk_add_f32 v[40:41], v[40:41], 1.0 op_sel_hi:[1,0]
	s_waitcnt vmcnt(0)
	v_pk_fma_f32 v[30:31], v[38:39], v[30:31], v[34:35]
	v_pk_fma_f32 v[32:33], v[40:41], v[32:33], v[36:37]
	v_cvt_pk_bf16_f32 v30, v30, v31
	s_nop 0
	v_cvt_pk_bf16_f32 v31, v32, v33
	global_store_dwordx2 v[54:55], v[30:31], off
	global_load_dwordx4 v[30:33], v[42:43], off offset:1024 nt
	s_nop 0
	global_load_dwordx4 v[34:37], v58, s[0:1]
	global_load_dwordx4 v[38:41], v58, s[12:13]
	s_waitcnt vmcnt(2)
	v_pk_mul_f32 v[2:3], v[30:31], v[2:3]
	v_pk_mul_f32 v[4:5], v[32:33], v[4:5]
	s_waitcnt vmcnt(1)
	v_pk_add_f32 v[32:33], v[34:35], 1.0 op_sel_hi:[1,0]
	v_pk_add_f32 v[30:31], v[36:37], 1.0 op_sel_hi:[1,0]
	s_waitcnt vmcnt(0)
	v_pk_fma_f32 v[2:3], v[32:33], v[2:3], v[38:39]
	v_pk_fma_f32 v[4:5], v[30:31], v[4:5], v[40:41]
	v_cvt_pk_bf16_f32 v2, v2, v3
	s_nop 0
	v_cvt_pk_bf16_f32 v3, v4, v5
	global_store_dwordx2 v[54:55], v[2:3], off offset:512
	global_load_dwordx4 v[2:5], v[42:43], off offset:2048 nt
	s_nop 0
	global_load_dwordx4 v[30:33], v59, s[0:1]
	global_load_dwordx4 v[34:37], v59, s[12:13]
	s_waitcnt vmcnt(2)
	v_pk_mul_f32 v[2:3], v[14:15], v[2:3]
	v_pk_mul_f32 v[4:5], v[16:17], v[4:5]
	s_waitcnt vmcnt(1)
	v_pk_add_f32 v[16:17], v[30:31], 1.0 op_sel_hi:[1,0]
	v_pk_add_f32 v[14:15], v[32:33], 1.0 op_sel_hi:[1,0]
	s_waitcnt vmcnt(0)
	v_pk_fma_f32 v[2:3], v[2:3], v[16:17], v[34:35]
	v_pk_fma_f32 v[4:5], v[4:5], v[14:15], v[36:37]
	v_cvt_pk_bf16_f32 v2, v2, v3
	s_nop 0
	v_cvt_pk_bf16_f32 v3, v4, v5
	global_store_dwordx2 v[54:55], v[2:3], off offset:1024
	global_load_dwordx4 v[2:5], v[42:43], off offset:3072 nt
	s_nop 0
	global_load_dwordx4 v[14:17], v60, s[0:1]
	global_load_dwordx4 v[30:33], v60, s[12:13]
	s_waitcnt vmcnt(2)
	v_pk_mul_f32 v[2:3], v[6:7], v[2:3]
	v_pk_mul_f32 v[4:5], v[8:9], v[4:5]
	s_waitcnt vmcnt(1)
	v_pk_add_f32 v[8:9], v[14:15], 1.0 op_sel_hi:[1,0]
	v_pk_add_f32 v[6:7], v[16:17], 1.0 op_sel_hi:[1,0]
	s_waitcnt vmcnt(0)
	v_pk_fma_f32 v[2:3], v[2:3], v[8:9], v[30:31]
	v_pk_fma_f32 v[4:5], v[4:5], v[6:7], v[32:33]
	v_cvt_pk_bf16_f32 v2, v2, v3
	s_nop 0
	v_cvt_pk_bf16_f32 v3, v4, v5
	global_store_dwordx2 v[54:55], v[2:3], off offset:1536
	global_load_dwordx4 v[2:5], v[44:45], off nt
	s_nop 0
	global_load_dwordx4 v[6:9], v61, s[0:1]
	global_load_dwordx4 v[14:17], v61, s[12:13]
	s_waitcnt vmcnt(2)
	v_pk_mul_f32 v[2:3], v[10:11], v[2:3]
	s_waitcnt vmcnt(1)
	v_pk_add_f32 v[6:7], v[6:7], 1.0 op_sel_hi:[1,0]
	v_pk_mul_f32 v[4:5], v[12:13], v[4:5]
	v_pk_add_f32 v[8:9], v[8:9], 1.0 op_sel_hi:[1,0]
	s_waitcnt vmcnt(0)
	v_pk_fma_f32 v[2:3], v[2:3], v[6:7], v[14:15]
	v_pk_fma_f32 v[4:5], v[4:5], v[8:9], v[16:17]
	v_cvt_pk_bf16_f32 v2, v2, v3
	v_pk_mul_f32 v[16:17], v[26:27], v[0:1] op_sel_hi:[1,0]
	v_cvt_pk_bf16_f32 v3, v4, v5
	global_store_dwordx2 v[54:55], v[2:3], off offset:2048
	global_load_dwordx4 v[2:5], v[46:47], off nt
	s_nop 0
	global_load_dwordx4 v[6:9], v62, s[0:1]
	global_load_dwordx4 v[10:13], v62, s[12:13]
	v_pk_mul_f32 v[14:15], v[28:29], v[0:1] op_sel_hi:[1,0]
	s_waitcnt vmcnt(2)
	v_pk_mul_f32 v[2:3], v[16:17], v[2:3]
	s_waitcnt vmcnt(1)
	v_pk_add_f32 v[6:7], v[6:7], 1.0 op_sel_hi:[1,0]
	v_pk_mul_f32 v[4:5], v[14:15], v[4:5]
	v_pk_add_f32 v[8:9], v[8:9], 1.0 op_sel_hi:[1,0]
	s_waitcnt vmcnt(0)
	v_pk_fma_f32 v[2:3], v[2:3], v[6:7], v[10:11]
	v_pk_fma_f32 v[4:5], v[4:5], v[8:9], v[12:13]
	v_cvt_pk_bf16_f32 v2, v2, v3
	v_pk_mul_f32 v[16:17], v[18:19], v[0:1] op_sel_hi:[1,0]
	v_cvt_pk_bf16_f32 v3, v4, v5
	global_store_dwordx2 v[54:55], v[2:3], off offset:2560
	global_load_dwordx4 v[2:5], v[48:49], off nt
	s_nop 0
	global_load_dwordx4 v[6:9], v63, s[0:1]
	global_load_dwordx4 v[10:13], v63, s[12:13]
	v_pk_mul_f32 v[14:15], v[20:21], v[0:1] op_sel_hi:[1,0]
	s_waitcnt vmcnt(2)
	v_pk_mul_f32 v[2:3], v[16:17], v[2:3]
	s_waitcnt vmcnt(1)
	v_pk_add_f32 v[6:7], v[6:7], 1.0 op_sel_hi:[1,0]
	v_pk_mul_f32 v[4:5], v[14:15], v[4:5]
	v_pk_add_f32 v[8:9], v[8:9], 1.0 op_sel_hi:[1,0]
	s_waitcnt vmcnt(0)
	v_pk_fma_f32 v[2:3], v[2:3], v[6:7], v[10:11]
	v_pk_fma_f32 v[4:5], v[4:5], v[8:9], v[12:13]
	v_cvt_pk_bf16_f32 v2, v2, v3
	v_pk_mul_f32 v[16:17], v[22:23], v[0:1] op_sel_hi:[1,0]
	v_cvt_pk_bf16_f32 v3, v4, v5
	global_store_dwordx2 v[54:55], v[2:3], off offset:3072
	global_load_dwordx4 v[2:5], v[50:51], off nt
	s_nop 0
	global_load_dwordx4 v[6:9], v64, s[0:1]
	global_load_dwordx4 v[10:13], v64, s[12:13]
	v_pk_mul_f32 v[14:15], v[24:25], v[0:1] op_sel_hi:[1,0]
	s_waitcnt vmcnt(2)
	v_pk_mul_f32 v[2:3], v[16:17], v[2:3]
	s_waitcnt vmcnt(1)
	v_pk_add_f32 v[6:7], v[6:7], 1.0 op_sel_hi:[1,0]
	v_pk_mul_f32 v[4:5], v[14:15], v[4:5]
	v_pk_add_f32 v[8:9], v[8:9], 1.0 op_sel_hi:[1,0]
	s_waitcnt vmcnt(0)
	v_pk_fma_f32 v[2:3], v[2:3], v[6:7], v[10:11]
	v_pk_fma_f32 v[4:5], v[4:5], v[8:9], v[12:13]
	v_cvt_pk_bf16_f32 v2, v2, v3
	s_nop 0
	v_cvt_pk_bf16_f32 v3, v4, v5
	global_store_dwordx2 v[54:55], v[2:3], off offset:3584
	v_lshl_add_u64 v[54:55], v[54:55], 0, s[8:9]
	s_cbranch_scc1 .LBB0_878

; __device__ __forceinline__ void norm_rows(const float* x, bf16_t* H, const float* g, const float* modl, int sh_off, int sc_off, int gw, int NGW, int lane, bool stream) {
;     ...
;         for (int b = 0; b < NB; ++b) {
;             f32x4 gp[8], sp[8];
; #pragma unroll
;             for (int j = 0; j < 8; ++j) { const int col = 4 * lane + 256 * j;
;                 gp[j] = *(const f32x4*)(g + col) * (*(const f32x4*)(modl + b * MODW + sc_off + col) + 1.0f); sp[j] = *(const f32x4*)(modl + b * MODW + sh_off + col); }
;             for (int k = 0; k < per_b; k += 2) {
;                 const int m0 = b * SEQ + gw + NGW * k, m1 = m0 + NGW;
;                 const f32x4* x0 = (const f32x4*)(x + (size_t)m0 * DM) + lane; const f32x4* x1 = (const f32x4*)(x + (size_t)m1 * DM) + lane;
;                 f32x4 v0[8], v1[8]; float s0 = 0.f, s1 = 0.f;
;                 if (stream) { _Pragma("unroll") for (int j = 0; j < 8; ++j) { v0[j] = __builtin_nontemporal_load(x0 + 64 * j); v1[j] = __builtin_nontemporal_load(x1 + 64 * j); } }
;                 else { _Pragma("unroll") for (int j = 0; j < 8; ++j) { v0[j] = x0[64 * j]; v1[j] = x1[64 * j]; } }
.LBB0_883:
	v_readlane_b32 s0, v253, 50
	v_readlane_b32 s1, v253, 51
	s_andn2_b64 vcc, exec, s[0:1]
	s_cbranch_vccnz .LBB0_882
	s_mul_i32 s60, s4, 0x3000
	s_lshl_b64 s[0:1], s[60:61], 2
	s_add_u32 s0, s10, s0
	s_addc_u32 s1, s11, s1
	s_add_u32 s12, s0, 0x8000
	s_addc_u32 s13, s1, 0
	global_load_dwordx4 v[2:5], v[82:83], off nt
	global_load_dwordx4 v[6:9], v0, s[12:13]
	s_add_u32 s0, s0, 0x6000
	s_addc_u32 s1, s1, 0
	s_mov_b32 s6, 0
	s_waitcnt vmcnt(0)
	v_pk_add_f32 v[8:9], v[8:9], 1.0 op_sel_hi:[1,0]
	v_pk_add_f32 v[6:7], v[6:7], 1.0 op_sel_hi:[1,0]
	v_pk_mul_f32 v[92:93], v[4:5], v[8:9]
	v_pk_mul_f32 v[94:95], v[2:3], v[6:7]
	global_load_dwordx4 v[2:5], v0, s[0:1]
	global_load_dwordx4 v[6:9], v[82:83], off offset:1024 nt
	global_load_dwordx4 v[10:13], v125, s[12:13]
	s_waitcnt vmcnt(0)
	v_pk_add_f32 v[12:13], v[12:13], 1.0 op_sel_hi:[1,0]
	v_pk_add_f32 v[10:11], v[10:11], 1.0 op_sel_hi:[1,0]
	v_pk_mul_f32 v[96:97], v[8:9], v[12:13]
	v_pk_mul_f32 v[98:99], v[6:7], v[10:11]
	global_load_dwordx4 v[6:9], v125, s[0:1]
	global_load_dwordx4 v[10:13], v[82:83], off offset:2048 nt
	global_load_dwordx4 v[14:17], v126, s[12:13]
	s_waitcnt vmcnt(0)
	v_pk_add_f32 v[16:17], v[16:17], 1.0 op_sel_hi:[1,0]
	v_pk_add_f32 v[14:15], v[14:15], 1.0 op_sel_hi:[1,0]
	v_pk_mul_f32 v[100:101], v[12:13], v[16:17]
	v_pk_mul_f32 v[102:103], v[10:11], v[14:15]
	global_load_dwordx4 v[10:13], v126, s[0:1]
	global_load_dwordx4 v[14:17], v[82:83], off offset:3072 nt
	global_load_dwordx4 v[18:21], v127, s[12:13]
	s_waitcnt vmcnt(0)
	v_pk_add_f32 v[20:21], v[20:21], 1.0 op_sel_hi:[1,0]
	v_pk_add_f32 v[18:19], v[18:19], 1.0 op_sel_hi:[1,0]
	v_pk_mul_f32 v[104:105], v[16:17], v[20:21]
	v_pk_mul_f32 v[106:107], v[14:15], v[18:19]
	global_load_dwordx4 v[14:17], v127, s[0:1]
	global_load_dwordx4 v[18:21], v[84:85], off nt
	global_load_dwordx4 v[22:25], v128, s[12:13]
	s_waitcnt vmcnt(0)
	v_pk_add_f32 v[24:25], v[24:25], 1.0 op_sel_hi:[1,0]
	v_pk_add_f32 v[22:23], v[22:23], 1.0 op_sel_hi:[1,0]
	v_pk_mul_f32 v[108:109], v[20:21], v[24:25]
	v_pk_mul_f32 v[110:111], v[18:19], v[22:23]
	global_load_dwordx4 v[18:21], v128, s[0:1]
	global_load_dwordx4 v[22:25], v[86:87], off nt
	global_load_dwordx4 v[26:29], v129, s[12:13]
	s_waitcnt vmcnt(0)
	v_pk_add_f32 v[28:29], v[28:29], 1.0 op_sel_hi:[1,0]
	v_pk_add_f32 v[26:27], v[26:27], 1.0 op_sel_hi:[1,0]
	v_pk_mul_f32 v[112:113], v[24:25], v[28:29]
	v_pk_mul_f32 v[114:115], v[22:23], v[26:27]
	global_load_dwordx4 v[22:25], v129, s[0:1]
	global_load_dwordx4 v[26:29], v[88:89], off nt
	global_load_dwordx4 v[30:33], v130, s[12:13]
	s_waitcnt vmcnt(0)
	v_pk_add_f32 v[32:33], v[32:33], 1.0 op_sel_hi:[1,0]
	v_pk_add_f32 v[30:31], v[30:31], 1.0 op_sel_hi:[1,0]
	v_pk_mul_f32 v[116:117], v[28:29], v[32:33]
	v_pk_mul_f32 v[118:119], v[26:27], v[30:31]
	global_load_dwordx4 v[26:29], v130, s[0:1]
	global_load_dwordx4 v[30:33], v[90:91], off nt
	global_load_dwordx4 v[34:37], v131, s[12:13]
	s_mov_b32 s12, s5
	s_waitcnt vmcnt(0)
	v_pk_add_f32 v[36:37], v[36:37], 1.0 op_sel_hi:[1,0]
	v_pk_add_f32 v[34:35], v[34:35], 1.0 op_sel_hi:[1,0]
	v_pk_mul_f32 v[120:121], v[32:33], v[36:37]
	v_pk_mul_f32 v[122:123], v[30:31], v[34:35]
	global_load_dwordx4 v[30:33], v131, s[0:1]
	v_and_b32_e32 v35, 64, v206
	v_xor_b32_e32 v34, 32, v206
	v_add_u32_e32 v35, 64, v35
	v_cmp_lt_i32_e32 vcc, v34, v35
	s_nop 1
	v_cndmask_b32_e32 v34, v206, v34, vcc
	v_lshlrev_b32_e32 v132, 2, v34
.LBB0_885:
	s_ashr_i32 s13, s12, 31
	s_lshl_b64 s[0:1], s[12:13], 13
	v_lshl_add_u64 v[34:35], v[78:79], 0, s[0:1]
	s_add_i32 s16, s78, s12
	global_load_dwordx4 v[134:137], v[34:35], off nt
	global_load_dwordx4 v[138:141], v[34:35], off offset:1024 nt
	global_load_dwordx4 v[74:77], v[34:35], off offset:2048 nt
	global_load_dwordx4 v[66:69], v[34:35], off offset:3072 nt
	s_ashr_i32 s17, s16, 31
	v_add_co_u32_e32 v34, vcc, s79, v34
	s_lshl_b64 s[0:1], s[16:17], 13
	s_nop 0
	v_addc_co_u32_e32 v35, vcc, 0, v35, vcc
	v_lshl_add_u64 v[38:39], v[78:79], 0, s[0:1]
	global_load_dwordx4 v[58:61], v[34:35], off nt
	global_load_dwordx4 v[50:53], v[34:35], off offset:1024 nt
	global_load_dwordx4 v[42:45], v[34:35], off offset:2048 nt
	s_nop 0
	global_load_dwordx4 v[34:37], v[34:35], off offset:3072 nt
	s_nop 0
	global_load_dwordx4 v[142:145], v[38:39], off nt
	global_load_dwordx4 v[146:149], v[38:39], off offset:1024 nt
	global_load_dwordx4 v[150:153], v[38:39], off offset:2048 nt
	global_load_dwordx4 v[70:73], v[38:39], off offset:3072 nt
	v_add_co_u32_e32 v38, vcc, s79, v38
	s_add_i32 s6, s6, 2
	s_nop 0
	v_addc_co_u32_e32 v39, vcc, 0, v39, vcc
	global_load_dwordx4 v[62:65], v[38:39], off nt
	global_load_dwordx4 v[54:57], v[38:39], off offset:1024 nt
	global_load_dwordx4 v[46:49], v[38:39], off offset:2048 nt
	s_nop 0
	global_load_dwordx4 v[38:41], v[38:39], off offset:3072 nt
	s_waitcnt vmcnt(15)
	v_mov_b32_e32 v156, v135
	s_waitcnt vmcnt(14)
	v_mov_b32_e32 v157, v139
	v_mov_b32_e32 v154, v134
	v_mov_b32_e32 v155, v138
	v_pk_mul_f32 v[156:157], v[156:157], v[156:157]
	v_mov_b32_e32 v158, v137
	v_mov_b32_e32 v159, v141
	v_pk_fma_f32 v[154:155], v[154:155], v[154:155], v[156:157]
	v_mov_b32_e32 v156, v136
	v_mov_b32_e32 v157, v140
	v_pk_mul_f32 v[158:159], v[158:159], v[158:159]
	s_waitcnt vmcnt(7)
	v_mov_b32_e32 v160, v145
	v_pk_fma_f32 v[156:157], v[156:157], v[156:157], v[158:159]
	v_mov_b32_e32 v158, v143
	s_waitcnt vmcnt(6)
; __device__ __forceinline__ void norm_rows(const float* x, bf16_t* H, const float* g, const float* modl, int sh_off, int sc_off, int gw, int NGW, int lane, bool stream) {
;     ...
; #pragma unroll
;                 for (int j = 0; j < 8; ++j) { s0 += (v0[j][0] * v0[j][0] + v0[j][1] * v0[j][1]) + (v0[j][2] * v0[j][2] + v0[j][3] * v0[j][3]);
;                                               s1 += (v1[j][0] * v1[j][0] + v1[j][1] * v1[j][1]) + (v1[j][2] * v1[j][2] + v1[j][3] * v1[j][3]); }
;                 const float r0 = 1.0f / sqrtf(wave_sum(s0) * (1.0f / DM) + EPS), r1 = 1.0f / sqrtf(wave_sum(s1) * (1.0f / DM) + EPS);
	v_mov_b32_e32 v159, v147
	v_pk_add_f32 v[154:155], v[154:155], v[156:157]
	v_mov_b32_e32 v156, v142
	v_mov_b32_e32 v157, v146
	v_pk_mul_f32 v[158:159], v[158:159], v[158:159]
	v_mov_b32_e32 v161, v149
	v_pk_fma_f32 v[156:157], v[156:157], v[156:157], v[158:159]
	v_mov_b32_e32 v158, v144
	v_mov_b32_e32 v159, v148
	v_pk_mul_f32 v[160:161], v[160:161], v[160:161]
	v_mul_f32_e32 v133, v58, v58
	v_pk_fma_f32 v[158:159], v[158:159], v[158:159], v[160:161]
	v_pk_mul_f32 v[160:161], v[74:75], v[74:75]
	v_pk_add_f32 v[156:157], v[156:157], v[158:159]
	v_pk_mul_f32 v[158:159], v[76:77], v[76:77]
	v_pk_add_f32 v[154:155], v[154:155], v[154:155] op_sel:[0,1] op_sel_hi:[1,0]
	v_pk_mov_b32 v[162:163], v[160:161], v[158:159] op_sel:[1,0]
	v_mov_b32_e32 v161, v159
	v_pk_add_f32 v[158:159], v[162:163], v[160:161]
	s_waitcnt vmcnt(5)
	v_pk_mul_f32 v[160:161], v[152:153], v[152:153]
	v_pk_mul_f32 v[162:163], v[150:151], v[150:151]
	v_pk_add_f32 v[158:159], v[158:159], v[158:159] op_sel:[0,1] op_sel_hi:[1,0]
	v_pk_mov_b32 v[164:165], v[162:163], v[160:161] op_sel:[1,0]
	v_mov_b32_e32 v163, v161
	v_pk_add_f32 v[160:161], v[164:165], v[162:163]
	v_mul_f32_e32 v162, v59, v59
	v_mov_b32_e32 v155, v133
	v_mov_b32_e32 v159, v162
	v_pk_add_f32 v[154:155], v[154:155], v[158:159]
	v_mul_f32_e32 v158, v67, v67
	v_mul_f32_e32 v163, v60, v60
	v_pk_fma_f32 v[158:159], v[66:67], v[66:67], v[158:159] op_sel_hi:[1,1,0]
	v_mul_f32_e32 v162, v69, v69
	v_mul_f32_e32 v164, v61, v61
	v_mov_b32_e32 v159, v163
	v_pk_fma_f32 v[162:163], v[68:69], v[68:69], v[162:163] op_sel_hi:[1,1,0]
	s_waitcnt vmcnt(3)
	v_mul_f32_e32 v133, v62, v62
	v_mov_b32_e32 v163, v164
	v_pk_add_f32 v[158:159], v[158:159], v[162:163]
	v_mul_f32_e32 v162, v63, v63
	v_pk_add_f32 v[154:155], v[154:155], v[158:159]
	v_pk_add_f32 v[156:157], v[156:157], v[156:157] op_sel:[0,1] op_sel_hi:[1,0]
	v_pk_add_f32 v[158:159], v[160:161], v[160:161] op_sel:[0,1] op_sel_hi:[1,0]
	v_mov_b32_e32 v157, v133
	v_mov_b32_e32 v159, v162
	v_pk_add_f32 v[156:157], v[156:157], v[158:159]
	v_mul_f32_e32 v158, v71, v71
	v_mul_f32_e32 v160, v73, v73
	v_mul_f32_e32 v163, v64, v64
	v_mul_f32_e32 v164, v65, v65
	v_pk_fma_f32 v[158:159], v[70:71], v[70:71], v[158:159] op_sel_hi:[1,1,0]
	v_pk_fma_f32 v[160:161], v[72:73], v[72:73], v[160:161] op_sel_hi:[1,1,0]
	v_mov_b32_e32 v159, v163
	v_mov_b32_e32 v161, v164
	v_pk_add_f32 v[158:159], v[158:159], v[160:161]
	v_pk_mul_f32 v[160:161], v[50:51], v[50:51]
	v_pk_add_f32 v[156:157], v[156:157], v[158:159]
	v_pk_mul_f32 v[158:159], v[52:53], v[52:53]
	v_mul_f32_e32 v133, v34, v34
	v_pk_mov_b32 v[162:163], v[160:161], v[158:159] op_sel:[1,0]
	v_mov_b32_e32 v161, v159
	v_pk_add_f32 v[158:159], v[162:163], v[160:161]
	s_waitcnt vmcnt(2)
	v_pk_mul_f32 v[160:161], v[56:57], v[56:57]
	v_pk_mul_f32 v[162:163], v[54:55], v[54:55]
	v_pk_add_f32 v[154:155], v[154:155], v[154:155] op_sel:[0,1] op_sel_hi:[1,0]
	v_pk_mov_b32 v[164:165], v[162:163], v[160:161] op_sel:[1,0]
	v_mov_b32_e32 v163, v161
	v_pk_add_f32 v[160:161], v[164:165], v[162:163]
	v_mul_f32_e32 v162, v35, v35
	v_pk_add_f32 v[158:159], v[158:159], v[158:159] op_sel:[0,1] op_sel_hi:[1,0]
	v_mov_b32_e32 v155, v133
	v_mov_b32_e32 v159, v162
	v_pk_add_f32 v[154:155], v[154:155], v[158:159]
	v_mul_f32_e32 v158, v43, v43
	v_mul_f32_e32 v163, v36, v36
	v_pk_fma_f32 v[158:159], v[42:43], v[42:43], v[158:159] op_sel_hi:[1,1,0]
	v_mul_f32_e32 v162, v45, v45
	v_mul_f32_e32 v164, v37, v37
	v_mov_b32_e32 v159, v163
	v_pk_fma_f32 v[162:163], v[44:45], v[44:45], v[162:163] op_sel_hi:[1,1,0]
	s_nop 0
	v_mov_b32_e32 v163, v164
	v_pk_add_f32 v[158:159], v[158:159], v[162:163]
	s_waitcnt vmcnt(0)
	v_mul_f32_e32 v162, v40, v40
	v_pk_add_f32 v[154:155], v[154:155], v[158:159]
	v_mul_f32_e32 v158, v38, v38
	v_add_f32_e32 v133, v154, v155
	v_mul_f32_e32 v159, v39, v39
	v_pk_add_f32 v[154:155], v[156:157], v[156:157] op_sel:[0,1] op_sel_hi:[1,0]
	v_pk_add_f32 v[156:157], v[160:161], v[160:161] op_sel:[0,1] op_sel_hi:[1,0]
	v_mov_b32_e32 v155, v158
	v_mov_b32_e32 v157, v159
	v_pk_add_f32 v[154:155], v[154:155], v[156:157]
	v_mul_f32_e32 v156, v47, v47
	v_mul_f32_e32 v158, v49, v49
	v_mul_f32_e32 v163, v41, v41
	v_pk_fma_f32 v[156:157], v[46:47], v[46:47], v[156:157] op_sel_hi:[1,1,0]
	v_pk_fma_f32 v[158:159], v[48:49], v[48:49], v[158:159] op_sel_hi:[1,1,0]
	v_mov_b32_e32 v157, v162
	v_mov_b32_e32 v159, v163
	v_pk_add_f32 v[156:157], v[156:157], v[158:159]
	s_nop 0
	v_pk_add_f32 v[154:155], v[154:155], v[156:157]
	s_nop 0
	v_add_f32_e32 v155, v154, v155
	ds_swizzle_b32 v154, v133 offset:swizzle(SWAP,1)
	s_waitcnt lgkmcnt(0)
	v_add_f32_e32 v133, v133, v154
	ds_swizzle_b32 v154, v133 offset:swizzle(SWAP,2)
	s_waitcnt lgkmcnt(0)
	v_add_f32_e32 v133, v133, v154
	ds_swizzle_b32 v154, v133 offset:swizzle(SWAP,4)
	s_waitcnt lgkmcnt(0)
	v_add_f32_e32 v133, v133, v154
	ds_swizzle_b32 v154, v133 offset:swizzle(SWAP,8)
	s_waitcnt lgkmcnt(0)
	v_add_f32_e32 v133, v133, v154
	ds_swizzle_b32 v154, v133 offset:swizzle(SWAP,16)
	s_waitcnt lgkmcnt(0)
	v_add_f32_e32 v133, v133, v154
	ds_bpermute_b32 v154, v132, v133
	s_waitcnt lgkmcnt(0)
; __device__ __forceinline__ unsigned cvt_pk_bf16(float lo, float hi) { unsigned r; asm volatile("v_cvt_pk_bf16_f32 %0, %1, %2" : "=v"(r) : "v"(lo), "v"(hi)); return r; }
; __device__ __forceinline__ void norm_rows(const float* x, bf16_t* H, const float* g, const float* modl, int sh_off, int sc_off, int gw, int NGW, int lane, bool stream) {
;     ...
;                 const float r0 = 1.0f / sqrtf(wave_sum(s0) * (1.0f / DM) + EPS), r1 = 1.0f / sqrtf(wave_sum(s1) * (1.0f / DM) + EPS);
;                 u32x2* o0 = (u32x2*)(H + (size_t)m0 * DM) + lane; u32x2* o1 = (u32x2*)(H + (size_t)m1 * DM) + lane;
; #pragma unroll
;                 for (int j = 0; j < 8; ++j) { const f32x4 a = (v0[j] * r0) * gp[j] + sp[j], c = (v1[j] * r1) * gp[j] + sp[j];
;                     u32x2 w; w.x = cvt_pk_bf16(a[0], a[1]); w.y = cvt_pk_bf16(a[2], a[3]); o0[64 * j] = w;
;                     u32x2 z; z.x = cvt_pk_bf16(c[0], c[1]); z.y = cvt_pk_bf16(c[2], c[3]); o1[64 * j] = z; }
	v_add_f32_e32 v133, v133, v154
	v_fmamk_f32 v133, v133, 0x3a000000, v203
	v_cmp_gt_f32_e32 vcc, s91, v133
	v_mul_f32_e32 v154, 0x4f800000, v133
	s_nop 0
	v_cndmask_b32_e32 v133, v133, v154, vcc
	v_sqrt_f32_e32 v154, v133
	s_nop 0
	v_add_u32_e32 v156, -1, v154
	v_fma_f32 v157, -v156, v154, v133
	v_cmp_ge_f32_e64 s[0:1], 0, v157
	v_add_u32_e32 v157, 1, v154
	s_nop 0
	v_cndmask_b32_e64 v156, v154, v156, s[0:1]
	v_fma_f32 v154, -v157, v154, v133
	v_cmp_lt_f32_e64 s[0:1], 0, v154
	s_nop 1
	v_cndmask_b32_e64 v154, v156, v157, s[0:1]
	v_mul_f32_e32 v156, 0x37800000, v154
	v_cndmask_b32_e32 v154, v154, v156, vcc
	v_cmp_class_f32_e32 vcc, v133, v204
	s_nop 1
	v_cndmask_b32_e32 v133, v154, v133, vcc
	v_div_scale_f32 v154, s[0:1], v133, v133, 1.0
	v_rcp_f32_e32 v156, v154
	s_nop 0
	v_fma_f32 v157, -v154, v156, 1.0
	v_fmac_f32_e32 v156, v157, v156
	v_div_scale_f32 v157, vcc, 1.0, v133, 1.0
	v_mul_f32_e32 v158, v157, v156
	v_fma_f32 v159, -v154, v158, v157
	v_fmac_f32_e32 v158, v159, v156
	v_fma_f32 v154, -v154, v158, v157
	v_div_fmas_f32 v154, v154, v156, v158
	v_div_fixup_f32 v154, v154, v133, 1.0
	ds_swizzle_b32 v133, v155 offset:swizzle(SWAP,1)
	s_waitcnt lgkmcnt(0)
	v_add_f32_e32 v133, v155, v133
	ds_swizzle_b32 v155, v133 offset:swizzle(SWAP,2)
	s_waitcnt lgkmcnt(0)
	v_add_f32_e32 v133, v133, v155
	ds_swizzle_b32 v155, v133 offset:swizzle(SWAP,4)
	s_waitcnt lgkmcnt(0)
	v_add_f32_e32 v133, v133, v155
	ds_swizzle_b32 v155, v133 offset:swizzle(SWAP,8)
	s_waitcnt lgkmcnt(0)
	v_add_f32_e32 v133, v133, v155
	ds_swizzle_b32 v155, v133 offset:swizzle(SWAP,16)
	s_waitcnt lgkmcnt(0)
	v_add_f32_e32 v133, v133, v155
	ds_bpermute_b32 v155, v132, v133
	s_waitcnt lgkmcnt(0)
	v_add_f32_e32 v133, v133, v155
	v_fmamk_f32 v133, v133, 0x3a000000, v203
	v_cmp_gt_f32_e32 vcc, s91, v133
	v_mul_f32_e32 v155, 0x4f800000, v133
	s_nop 0
	v_cndmask_b32_e32 v133, v133, v155, vcc
	v_sqrt_f32_e32 v155, v133
	s_nop 0
	v_add_u32_e32 v156, -1, v155
	v_fma_f32 v157, -v156, v155, v133
	v_cmp_ge_f32_e64 s[0:1], 0, v157
	v_add_u32_e32 v157, 1, v155
	s_nop 0
	v_cndmask_b32_e64 v156, v155, v156, s[0:1]
	v_fma_f32 v155, -v157, v155, v133
	v_cmp_lt_f32_e64 s[0:1], 0, v155
	s_nop 1
	v_cndmask_b32_e64 v155, v156, v157, s[0:1]
	v_mul_f32_e32 v156, 0x37800000, v155
	v_cndmask_b32_e32 v155, v155, v156, vcc
	v_cmp_class_f32_e32 vcc, v133, v204
	s_nop 1
	v_cndmask_b32_e32 v133, v155, v133, vcc
	v_div_scale_f32 v155, s[0:1], v133, v133, 1.0
	v_rcp_f32_e32 v156, v155
	s_lshl_b64 s[0:1], s[12:13], 12
	s_add_i32 s12, s12, s29
	v_fma_f32 v157, -v155, v156, 1.0
	v_fmac_f32_e32 v156, v157, v156
	v_div_scale_f32 v157, vcc, 1.0, v133, 1.0
	v_mul_f32_e32 v158, v157, v156
	v_fma_f32 v159, -v155, v158, v157
	v_fmac_f32_e32 v158, v159, v156
	v_fma_f32 v155, -v155, v158, v157
	v_div_fmas_f32 v155, v155, v156, v158
	v_pk_mul_f32 v[134:135], v[134:135], v[154:155] op_sel_hi:[1,0]
	v_div_fixup_f32 v156, v155, v133, 1.0
	v_pk_mul_f32 v[136:137], v[136:137], v[154:155] op_sel_hi:[1,0]
	v_pk_fma_f32 v[134:135], v[94:95], v[134:135], v[2:3]
	v_lshl_add_u64 v[158:159], v[80:81], 0, s[0:1]
	s_lshl_b64 s[0:1], s[16:17], 12
	v_pk_fma_f32 v[136:137], v[92:93], v[136:137], v[4:5]
	v_pk_mul_f32 v[142:143], v[142:143], v[156:157] op_sel_hi:[1,0]
	v_pk_mul_f32 v[144:145], v[144:145], v[156:157] op_sel_hi:[1,0]
	v_cvt_pk_bf16_f32 v134, v134, v135
	v_cvt_pk_bf16_f32 v135, v136, v137
	v_lshl_add_u64 v[160:161], v[80:81], 0, s[0:1]
	v_pk_fma_f32 v[144:145], v[92:93], v[144:145], v[4:5]
	v_pk_fma_f32 v[142:143], v[94:95], v[142:143], v[2:3]
	global_store_dwordx2 v[158:159], v[134:135], off
	v_cvt_pk_bf16_f32 v134, v142, v143
	v_cvt_pk_bf16_f32 v135, v144, v145
	global_store_dwordx2 v[160:161], v[134:135], off
	v_pk_mul_f32 v[134:135], v[138:139], v[154:155] op_sel_hi:[1,0]
	v_pk_mul_f32 v[136:137], v[140:141], v[154:155] op_sel_hi:[1,0]
	v_pk_fma_f32 v[134:135], v[98:99], v[134:135], v[6:7]
	v_pk_fma_f32 v[136:137], v[96:97], v[136:137], v[8:9]
	v_pk_mul_f32 v[138:139], v[146:147], v[156:157] op_sel_hi:[1,0]
	v_pk_mul_f32 v[140:141], v[148:149], v[156:157] op_sel_hi:[1,0]
	v_cvt_pk_bf16_f32 v134, v134, v135
	v_cvt_pk_bf16_f32 v135, v136, v137
	v_pk_mul_f32 v[74:75], v[74:75], v[154:155] op_sel_hi:[1,0]
	v_pk_fma_f32 v[140:141], v[96:97], v[140:141], v[8:9]
	v_pk_fma_f32 v[138:139], v[98:99], v[138:139], v[6:7]
	global_store_dwordx2 v[158:159], v[134:135], off offset:512
	v_cvt_pk_bf16_f32 v134, v138, v139
; __device__ __forceinline__ unsigned cvt_pk_bf16(float lo, float hi) { unsigned r; asm volatile("v_cvt_pk_bf16_f32 %0, %1, %2" : "=v"(r) : "v"(lo), "v"(hi)); return r; }
; __device__ __forceinline__ void norm_rows(const float* x, bf16_t* H, const float* g, const float* modl, int sh_off, int sc_off, int gw, int NGW, int lane, bool stream) {
;     ...
;                 u32x2* o0 = (u32x2*)(H + (size_t)m0 * DM) + lane; u32x2* o1 = (u32x2*)(H + (size_t)m1 * DM) + lane;
; #pragma unroll
;                 for (int j = 0; j < 8; ++j) { const f32x4 a = (v0[j] * r0) * gp[j] + sp[j], c = (v1[j] * r1) * gp[j] + sp[j];
;                     u32x2 w; w.x = cvt_pk_bf16(a[0], a[1]); w.y = cvt_pk_bf16(a[2], a[3]); o0[64 * j] = w;
;                     u32x2 z; z.x = cvt_pk_bf16(c[0], c[1]); z.y = cvt_pk_bf16(c[2], c[3]); o1[64 * j] = z; }
;             }
	v_cvt_pk_bf16_f32 v135, v140, v141
	v_pk_mul_f32 v[76:77], v[76:77], v[154:155] op_sel_hi:[1,0]
	v_pk_fma_f32 v[74:75], v[102:103], v[74:75], v[10:11]
	v_pk_mul_f32 v[66:67], v[66:67], v[154:155] op_sel_hi:[1,0]
	global_store_dwordx2 v[160:161], v[134:135], off offset:512
	v_pk_fma_f32 v[76:77], v[100:101], v[76:77], v[12:13]
	v_pk_mul_f32 v[134:135], v[150:151], v[156:157] op_sel_hi:[1,0]
	v_pk_mul_f32 v[136:137], v[152:153], v[156:157] op_sel_hi:[1,0]
	v_cvt_pk_bf16_f32 v74, v74, v75
	v_cvt_pk_bf16_f32 v75, v76, v77
	v_pk_mul_f32 v[68:69], v[68:69], v[154:155] op_sel_hi:[1,0]
	v_pk_fma_f32 v[66:67], v[106:107], v[66:67], v[14:15]
	v_pk_mul_f32 v[58:59], v[58:59], v[154:155] op_sel_hi:[1,0]
	v_pk_fma_f32 v[136:137], v[100:101], v[136:137], v[12:13]
	v_pk_fma_f32 v[134:135], v[102:103], v[134:135], v[10:11]
	global_store_dwordx2 v[158:159], v[74:75], off offset:1024
	v_cvt_pk_bf16_f32 v74, v134, v135
	v_cvt_pk_bf16_f32 v75, v136, v137
	global_store_dwordx2 v[160:161], v[74:75], off offset:1024
	v_pk_fma_f32 v[68:69], v[104:105], v[68:69], v[16:17]
	v_pk_mul_f32 v[70:71], v[70:71], v[156:157] op_sel_hi:[1,0]
	v_pk_mul_f32 v[72:73], v[72:73], v[156:157] op_sel_hi:[1,0]
	v_cvt_pk_bf16_f32 v66, v66, v67
	v_cvt_pk_bf16_f32 v67, v68, v69
	v_pk_mul_f32 v[60:61], v[60:61], v[154:155] op_sel_hi:[1,0]
	v_pk_fma_f32 v[58:59], v[110:111], v[58:59], v[18:19]
	v_pk_mul_f32 v[50:51], v[50:51], v[154:155] op_sel_hi:[1,0]
	v_pk_fma_f32 v[72:73], v[104:105], v[72:73], v[16:17]
	v_pk_fma_f32 v[70:71], v[106:107], v[70:71], v[14:15]
	global_store_dwordx2 v[158:159], v[66:67], off offset:1536
	v_cvt_pk_bf16_f32 v66, v70, v71
	v_cvt_pk_bf16_f32 v67, v72, v73
	global_store_dwordx2 v[160:161], v[66:67], off offset:1536
	v_pk_fma_f32 v[60:61], v[108:109], v[60:61], v[20:21]
	v_pk_mul_f32 v[62:63], v[62:63], v[156:157] op_sel_hi:[1,0]
	v_pk_mul_f32 v[64:65], v[64:65], v[156:157] op_sel_hi:[1,0]
	v_cvt_pk_bf16_f32 v58, v58, v59
	v_cvt_pk_bf16_f32 v59, v60, v61
	v_pk_mul_f32 v[52:53], v[52:53], v[154:155] op_sel_hi:[1,0]
	v_pk_fma_f32 v[50:51], v[114:115], v[50:51], v[22:23]
	v_pk_mul_f32 v[42:43], v[42:43], v[154:155] op_sel_hi:[1,0]
	v_pk_fma_f32 v[64:65], v[108:109], v[64:65], v[20:21]
	v_pk_fma_f32 v[62:63], v[110:111], v[62:63], v[18:19]
	global_store_dwordx2 v[158:159], v[58:59], off offset:2048
	v_cvt_pk_bf16_f32 v58, v62, v63
	v_cvt_pk_bf16_f32 v59, v64, v65
	global_store_dwordx2 v[160:161], v[58:59], off offset:2048
	v_pk_fma_f32 v[52:53], v[112:113], v[52:53], v[24:25]
	v_pk_mul_f32 v[54:55], v[54:55], v[156:157] op_sel_hi:[1,0]
	v_pk_mul_f32 v[56:57], v[56:57], v[156:157] op_sel_hi:[1,0]
	v_cvt_pk_bf16_f32 v50, v50, v51
	v_cvt_pk_bf16_f32 v51, v52, v53
	v_pk_mul_f32 v[44:45], v[44:45], v[154:155] op_sel_hi:[1,0]
	v_pk_fma_f32 v[42:43], v[118:119], v[42:43], v[26:27]
	v_pk_mul_f32 v[34:35], v[34:35], v[154:155] op_sel_hi:[1,0]
	v_pk_fma_f32 v[56:57], v[112:113], v[56:57], v[24:25]
	v_pk_fma_f32 v[54:55], v[114:115], v[54:55], v[22:23]
	global_store_dwordx2 v[158:159], v[50:51], off offset:2560
	v_cvt_pk_bf16_f32 v50, v54, v55
	v_cvt_pk_bf16_f32 v51, v56, v57
	global_store_dwordx2 v[160:161], v[50:51], off offset:2560
	v_pk_fma_f32 v[44:45], v[116:117], v[44:45], v[28:29]
	v_pk_mul_f32 v[46:47], v[46:47], v[156:157] op_sel_hi:[1,0]
	v_pk_mul_f32 v[48:49], v[48:49], v[156:157] op_sel_hi:[1,0]
	v_cvt_pk_bf16_f32 v42, v42, v43
	v_cvt_pk_bf16_f32 v43, v44, v45
	v_pk_mul_f32 v[36:37], v[36:37], v[154:155] op_sel_hi:[1,0]
	v_pk_fma_f32 v[34:35], v[122:123], v[34:35], v[30:31]
	v_pk_fma_f32 v[48:49], v[116:117], v[48:49], v[28:29]
	v_pk_fma_f32 v[46:47], v[118:119], v[46:47], v[26:27]
	global_store_dwordx2 v[158:159], v[42:43], off offset:3072
	v_cvt_pk_bf16_f32 v42, v46, v47
	v_cvt_pk_bf16_f32 v43, v48, v49
	global_store_dwordx2 v[160:161], v[42:43], off offset:3072
	v_pk_fma_f32 v[36:37], v[120:121], v[36:37], v[32:33]
	v_pk_mul_f32 v[38:39], v[38:39], v[156:157] op_sel_hi:[1,0]
	v_pk_mul_f32 v[40:41], v[40:41], v[156:157] op_sel_hi:[1,0]
	v_cvt_pk_bf16_f32 v34, v34, v35
	v_cvt_pk_bf16_f32 v35, v36, v37
	s_cmp_ge_i32 s6, s33
	v_pk_fma_f32 v[40:41], v[120:121], v[40:41], v[32:33]
	v_pk_fma_f32 v[38:39], v[122:123], v[38:39], v[30:31]
	global_store_dwordx2 v[158:159], v[34:35], off offset:3584
	v_cvt_pk_bf16_f32 v34, v38, v39
	v_cvt_pk_bf16_f32 v35, v40, v41
	global_store_dwordx2 v[160:161], v[34:35], off offset:3584
	s_cbranch_scc0 .LBB0_885
	s_branch .LBB0_882

; __device__ __forceinline__ void norm_rows(const float* x, bf16_t* H, const float* g, const float* modl, int sh_off, int sc_off, int gw, int NGW, int lane, bool stream) {
;     ...
;         const int blk_ = gw >> 3, wv_ = gw & 7, x_ = blk_ & 7, i_ = blk_ >> 3, b = x_ >> 1, rbase = 2048 * x_ + 64 * i_ + 8 * wv_;
;         f32x4 gp[8], sp[8];
; #pragma unroll
;         for (int j = 0; j < 8; ++j) { const int col = 4 * lane + 256 * j;
;             gp[j] = *(const f32x4*)(g + col) * (*(const f32x4*)(modl + b * MODW + sc_off + col) + 1.0f); sp[j] = *(const f32x4*)(modl + b * MODW + sh_off + col); }
;         for (int k = 0; k < 8; k += 4) {
;             const f32x4* xp = (const f32x4*)(x + (size_t)(rbase + k) * DM) + lane;
;             f32x4 v[4][8]; float s[4] = {0.f, 0.f, 0.f, 0.f};
;             if (stream) { _Pragma("unroll") for (int q = 0; q < 4; ++q) _Pragma("unroll") for (int j = 0; j < 8; ++j) v[q][j] = __builtin_nontemporal_load(xp + q * (DM / 4) + 64 * j); }
;             else { _Pragma("unroll") for (int q = 0; q < 4; ++q) _Pragma("unroll") for (int j = 0; j < 8; ++j) v[q][j] = xp[q * (DM / 4) + 64 * j]; }
.LBB0_887:
	s_andn2_b64 vcc, exec, s[0:1]
	s_cbranch_vccnz .LBB0_889
	v_readlane_b32 s0, v254, 34
	s_lshl_b32 s0, s0, 2
	s_add_u32 s4, s10, s0
	s_addc_u32 s5, s11, 0
	s_add_u32 s0, s4, 0x8000
	v_lshlrev_b32_e32 v0, 4, v124
	s_addc_u32 s1, s5, 0
	v_or_b32_e32 v3, 0x800, v0
	v_or_b32_e32 v4, 0xc00, v0
	global_load_dwordx4 v[42:45], v3, s[0:1]
	global_load_dwordx4 v[46:49], v4, s[0:1]
	v_or_b32_e32 v2, 0x400, v0
	global_load_dwordx4 v[34:37], v0, s[0:1]
	global_load_dwordx4 v[38:41], v2, s[0:1]
	v_or_b32_e32 v5, 0x1000, v0
	v_or_b32_e32 v6, 0x1400, v0
	v_or_b32_e32 v7, 0x1800, v0
	s_waitcnt vmcnt(23)
	v_or_b32_e32 v102, 0x1c00, v0
	global_load_dwordx4 v[50:53], v5, s[0:1]
	global_load_dwordx4 v[54:57], v6, s[0:1]
	global_load_dwordx4 v[58:61], v7, s[0:1]
	global_load_dwordx4 v[62:65], v102, s[0:1]
	global_load_dwordx4 v[66:69], v0, s[14:15]
	global_load_dwordx4 v[70:73], v0, s[14:15] offset:1024
	global_load_dwordx4 v[74:77], v0, s[14:15] offset:2048
	global_load_dwordx4 v[78:81], v0, s[14:15] offset:3072
	global_load_dwordx4 v[82:85], v5, s[14:15]
	global_load_dwordx4 v[86:89], v6, s[14:15]
	global_load_dwordx4 v[90:93], v7, s[14:15]
	global_load_dwordx4 v[94:97], v102, s[14:15]
	v_readlane_b32 s0, v251, 21
	v_lshl_add_u64 v[200:201], s[70:71], 0, v[0:1]
	v_readlane_b32 s1, v251, 22
	v_and_b32_e32 v9, 64, v206
	v_xor_b32_e32 v8, 32, v206
	v_lshl_add_u64 v[98:99], v[200:201], 0, s[0:1]
	global_load_dwordx4 v[154:157], v[98:99], off nt
	global_load_dwordx4 v[150:153], v[98:99], off offset:1024 nt
	global_load_dwordx4 v[146:149], v[98:99], off offset:2048 nt
	v_add_u32_e32 v9, 64, v9
	v_cmp_lt_i32_e32 vcc, v8, v9
	s_add_u32 s0, s4, 0x6000
	s_addc_u32 s1, s5, 0
	v_cndmask_b32_e32 v8, v206, v8, vcc
	v_add_co_u32_e32 v100, vcc, s79, v98
	v_lshlrev_b32_e32 v213, 2, v8
	s_nop 0
	v_addc_co_u32_e32 v101, vcc, 0, v99, vcc
	global_load_dwordx4 v[130:133], v[100:101], off nt
	global_load_dwordx4 v[30:33], v0, s[0:1]
	global_load_dwordx4 v[26:29], v2, s[0:1]
	global_load_dwordx4 v[22:25], v3, s[0:1]
	global_load_dwordx4 v[18:21], v4, s[0:1]
	global_load_dwordx4 v[14:17], v5, s[0:1]
	global_load_dwordx4 v[10:13], v6, s[0:1]
	s_nop 0
	global_load_dwordx4 v[6:9], v7, s[0:1]
	s_nop 0
	global_load_dwordx4 v[2:5], v102, s[0:1]
	global_load_dwordx4 v[158:161], v[98:99], off offset:3072 nt
	s_movk_i32 s6, 0x7000
	s_movk_i32 s7, 0x6000
	s_movk_i32 s8, 0x5000
	s_movk_i32 s9, 0x2000
	s_movk_i32 s4, 0x4000
	v_lshlrev_b32_e32 v0, 3, v124
	s_movk_i32 s5, 0x3000
	v_readlane_b32 s0, v252, 61
	v_readlane_b32 s1, v252, 62
	s_waitcnt vmcnt(28)
	v_pk_add_f32 v[44:45], v[44:45], 1.0 op_sel_hi:[1,0]
	s_waitcnt vmcnt(27)
	v_pk_add_f32 v[46:47], v[46:47], 1.0 op_sel_hi:[1,0]
	v_pk_add_f32 v[42:43], v[42:43], 1.0 op_sel_hi:[1,0]
	s_waitcnt vmcnt(26)
	v_pk_add_f32 v[36:37], v[36:37], 1.0 op_sel_hi:[1,0]
	v_pk_add_f32 v[34:35], v[34:35], 1.0 op_sel_hi:[1,0]
	s_waitcnt vmcnt(25)
	v_pk_add_f32 v[40:41], v[40:41], 1.0 op_sel_hi:[1,0]
	v_pk_add_f32 v[38:39], v[38:39], 1.0 op_sel_hi:[1,0]
	v_pk_add_f32 v[48:49], v[48:49], 1.0 op_sel_hi:[1,0]
	s_waitcnt vmcnt(17)
	v_pk_mul_f32 v[184:185], v[78:79], v[46:47]
	v_add_co_u32_e32 v46, vcc, s6, v98
	v_pk_mul_f32 v[194:195], v[68:69], v[36:37]
	s_nop 0
	v_addc_co_u32_e32 v47, vcc, 0, v99, vcc
	v_pk_mul_f32 v[196:197], v[66:67], v[34:35]
	v_pk_mul_f32 v[190:191], v[72:73], v[40:41]
	v_pk_mul_f32 v[192:193], v[70:71], v[38:39]
	v_pk_mul_f32 v[186:187], v[76:77], v[44:45]
	v_pk_mul_f32 v[188:189], v[74:75], v[42:43]
	v_pk_mul_f32 v[182:183], v[80:81], v[48:49]
	global_load_dwordx4 v[34:37], v[46:47], off offset:3072 nt
	global_load_dwordx4 v[38:41], v[46:47], off offset:2048 nt
	global_load_dwordx4 v[142:145], v[100:101], off offset:1024 nt
	global_load_dwordx4 v[42:45], v[46:47], off offset:1024 nt
	s_nop 0
	global_load_dwordx4 v[46:49], v[46:47], off nt
	s_nop 0
	global_load_dwordx4 v[138:141], v[100:101], off offset:2048 nt
	global_load_dwordx4 v[134:137], v[100:101], off offset:3072 nt
	v_pk_add_f32 v[62:63], v[62:63], 1.0 op_sel_hi:[1,0]
	v_pk_add_f32 v[52:53], v[52:53], 1.0 op_sel_hi:[1,0]
	s_waitcnt vmcnt(20)
	v_pk_mul_f32 v[164:165], v[94:95], v[62:63]
	v_add_co_u32_e32 v62, vcc, s7, v98
	v_pk_add_f32 v[50:51], v[50:51], 1.0 op_sel_hi:[1,0]
	s_nop 0
	v_addc_co_u32_e32 v63, vcc, 0, v99, vcc
	v_add_co_u32_e32 v78, vcc, s8, v98
	v_pk_add_f32 v[56:57], v[56:57], 1.0 op_sel_hi:[1,0]
	s_nop 0
	v_addc_co_u32_e32 v79, vcc, 0, v99, vcc
	v_add_co_u32_e32 v100, vcc, s9, v98
	v_pk_add_f32 v[54:55], v[54:55], 1.0 op_sel_hi:[1,0]
	v_pk_add_f32 v[60:61], v[60:61], 1.0 op_sel_hi:[1,0]
	v_pk_add_f32 v[58:59], v[58:59], 1.0 op_sel_hi:[1,0]
	v_pk_add_f32 v[64:65], v[64:65], 1.0 op_sel_hi:[1,0]
	v_addc_co_u32_e32 v101, vcc, 0, v99, vcc
	v_pk_mul_f32 v[174:175], v[84:85], v[52:53]
	v_pk_mul_f32 v[176:177], v[82:83], v[50:51]
	v_pk_mul_f32 v[170:171], v[88:89], v[56:57]
	v_pk_mul_f32 v[172:173], v[86:87], v[54:55]
	v_pk_mul_f32 v[166:167], v[92:93], v[60:61]
	v_pk_mul_f32 v[168:169], v[90:91], v[58:59]
	v_pk_mul_f32 v[162:163], v[96:97], v[64:65]
	global_load_dwordx4 v[50:53], v[62:63], off offset:3072 nt
	global_load_dwordx4 v[54:57], v[62:63], off offset:2048 nt
	global_load_dwordx4 v[58:61], v[62:63], off offset:1024 nt
	s_nop 0
	global_load_dwordx4 v[62:65], v[62:63], off nt
	s_nop 0
	global_load_dwordx4 v[66:69], v[78:79], off offset:3072 nt
	global_load_dwordx4 v[70:73], v[78:79], off offset:2048 nt
	global_load_dwordx4 v[122:125], v[100:101], off offset:1024 nt
	global_load_dwordx4 v[126:129], v[100:101], off nt
	global_load_dwordx4 v[74:77], v[78:79], off offset:1024 nt
	s_nop 0
	global_load_dwordx4 v[78:81], v[78:79], off nt
	v_add_co_u32_e32 v94, vcc, s4, v98
	s_waitcnt vmcnt(29)
; __device__ __forceinline__ void norm_rows(const float* x, bf16_t* H, const float* g, const float* modl, int sh_off, int sc_off, int gw, int NGW, int lane, bool stream) {
;     ...
;         for (int k = 0; k < 8; k += 4) {
;             const f32x4* xp = (const f32x4*)(x + (size_t)(rbase + k) * DM) + lane;
;             f32x4 v[4][8]; float s[4] = {0.f, 0.f, 0.f, 0.f};
;             if (stream) { _Pragma("unroll") for (int q = 0; q < 4; ++q) _Pragma("unroll") for (int j = 0; j < 8; ++j) v[q][j] = __builtin_nontemporal_load(xp + q * (DM / 4) + 64 * j); }
;             else { _Pragma("unroll") for (int q = 0; q < 4; ++q) _Pragma("unroll") for (int j = 0; j < 8; ++j) v[q][j] = xp[q * (DM / 4) + 64 * j]; }
; #pragma unroll
;             for (int q = 0; q < 4; ++q)
; #pragma unroll
;                 for (int j = 0; j < 8; ++j) s[q] += (v[q][j][0] * v[q][j][0] + v[q][j][1] * v[q][j][1]) + (v[q][j][2] * v[q][j][2] + v[q][j][3] * v[q][j][3]);
	v_mov_b32_e32 v216, v155
	v_addc_co_u32_e32 v95, vcc, 0, v99, vcc
	global_load_dwordx4 v[82:85], v[94:95], off offset:3072 nt
	global_load_dwordx4 v[86:89], v[94:95], off offset:2048 nt
	global_load_dwordx4 v[90:93], v[94:95], off offset:1024 nt
	s_nop 0
	global_load_dwordx4 v[94:97], v[94:95], off nt
	s_nop 0
	global_load_dwordx4 v[114:117], v[100:101], off offset:3072 nt
	global_load_dwordx4 v[118:121], v[100:101], off offset:2048 nt
	v_add_co_u32_e32 v110, vcc, s5, v98
	s_waitcnt vmcnt(34)
	v_mov_b32_e32 v217, v151
	v_addc_co_u32_e32 v111, vcc, 0, v99, vcc
	global_load_dwordx4 v[98:101], v[110:111], off offset:3072 nt
	global_load_dwordx4 v[102:105], v[110:111], off offset:2048 nt
	global_load_dwordx4 v[106:109], v[110:111], off offset:1024 nt
	s_nop 0
	global_load_dwordx4 v[110:113], v[110:111], off nt
	v_mov_b32_e32 v214, v154
	v_mov_b32_e32 v215, v150
	v_pk_mul_f32 v[216:217], v[216:217], v[216:217]
	v_mov_b32_e32 v218, v157
	v_mov_b32_e32 v219, v153
	v_pk_fma_f32 v[214:215], v[214:215], v[214:215], v[216:217]
	v_mov_b32_e32 v216, v156
	v_mov_b32_e32 v217, v152
	v_pk_mul_f32 v[218:219], v[218:219], v[218:219]
	v_lshl_add_u64 v[198:199], s[0:1], 0, v[0:1]
	v_pk_fma_f32 v[216:217], v[216:217], v[216:217], v[218:219]
	s_waitcnt vmcnt(37)
	v_pk_mul_f32 v[218:219], v[146:147], v[146:147]
	v_pk_add_f32 v[214:215], v[214:215], v[216:217]
	v_pk_mul_f32 v[216:217], v[148:149], v[148:149]
	s_waitcnt vmcnt(36)
	v_mul_f32_e32 v0, v130, v130
	v_pk_mov_b32 v[220:221], v[218:219], v[216:217] op_sel:[1,0]
	v_mov_b32_e32 v219, v217
	v_pk_add_f32 v[216:217], v[220:221], v[218:219]
	v_mul_f32_e32 v218, v131, v131
	v_pk_add_f32 v[214:215], v[214:215], v[214:215] op_sel:[0,1] op_sel_hi:[1,0]
	v_pk_add_f32 v[216:217], v[216:217], v[216:217] op_sel:[0,1] op_sel_hi:[1,0]
	v_mov_b32_e32 v215, v0
	v_mov_b32_e32 v217, v218
	s_waitcnt vmcnt(27)
	v_mul_f32_e32 v0, v159, v159
	v_mul_f32_e32 v219, v132, v132
	v_pk_add_f32 v[214:215], v[214:215], v[216:217]
	v_pk_fma_f32 v[216:217], v[158:159], v[158:159], v[0:1] op_sel_hi:[1,1,0]
	v_mul_f32_e32 v0, v161, v161
	v_mul_f32_e32 v220, v133, v133
	v_mov_b32_e32 v217, v219
	v_pk_fma_f32 v[218:219], v[160:161], v[160:161], v[0:1] op_sel_hi:[1,1,0]
	s_waitcnt vmcnt(20)
	v_mul_f32_e32 v0, v134, v134
	v_mov_b32_e32 v219, v220
	v_pk_add_f32 v[216:217], v[216:217], v[218:219]
	v_pk_mul_f32 v[218:219], v[142:143], v[142:143]
	v_pk_add_f32 v[214:215], v[214:215], v[216:217]
	v_pk_mul_f32 v[216:217], v[144:145], v[144:145]
	v_pk_add_f32 v[214:215], v[214:215], v[214:215] op_sel:[0,1] op_sel_hi:[1,0]
	v_pk_mov_b32 v[220:221], v[218:219], v[216:217] op_sel:[1,0]
	v_mov_b32_e32 v219, v217
	v_pk_add_f32 v[216:217], v[220:221], v[218:219]
	v_mul_f32_e32 v218, v135, v135
	v_pk_add_f32 v[216:217], v[216:217], v[216:217] op_sel:[0,1] op_sel_hi:[1,0]
	v_mov_b32_e32 v215, v0
	v_mov_b32_e32 v217, v218
	v_mul_f32_e32 v0, v139, v139
	v_mul_f32_e32 v219, v136, v136
	v_pk_add_f32 v[214:215], v[214:215], v[216:217]
	v_pk_fma_f32 v[216:217], v[138:139], v[138:139], v[0:1] op_sel_hi:[1,1,0]
	v_mul_f32_e32 v0, v141, v141
	v_mul_f32_e32 v220, v137, v137
	v_mov_b32_e32 v217, v219
	v_pk_fma_f32 v[218:219], v[140:141], v[140:141], v[0:1] op_sel_hi:[1,1,0]
	s_waitcnt vmcnt(5)
	v_mul_f32_e32 v0, v114, v114
	v_mov_b32_e32 v219, v220
	v_pk_add_f32 v[216:217], v[216:217], v[218:219]
	v_mov_b32_e32 v218, v125
	v_pk_add_f32 v[214:215], v[214:215], v[216:217]
	v_mov_b32_e32 v216, v123
	v_mov_b32_e32 v217, v127
	v_add_f32_e32 v222, v214, v215
	v_mov_b32_e32 v214, v122
	v_mov_b32_e32 v215, v126
	v_pk_mul_f32 v[216:217], v[216:217], v[216:217]
	v_mov_b32_e32 v219, v129
	v_pk_fma_f32 v[214:215], v[214:215], v[214:215], v[216:217]
	v_mov_b32_e32 v216, v124
	v_mov_b32_e32 v217, v128
	v_pk_mul_f32 v[218:219], v[218:219], v[218:219]
	s_nop 0
	v_pk_fma_f32 v[216:217], v[216:217], v[216:217], v[218:219]
	s_waitcnt vmcnt(4)
	v_pk_mul_f32 v[218:219], v[118:119], v[118:119]
	v_pk_add_f32 v[214:215], v[214:215], v[216:217]
	v_pk_mul_f32 v[216:217], v[120:121], v[120:121]
	v_pk_add_f32 v[214:215], v[214:215], v[214:215] op_sel_hi:[0,1]
	v_pk_mov_b32 v[220:221], v[218:219], v[216:217] op_sel:[1,0]
	v_mov_b32_e32 v219, v217
	v_pk_add_f32 v[216:217], v[220:221], v[218:219]
	v_pk_fma_f32 v[218:219], v[114:115], v[114:115], v[0:1] op_sel_hi:[1,1,0]
	v_mul_f32_e32 v0, v116, v116
	v_pk_add_f32 v[216:217], v[216:217], v[216:217] op_sel_hi:[0,1]
	v_pk_fma_f32 v[220:221], v[116:117], v[116:117], v[0:1] op_sel_hi:[1,1,0]
	s_waitcnt vmcnt(0)
; template <int M> __device__ __forceinline__ float swz_xor(float v) { return __builtin_bit_cast(float, __builtin_amdgcn_ds_swizzle(__builtin_bit_cast(int, v), (M << 10) | 0x1F)); }
; __device__ __forceinline__ float wave_sum(float v) {
;     v += swz_xor<1>(v); v += swz_xor<2>(v); v += swz_xor<4>(v); v += swz_xor<8>(v); v += swz_xor<16>(v);
;     return v + __shfl_xor(v, 32);
; }
; __device__ __forceinline__ void norm_rows(const float* x, bf16_t* H, const float* g, const float* modl, int sh_off, int sc_off, int gw, int NGW, int lane, bool stream) {
;     ...
; #pragma unroll
;             for (int q = 0; q < 4; ++q)
; #pragma unroll
;                 for (int j = 0; j < 8; ++j) s[q] += (v[q][j][0] * v[q][j][0] + v[q][j][1] * v[q][j][1]) + (v[q][j][2] * v[q][j][2] + v[q][j][3] * v[q][j][3]);
; #pragma unroll
;             for (int q = 0; q < 4; ++q) { const float r = 1.0f / sqrtf(wave_sum(s[q]) * (1.0f / DM) + EPS);
	v_mul_f32_e32 v218, v110, v110
	v_mul_f32_e32 v220, v111, v111
	v_mul_f32_e32 v216, v112, v112
	v_mul_f32_e32 v214, v113, v113
	v_pk_add_f32 v[218:219], v[218:219], v[220:221]
	v_pk_add_f32 v[214:215], v[216:217], v[214:215]
	v_pk_mul_f32 v[216:217], v[108:109], v[108:109]
	v_pk_add_f32 v[214:215], v[218:219], v[214:215]
	v_pk_mul_f32 v[218:219], v[106:107], v[106:107]
	v_mul_f32_e32 v0, v102, v102
	v_pk_mov_b32 v[220:221], v[218:219], v[216:217] op_sel:[1,0]
	v_mov_b32_e32 v219, v217
	v_pk_add_f32 v[216:217], v[220:221], v[218:219]
	v_pk_fma_f32 v[218:219], v[102:103], v[102:103], v[0:1] op_sel_hi:[1,1,0]
	v_mul_f32_e32 v0, v104, v104
	v_pk_add_f32 v[214:215], v[214:215], v[214:215] op_sel_hi:[0,1]
	v_pk_add_f32 v[216:217], v[216:217], v[216:217] op_sel_hi:[0,1]
	v_pk_fma_f32 v[220:221], v[104:105], v[104:105], v[0:1] op_sel_hi:[1,1,0]
	v_mul_f32_e32 v218, v98, v98
	v_mul_f32_e32 v220, v99, v99
	v_mul_f32_e32 v216, v100, v100
	v_mul_f32_e32 v214, v101, v101
	v_pk_add_f32 v[218:219], v[218:219], v[220:221]
	v_pk_add_f32 v[214:215], v[216:217], v[214:215]
	v_mov_b32_e32 v216, v91
	v_pk_add_f32 v[214:215], v[218:219], v[214:215]
	v_mov_b32_e32 v217, v95
	v_add_f32_e32 v223, v214, v215
	v_mov_b32_e32 v214, v90
	v_mov_b32_e32 v215, v94
	v_pk_mul_f32 v[216:217], v[216:217], v[216:217]
	v_mov_b32_e32 v218, v93
	v_mov_b32_e32 v219, v97
	v_pk_fma_f32 v[214:215], v[214:215], v[214:215], v[216:217]
	v_mov_b32_e32 v216, v92
	v_mov_b32_e32 v217, v96
	v_pk_mul_f32 v[218:219], v[218:219], v[218:219]
	v_mul_f32_e32 v0, v82, v82
	v_pk_fma_f32 v[216:217], v[216:217], v[216:217], v[218:219]
	v_pk_mul_f32 v[218:219], v[86:87], v[86:87]
	v_pk_add_f32 v[214:215], v[214:215], v[216:217]
	v_pk_mul_f32 v[216:217], v[88:89], v[88:89]
	v_pk_add_f32 v[214:215], v[214:215], v[214:215] op_sel_hi:[0,1]
	v_pk_mov_b32 v[220:221], v[218:219], v[216:217] op_sel:[1,0]
	v_mov_b32_e32 v219, v217
	v_pk_add_f32 v[216:217], v[220:221], v[218:219]
	v_pk_fma_f32 v[218:219], v[82:83], v[82:83], v[0:1] op_sel_hi:[1,1,0]
	v_mul_f32_e32 v0, v84, v84
	v_pk_add_f32 v[216:217], v[216:217], v[216:217] op_sel_hi:[0,1]
	v_pk_fma_f32 v[220:221], v[84:85], v[84:85], v[0:1] op_sel_hi:[1,1,0]
	v_mul_f32_e32 v218, v78, v78
	v_mul_f32_e32 v220, v79, v79
	v_mul_f32_e32 v216, v80, v80
	v_mul_f32_e32 v214, v81, v81
	v_pk_add_f32 v[218:219], v[218:219], v[220:221]
	v_pk_add_f32 v[214:215], v[216:217], v[214:215]
	v_pk_mul_f32 v[216:217], v[76:77], v[76:77]
	v_pk_add_f32 v[214:215], v[218:219], v[214:215]
	v_pk_mul_f32 v[218:219], v[74:75], v[74:75]
	v_mul_f32_e32 v0, v70, v70
	v_pk_mov_b32 v[220:221], v[218:219], v[216:217] op_sel:[1,0]
	v_mov_b32_e32 v219, v217
	v_pk_add_f32 v[216:217], v[220:221], v[218:219]
	v_pk_fma_f32 v[218:219], v[70:71], v[70:71], v[0:1] op_sel_hi:[1,1,0]
	v_mul_f32_e32 v0, v72, v72
	v_pk_add_f32 v[214:215], v[214:215], v[214:215] op_sel_hi:[0,1]
	v_pk_add_f32 v[216:217], v[216:217], v[216:217] op_sel_hi:[0,1]
	v_pk_fma_f32 v[220:221], v[72:73], v[72:73], v[0:1] op_sel_hi:[1,1,0]
	v_mul_f32_e32 v218, v66, v66
	v_mul_f32_e32 v220, v67, v67
	v_mul_f32_e32 v216, v68, v68
	v_mul_f32_e32 v214, v69, v69
	v_pk_add_f32 v[218:219], v[218:219], v[220:221]
	v_pk_add_f32 v[214:215], v[216:217], v[214:215]
	v_mov_b32_e32 v216, v59
	v_pk_add_f32 v[214:215], v[218:219], v[214:215]
	v_mov_b32_e32 v217, v63
	v_add_f32_e32 v224, v214, v215
	v_mov_b32_e32 v214, v58
	v_mov_b32_e32 v215, v62
	v_pk_mul_f32 v[216:217], v[216:217], v[216:217]
	v_mov_b32_e32 v218, v61
	v_mov_b32_e32 v219, v65
	v_pk_fma_f32 v[214:215], v[214:215], v[214:215], v[216:217]
	v_mov_b32_e32 v216, v60
	v_mov_b32_e32 v217, v64
	v_pk_mul_f32 v[218:219], v[218:219], v[218:219]
	v_mul_f32_e32 v0, v50, v50
	v_pk_fma_f32 v[216:217], v[216:217], v[216:217], v[218:219]
	v_pk_mul_f32 v[218:219], v[54:55], v[54:55]
	v_pk_add_f32 v[214:215], v[214:215], v[216:217]
	v_pk_mul_f32 v[216:217], v[56:57], v[56:57]
	v_pk_add_f32 v[214:215], v[214:215], v[214:215] op_sel_hi:[0,1]
	ds_swizzle_b32 v214, v222 offset:swizzle(SWAP,1)
	v_pk_mov_b32 v[220:221], v[218:219], v[216:217] op_sel:[1,0]
	v_mov_b32_e32 v219, v217
	v_pk_add_f32 v[216:217], v[220:221], v[218:219]
	v_pk_fma_f32 v[218:219], v[50:51], v[50:51], v[0:1] op_sel_hi:[1,1,0]
	v_mul_f32_e32 v0, v52, v52
	v_pk_fma_f32 v[220:221], v[52:53], v[52:53], v[0:1] op_sel_hi:[1,1,0]
	s_waitcnt lgkmcnt(0)
	v_add_f32_e32 v0, v222, v214
	ds_swizzle_b32 v222, v0 offset:swizzle(SWAP,2)
	v_pk_add_f32 v[216:217], v[216:217], v[216:217] op_sel_hi:[0,1]
	v_mul_f32_e32 v218, v46, v46
	v_mul_f32_e32 v220, v47, v47
	v_mul_f32_e32 v216, v48, v48
	s_waitcnt lgkmcnt(0)
	v_add_f32_e32 v0, v0, v222
	ds_swizzle_b32 v222, v0 offset:swizzle(SWAP,4)
	v_mul_f32_e32 v214, v49, v49
	v_pk_add_f32 v[218:219], v[218:219], v[220:221]
	v_pk_add_f32 v[214:215], v[216:217], v[214:215]
	v_pk_mul_f32 v[216:217], v[44:45], v[44:45]
	v_pk_add_f32 v[214:215], v[218:219], v[214:215]
	s_waitcnt lgkmcnt(0)
	v_add_f32_e32 v0, v0, v222
	v_pk_add_f32 v[214:215], v[214:215], v[214:215] op_sel_hi:[0,1]
	ds_swizzle_b32 v214, v0 offset:swizzle(SWAP,8)
	v_pk_mul_f32 v[218:219], v[42:43], v[42:43]
	s_waitcnt lgkmcnt(0)
	v_add_f32_e32 v214, v0, v214
	ds_swizzle_b32 v222, v214 offset:swizzle(SWAP,16)
	v_pk_mov_b32 v[220:221], v[218:219], v[216:217] op_sel:[1,0]
	v_mov_b32_e32 v219, v217
	v_pk_add_f32 v[216:217], v[220:221], v[218:219]
	v_mul_f32_e32 v0, v38, v38
	v_pk_add_f32 v[216:217], v[216:217], v[216:217] op_sel_hi:[0,1]
	s_waitcnt lgkmcnt(0)
	v_add_f32_e32 v214, v214, v222
	ds_bpermute_b32 v216, v213, v214
	v_pk_fma_f32 v[218:219], v[38:39], v[38:39], v[0:1] op_sel_hi:[1,1,0]
	v_mul_f32_e32 v0, v40, v40
	v_pk_fma_f32 v[220:221], v[40:41], v[40:41], v[0:1] op_sel_hi:[1,1,0]
	v_mul_f32_e32 v218, v34, v34
	s_waitcnt lgkmcnt(0)
; __device__ __forceinline__ unsigned cvt_pk_bf16(float lo, float hi) { unsigned r; asm volatile("v_cvt_pk_bf16_f32 %0, %1, %2" : "=v"(r) : "v"(lo), "v"(hi)); return r; }
; template <int M> __device__ __forceinline__ float swz_xor(float v) { return __builtin_bit_cast(float, __builtin_amdgcn_ds_swizzle(__builtin_bit_cast(int, v), (M << 10) | 0x1F)); }
; __device__ __forceinline__ float wave_sum(float v) {
;     v += swz_xor<1>(v); v += swz_xor<2>(v); v += swz_xor<4>(v); v += swz_xor<8>(v); v += swz_xor<16>(v);
;     return v + __shfl_xor(v, 32);
; }
; __device__ __forceinline__ void norm_rows(const float* x, bf16_t* H, const float* g, const float* modl, int sh_off, int sc_off, int gw, int NGW, int lane, bool stream) {
;     ...
;             for (int q = 0; q < 4; ++q) { const float r = 1.0f / sqrtf(wave_sum(s[q]) * (1.0f / DM) + EPS);
;                 u32x2* o = (u32x2*)(H + (size_t)(rbase + k + q) * DM) + lane;
; #pragma unroll
;                 for (int j = 0; j < 8; ++j) { const f32x4 a = (v[q][j] * r) * gp[j] + sp[j]; u32x2 w; w.x = cvt_pk_bf16(a[0], a[1]); w.y = cvt_pk_bf16(a[2], a[3]); o[64 * j] = w; } }
	v_add_f32_e32 v0, v214, v216
	v_fmamk_f32 v0, v0, 0x3a000000, v203
	v_mul_f32_e32 v214, 0x4f800000, v0
	v_cmp_gt_f32_e32 vcc, s91, v0
	v_mul_f32_e32 v220, v35, v35
	v_pk_add_f32 v[218:219], v[218:219], v[220:221]
	v_cndmask_b32_e32 v0, v0, v214, vcc
	v_sqrt_f32_e32 v222, v0
	v_mul_f32_e32 v216, v36, v36
	v_mul_f32_e32 v214, v37, v37
	v_pk_add_f32 v[214:215], v[216:217], v[214:215]
	v_add_u32_e32 v220, -1, v222
	v_fma_f32 v221, -v220, v222, v0
	v_cmp_ge_f32_e64 s[0:1], 0, v221
	v_add_u32_e32 v221, 1, v222
	v_pk_add_f32 v[214:215], v[218:219], v[214:215]
	v_cndmask_b32_e64 v220, v222, v220, s[0:1]
	v_fma_f32 v222, -v221, v222, v0
	v_cmp_lt_f32_e64 s[0:1], 0, v222
	s_nop 1
	v_cndmask_b32_e64 v220, v220, v221, s[0:1]
	v_mul_f32_e32 v221, 0x37800000, v220
	v_cndmask_b32_e32 v220, v220, v221, vcc
	v_cmp_class_f32_e32 vcc, v0, v204
	s_nop 1
	v_cndmask_b32_e32 v220, v220, v0, vcc
	v_div_scale_f32 v221, s[0:1], v220, v220, 1.0
	v_rcp_f32_e32 v222, v221
	v_add_f32_e32 v0, v214, v215
	v_readlane_b32 s0, v251, 23
	v_readlane_b32 s1, v251, 24
	v_fma_f32 v214, -v221, v222, 1.0
	v_fmac_f32_e32 v222, v214, v222
	v_div_scale_f32 v214, vcc, 1.0, v220, 1.0
	v_mul_f32_e32 v215, v214, v222
	v_fma_f32 v216, -v221, v215, v214
	v_fmac_f32_e32 v215, v216, v222
	v_fma_f32 v214, -v221, v215, v214
	v_div_fmas_f32 v214, v214, v222, v215
	v_div_fixup_f32 v214, v214, v220, 1.0
	v_pk_mul_f32 v[154:155], v[154:155], v[214:215] op_sel_hi:[1,0]
	v_pk_mul_f32 v[150:151], v[150:151], v[214:215] op_sel_hi:[1,0]
	v_lshl_add_u64 v[216:217], v[198:199], 0, s[0:1]
	v_pk_mul_f32 v[156:157], v[156:157], v[214:215] op_sel_hi:[1,0]
	v_pk_fma_f32 v[154:155], v[196:197], v[154:155], v[30:31]
	v_pk_fma_f32 v[150:151], v[192:193], v[150:151], v[26:27]
	v_pk_fma_f32 v[156:157], v[194:195], v[156:157], v[32:33]
	v_cvt_pk_bf16_f32 v154, v154, v155
	v_pk_mul_f32 v[152:153], v[152:153], v[214:215] op_sel_hi:[1,0]
	v_cvt_pk_bf16_f32 v155, v156, v157
	global_store_dwordx2 v[216:217], v[154:155], off
	v_cvt_pk_bf16_f32 v150, v150, v151
	v_pk_mul_f32 v[146:147], v[146:147], v[214:215] op_sel_hi:[1,0]
	v_pk_fma_f32 v[152:153], v[190:191], v[152:153], v[28:29]
	v_pk_mul_f32 v[148:149], v[148:149], v[214:215] op_sel_hi:[1,0]
	v_cvt_pk_bf16_f32 v151, v152, v153
	global_store_dwordx2 v[216:217], v[150:151], off offset:512
	v_pk_fma_f32 v[146:147], v[188:189], v[146:147], v[22:23]
	ds_swizzle_b32 v150, v223 offset:swizzle(SWAP,1)
	v_pk_fma_f32 v[148:149], v[186:187], v[148:149], v[24:25]
	v_cvt_pk_bf16_f32 v146, v146, v147
	v_pk_mul_f32 v[130:131], v[130:131], v[214:215] op_sel_hi:[1,0]
	v_cvt_pk_bf16_f32 v147, v148, v149
	global_store_dwordx2 v[216:217], v[146:147], off offset:1024
	v_pk_mul_f32 v[146:147], v[158:159], v[214:215] op_sel_hi:[1,0]
	v_pk_mul_f32 v[148:149], v[160:161], v[214:215] op_sel_hi:[1,0]
	v_pk_fma_f32 v[146:147], v[184:185], v[146:147], v[18:19]
	v_pk_fma_f32 v[148:149], v[182:183], v[148:149], v[20:21]
	v_cvt_pk_bf16_f32 v146, v146, v147
	v_pk_mul_f32 v[132:133], v[132:133], v[214:215] op_sel_hi:[1,0]
	v_cvt_pk_bf16_f32 v147, v148, v149
	global_store_dwordx2 v[216:217], v[146:147], off offset:1536
	s_waitcnt lgkmcnt(0)
	v_add_f32_e32 v146, v223, v150
	ds_swizzle_b32 v147, v146 offset:swizzle(SWAP,2)
	v_pk_fma_f32 v[130:131], v[176:177], v[130:131], v[14:15]
	v_pk_fma_f32 v[132:133], v[174:175], v[132:133], v[16:17]
	v_cvt_pk_bf16_f32 v130, v130, v131
	s_waitcnt lgkmcnt(0)
	v_add_f32_e32 v146, v146, v147
	ds_swizzle_b32 v147, v146 offset:swizzle(SWAP,4)
	v_cvt_pk_bf16_f32 v131, v132, v133
	global_store_dwordx2 v[216:217], v[130:131], off offset:2048
	v_pk_mul_f32 v[130:131], v[142:143], v[214:215] op_sel_hi:[1,0]
	v_pk_mul_f32 v[132:133], v[144:145], v[214:215] op_sel_hi:[1,0]
	s_waitcnt lgkmcnt(0)
	v_add_f32_e32 v142, v146, v147
	ds_swizzle_b32 v143, v142 offset:swizzle(SWAP,8)
	v_pk_fma_f32 v[130:131], v[172:173], v[130:131], v[10:11]
	v_pk_fma_f32 v[132:133], v[170:171], v[132:133], v[12:13]
	v_cvt_pk_bf16_f32 v130, v130, v131
	s_waitcnt lgkmcnt(0)
	v_add_f32_e32 v142, v142, v143
	ds_swizzle_b32 v143, v142 offset:swizzle(SWAP,16)
	v_cvt_pk_bf16_f32 v131, v132, v133
	global_store_dwordx2 v[216:217], v[130:131], off offset:2560
	v_pk_mul_f32 v[130:131], v[138:139], v[214:215] op_sel_hi:[1,0]
	v_pk_mul_f32 v[132:133], v[140:141], v[214:215] op_sel_hi:[1,0]
	s_waitcnt lgkmcnt(0)
	v_add_f32_e32 v138, v142, v143
	ds_bpermute_b32 v139, v213, v138
	v_pk_fma_f32 v[132:133], v[166:167], v[132:133], v[8:9]
	v_pk_fma_f32 v[130:131], v[168:169], v[130:131], v[6:7]
	s_nop 0
	v_cvt_pk_bf16_f32 v130, v130, v131
	v_cvt_pk_bf16_f32 v131, v132, v133
	s_waitcnt lgkmcnt(0)
; __device__ __forceinline__ unsigned cvt_pk_bf16(float lo, float hi) { unsigned r; asm volatile("v_cvt_pk_bf16_f32 %0, %1, %2" : "=v"(r) : "v"(lo), "v"(hi)); return r; }
; template <int M> __device__ __forceinline__ float swz_xor(float v) { return __builtin_bit_cast(float, __builtin_amdgcn_ds_swizzle(__builtin_bit_cast(int, v), (M << 10) | 0x1F)); }
; __device__ __forceinline__ float wave_sum(float v) {
;     v += swz_xor<1>(v); v += swz_xor<2>(v); v += swz_xor<4>(v); v += swz_xor<8>(v); v += swz_xor<16>(v);
;     return v + __shfl_xor(v, 32);
; }
; __device__ __forceinline__ void norm_rows(const float* x, bf16_t* H, const float* g, const float* modl, int sh_off, int sc_off, int gw, int NGW, int lane, bool stream) {
;     ...
;             for (int q = 0; q < 4; ++q) { const float r = 1.0f / sqrtf(wave_sum(s[q]) * (1.0f / DM) + EPS);
;                 u32x2* o = (u32x2*)(H + (size_t)(rbase + k + q) * DM) + lane;
; #pragma unroll
;                 for (int j = 0; j < 8; ++j) { const f32x4 a = (v[q][j] * r) * gp[j] + sp[j]; u32x2 w; w.x = cvt_pk_bf16(a[0], a[1]); w.y = cvt_pk_bf16(a[2], a[3]); o[64 * j] = w; } }
	v_add_f32_e32 v132, v138, v139
	v_fmamk_f32 v132, v132, 0x3a000000, v203
	v_mul_f32_e32 v133, 0x4f800000, v132
	v_cmp_gt_f32_e32 vcc, s91, v132
	global_store_dwordx2 v[216:217], v[130:131], off offset:3072
	v_pk_mul_f32 v[130:131], v[134:135], v[214:215] op_sel_hi:[1,0]
	v_cndmask_b32_e32 v134, v132, v133, vcc
	v_sqrt_f32_e32 v135, v134
	v_pk_mul_f32 v[132:133], v[136:137], v[214:215] op_sel_hi:[1,0]
	v_pk_fma_f32 v[130:131], v[164:165], v[130:131], v[2:3]
	v_pk_fma_f32 v[132:133], v[162:163], v[132:133], v[4:5]
	v_add_u32_e32 v136, -1, v135
	v_fma_f32 v137, -v136, v135, v134
	v_cmp_ge_f32_e64 s[0:1], 0, v137
	v_add_u32_e32 v137, 1, v135
	v_cvt_pk_bf16_f32 v130, v130, v131
	v_cvt_pk_bf16_f32 v131, v132, v133
	global_store_dwordx2 v[216:217], v[130:131], off offset:3584
	v_cndmask_b32_e64 v136, v135, v136, s[0:1]
	v_fma_f32 v135, -v137, v135, v134
	v_cmp_lt_f32_e64 s[0:1], 0, v135
	s_nop 1
	v_cndmask_b32_e64 v135, v136, v137, s[0:1]
	v_mul_f32_e32 v136, 0x37800000, v135
	v_cndmask_b32_e32 v135, v135, v136, vcc
	v_cmp_class_f32_e32 vcc, v134, v204
	s_nop 1
	v_cndmask_b32_e32 v134, v135, v134, vcc
	v_div_scale_f32 v135, s[0:1], v134, v134, 1.0
	v_rcp_f32_e32 v136, v135
	v_readlane_b32 s0, v251, 25
	v_readlane_b32 s1, v251, 26
	v_fma_f32 v130, -v135, v136, 1.0
	v_fmac_f32_e32 v136, v130, v136
	v_div_scale_f32 v130, vcc, 1.0, v134, 1.0
	v_mul_f32_e32 v131, v130, v136
	v_fma_f32 v132, -v135, v131, v130
	v_fmac_f32_e32 v131, v132, v136
	v_fma_f32 v130, -v135, v131, v130
	v_div_fmas_f32 v130, v130, v136, v131
	v_div_fixup_f32 v130, v130, v134, 1.0
	v_pk_mul_f32 v[126:127], v[126:127], v[130:131] op_sel_hi:[1,0]
	v_pk_mul_f32 v[122:123], v[122:123], v[130:131] op_sel_hi:[1,0]
	v_pk_mul_f32 v[118:119], v[118:119], v[130:131] op_sel_hi:[1,0]
	v_lshl_add_u64 v[132:133], v[198:199], 0, s[0:1]
	v_pk_mul_f32 v[128:129], v[128:129], v[130:131] op_sel_hi:[1,0]
	v_pk_fma_f32 v[126:127], v[196:197], v[126:127], v[30:31]
	v_pk_mul_f32 v[124:125], v[124:125], v[130:131] op_sel_hi:[1,0]
	v_pk_fma_f32 v[122:123], v[192:193], v[122:123], v[26:27]
	v_pk_fma_f32 v[118:119], v[188:189], v[118:119], v[22:23]
	v_pk_fma_f32 v[128:129], v[194:195], v[128:129], v[32:33]
	v_cvt_pk_bf16_f32 v126, v126, v127
	v_pk_fma_f32 v[124:125], v[190:191], v[124:125], v[28:29]
	v_cvt_pk_bf16_f32 v127, v128, v129
	global_store_dwordx2 v[132:133], v[126:127], off
	v_cvt_pk_bf16_f32 v122, v122, v123
	v_cvt_pk_bf16_f32 v123, v124, v125
	global_store_dwordx2 v[132:133], v[122:123], off offset:512
	v_pk_mul_f32 v[120:121], v[120:121], v[130:131] op_sel_hi:[1,0]
	v_cvt_pk_bf16_f32 v118, v118, v119
	v_pk_mul_f32 v[114:115], v[114:115], v[130:131] op_sel_hi:[1,0]
	v_pk_fma_f32 v[120:121], v[186:187], v[120:121], v[24:25]
	v_pk_fma_f32 v[114:115], v[184:185], v[114:115], v[18:19]
	v_cvt_pk_bf16_f32 v119, v120, v121
	global_store_dwordx2 v[132:133], v[118:119], off offset:1024
	ds_swizzle_b32 v118, v224 offset:swizzle(SWAP,1)
	v_pk_mul_f32 v[116:117], v[116:117], v[130:131] op_sel_hi:[1,0]
	v_cvt_pk_bf16_f32 v114, v114, v115
	v_pk_mul_f32 v[110:111], v[110:111], v[130:131] op_sel_hi:[1,0]
	v_pk_fma_f32 v[116:117], v[182:183], v[116:117], v[20:21]
	v_pk_mul_f32 v[112:113], v[112:113], v[130:131] op_sel_hi:[1,0]
	v_cvt_pk_bf16_f32 v115, v116, v117
	global_store_dwordx2 v[132:133], v[114:115], off offset:1536
	s_waitcnt lgkmcnt(0)
	v_add_f32_e32 v114, v224, v118
	ds_swizzle_b32 v115, v114 offset:swizzle(SWAP,2)
	v_pk_fma_f32 v[112:113], v[174:175], v[112:113], v[16:17]
	v_pk_fma_f32 v[110:111], v[176:177], v[110:111], v[14:15]
	v_pk_mul_f32 v[106:107], v[106:107], v[130:131] op_sel_hi:[1,0]
	v_cvt_pk_bf16_f32 v110, v110, v111
	v_cvt_pk_bf16_f32 v111, v112, v113
	s_waitcnt lgkmcnt(0)
	v_add_f32_e32 v112, v114, v115
	ds_swizzle_b32 v113, v112 offset:swizzle(SWAP,4)
	global_store_dwordx2 v[132:133], v[110:111], off offset:2048
	v_pk_fma_f32 v[106:107], v[172:173], v[106:107], v[10:11]
	v_pk_mul_f32 v[108:109], v[108:109], v[130:131] op_sel_hi:[1,0]
	v_cvt_pk_bf16_f32 v106, v106, v107
	s_waitcnt lgkmcnt(0)
	v_add_f32_e32 v110, v112, v113
	ds_swizzle_b32 v111, v110 offset:swizzle(SWAP,8)
	v_pk_fma_f32 v[108:109], v[170:171], v[108:109], v[12:13]
	v_pk_mul_f32 v[102:103], v[102:103], v[130:131] op_sel_hi:[1,0]
	v_cvt_pk_bf16_f32 v107, v108, v109
	global_store_dwordx2 v[132:133], v[106:107], off offset:2560
	s_waitcnt lgkmcnt(0)
	v_add_f32_e32 v106, v110, v111
	ds_swizzle_b32 v107, v106 offset:swizzle(SWAP,16)
	v_pk_fma_f32 v[102:103], v[168:169], v[102:103], v[6:7]
	v_pk_mul_f32 v[104:105], v[104:105], v[130:131] op_sel_hi:[1,0]
	v_cvt_pk_bf16_f32 v102, v102, v103
	v_pk_mul_f32 v[98:99], v[98:99], v[130:131] op_sel_hi:[1,0]
	s_waitcnt lgkmcnt(0)
	v_add_f32_e32 v106, v106, v107
	ds_bpermute_b32 v107, v213, v106
	v_pk_fma_f32 v[104:105], v[166:167], v[104:105], v[8:9]
	v_pk_fma_f32 v[98:99], v[164:165], v[98:99], v[2:3]
	v_cvt_pk_bf16_f32 v103, v104, v105
	global_store_dwordx2 v[132:133], v[102:103], off offset:3072
	s_waitcnt lgkmcnt(0)
; __device__ __forceinline__ unsigned cvt_pk_bf16(float lo, float hi) { unsigned r; asm volatile("v_cvt_pk_bf16_f32 %0, %1, %2" : "=v"(r) : "v"(lo), "v"(hi)); return r; }
; template <int M> __device__ __forceinline__ float swz_xor(float v) { return __builtin_bit_cast(float, __builtin_amdgcn_ds_swizzle(__builtin_bit_cast(int, v), (M << 10) | 0x1F)); }
; __device__ __forceinline__ float wave_sum(float v) {
;     v += swz_xor<1>(v); v += swz_xor<2>(v); v += swz_xor<4>(v); v += swz_xor<8>(v); v += swz_xor<16>(v);
;     return v + __shfl_xor(v, 32);
; }
; __device__ __forceinline__ void norm_rows(const float* x, bf16_t* H, const float* g, const float* modl, int sh_off, int sc_off, int gw, int NGW, int lane, bool stream) {
;     ...
;             for (int q = 0; q < 4; ++q) { const float r = 1.0f / sqrtf(wave_sum(s[q]) * (1.0f / DM) + EPS);
;                 u32x2* o = (u32x2*)(H + (size_t)(rbase + k + q) * DM) + lane;
; #pragma unroll
;                 for (int j = 0; j < 8; ++j) { const f32x4 a = (v[q][j] * r) * gp[j] + sp[j]; u32x2 w; w.x = cvt_pk_bf16(a[0], a[1]); w.y = cvt_pk_bf16(a[2], a[3]); o[64 * j] = w; } }
	v_add_f32_e32 v102, v106, v107
	v_fmamk_f32 v102, v102, 0x3a000000, v203
	v_mul_f32_e32 v103, 0x4f800000, v102
	v_cmp_gt_f32_e32 vcc, s91, v102
	v_pk_mul_f32 v[100:101], v[100:101], v[130:131] op_sel_hi:[1,0]
	v_cvt_pk_bf16_f32 v98, v98, v99
	s_nop 0
	v_cndmask_b32_e32 v102, v102, v103, vcc
	v_sqrt_f32_e32 v103, v102
	v_pk_fma_f32 v[100:101], v[162:163], v[100:101], v[4:5]
	v_add_u32_e32 v104, -1, v103
	v_fma_f32 v105, -v104, v103, v102
	v_cmp_ge_f32_e64 s[0:1], 0, v105
	v_add_u32_e32 v105, 1, v103
	v_cvt_pk_bf16_f32 v99, v100, v101
	global_store_dwordx2 v[132:133], v[98:99], off offset:3584
	v_cndmask_b32_e64 v104, v103, v104, s[0:1]
	v_fma_f32 v103, -v105, v103, v102
	v_cmp_lt_f32_e64 s[0:1], 0, v103
	s_nop 1
	v_cndmask_b32_e64 v103, v104, v105, s[0:1]
	v_mul_f32_e32 v104, 0x37800000, v103
	v_cndmask_b32_e32 v103, v103, v104, vcc
	v_cmp_class_f32_e32 vcc, v102, v204
	s_nop 1
	v_cndmask_b32_e32 v102, v103, v102, vcc
	v_div_scale_f32 v103, s[0:1], v102, v102, 1.0
	v_rcp_f32_e32 v104, v103
	v_readlane_b32 s0, v251, 27
	v_readlane_b32 s1, v251, 28
	v_fma_f32 v98, -v103, v104, 1.0
	v_fmac_f32_e32 v104, v98, v104
	v_div_scale_f32 v98, vcc, 1.0, v102, 1.0
	v_mul_f32_e32 v99, v98, v104
	v_fma_f32 v100, -v103, v99, v98
	v_fmac_f32_e32 v99, v100, v104
	v_fma_f32 v98, -v103, v99, v98
	v_div_fmas_f32 v98, v98, v104, v99
	v_div_fixup_f32 v98, v98, v102, 1.0
	v_pk_mul_f32 v[94:95], v[94:95], v[98:99] op_sel_hi:[1,0]
	v_pk_mul_f32 v[90:91], v[90:91], v[98:99] op_sel_hi:[1,0]
	v_pk_mul_f32 v[86:87], v[86:87], v[98:99] op_sel_hi:[1,0]
	v_lshl_add_u64 v[100:101], v[198:199], 0, s[0:1]
	v_pk_mul_f32 v[96:97], v[96:97], v[98:99] op_sel_hi:[1,0]
	v_pk_fma_f32 v[94:95], v[196:197], v[94:95], v[30:31]
	v_pk_mul_f32 v[92:93], v[92:93], v[98:99] op_sel_hi:[1,0]
	v_pk_fma_f32 v[90:91], v[192:193], v[90:91], v[26:27]
	v_pk_fma_f32 v[86:87], v[188:189], v[86:87], v[22:23]
	v_pk_fma_f32 v[96:97], v[194:195], v[96:97], v[32:33]
	v_cvt_pk_bf16_f32 v94, v94, v95
	v_pk_fma_f32 v[92:93], v[190:191], v[92:93], v[28:29]
	v_cvt_pk_bf16_f32 v95, v96, v97
	global_store_dwordx2 v[100:101], v[94:95], off
	v_cvt_pk_bf16_f32 v90, v90, v91
	v_cvt_pk_bf16_f32 v91, v92, v93
	global_store_dwordx2 v[100:101], v[90:91], off offset:512
	v_pk_mul_f32 v[88:89], v[88:89], v[98:99] op_sel_hi:[1,0]
	v_cvt_pk_bf16_f32 v86, v86, v87
	v_pk_mul_f32 v[82:83], v[82:83], v[98:99] op_sel_hi:[1,0]
	v_pk_fma_f32 v[88:89], v[186:187], v[88:89], v[24:25]
	v_pk_fma_f32 v[82:83], v[184:185], v[82:83], v[18:19]
	v_cvt_pk_bf16_f32 v87, v88, v89
	global_store_dwordx2 v[100:101], v[86:87], off offset:1024
	ds_swizzle_b32 v86, v0 offset:swizzle(SWAP,1)
	v_pk_mul_f32 v[84:85], v[84:85], v[98:99] op_sel_hi:[1,0]
	v_cvt_pk_bf16_f32 v82, v82, v83
	v_pk_mul_f32 v[78:79], v[78:79], v[98:99] op_sel_hi:[1,0]
	v_pk_fma_f32 v[84:85], v[182:183], v[84:85], v[20:21]
	s_waitcnt lgkmcnt(0)
	v_add_f32_e32 v0, v0, v86
	v_cvt_pk_bf16_f32 v83, v84, v85
	global_store_dwordx2 v[100:101], v[82:83], off offset:1536
	ds_swizzle_b32 v82, v0 offset:swizzle(SWAP,2)
	v_pk_mul_f32 v[80:81], v[80:81], v[98:99] op_sel_hi:[1,0]
	v_pk_fma_f32 v[78:79], v[176:177], v[78:79], v[14:15]
	v_pk_fma_f32 v[80:81], v[174:175], v[80:81], v[16:17]
	v_cvt_pk_bf16_f32 v78, v78, v79
	s_waitcnt lgkmcnt(0)
	v_add_f32_e32 v0, v0, v82
	v_cvt_pk_bf16_f32 v79, v80, v81
	ds_swizzle_b32 v80, v0 offset:swizzle(SWAP,4)
	global_store_dwordx2 v[100:101], v[78:79], off offset:2048
	v_pk_mul_f32 v[74:75], v[74:75], v[98:99] op_sel_hi:[1,0]
	v_pk_mul_f32 v[76:77], v[76:77], v[98:99] op_sel_hi:[1,0]
	v_pk_fma_f32 v[74:75], v[172:173], v[74:75], v[10:11]
	s_waitcnt lgkmcnt(0)
	v_add_f32_e32 v0, v0, v80
	ds_swizzle_b32 v78, v0 offset:swizzle(SWAP,8)
	v_cvt_pk_bf16_f32 v74, v74, v75
	v_pk_fma_f32 v[76:77], v[170:171], v[76:77], v[12:13]
	v_pk_mul_f32 v[70:71], v[70:71], v[98:99] op_sel_hi:[1,0]
	v_cvt_pk_bf16_f32 v75, v76, v77
	s_waitcnt lgkmcnt(0)
	v_add_f32_e32 v0, v0, v78
	global_store_dwordx2 v[100:101], v[74:75], off offset:2560
	ds_swizzle_b32 v74, v0 offset:swizzle(SWAP,16)
	v_pk_fma_f32 v[70:71], v[168:169], v[70:71], v[6:7]
	v_pk_mul_f32 v[72:73], v[72:73], v[98:99] op_sel_hi:[1,0]
	v_cvt_pk_bf16_f32 v70, v70, v71
	v_pk_mul_f32 v[66:67], v[66:67], v[98:99] op_sel_hi:[1,0]
	s_waitcnt lgkmcnt(0)
	v_add_f32_e32 v0, v0, v74
	ds_bpermute_b32 v74, v213, v0
	v_pk_fma_f32 v[72:73], v[166:167], v[72:73], v[8:9]
	v_pk_fma_f32 v[66:67], v[164:165], v[66:67], v[2:3]
	v_cvt_pk_bf16_f32 v71, v72, v73
	global_store_dwordx2 v[100:101], v[70:71], off offset:3072
	s_waitcnt lgkmcnt(0)
; __device__ __forceinline__ unsigned cvt_pk_bf16(float lo, float hi) { unsigned r; asm volatile("v_cvt_pk_bf16_f32 %0, %1, %2" : "=v"(r) : "v"(lo), "v"(hi)); return r; }
; __device__ __forceinline__ void norm_rows(const float* x, bf16_t* H, const float* g, const float* modl, int sh_off, int sc_off, int gw, int NGW, int lane, bool stream) {
;     ...
;         for (int k = 0; k < 8; k += 4) {
;             const f32x4* xp = (const f32x4*)(x + (size_t)(rbase + k) * DM) + lane;
;             f32x4 v[4][8]; float s[4] = {0.f, 0.f, 0.f, 0.f};
;             if (stream) { _Pragma("unroll") for (int q = 0; q < 4; ++q) _Pragma("unroll") for (int j = 0; j < 8; ++j) v[q][j] = __builtin_nontemporal_load(xp + q * (DM / 4) + 64 * j); }
;     ...
;             for (int q = 0; q < 4; ++q) { const float r = 1.0f / sqrtf(wave_sum(s[q]) * (1.0f / DM) + EPS);
;                 u32x2* o = (u32x2*)(H + (size_t)(rbase + k + q) * DM) + lane;
; #pragma unroll
;                 for (int j = 0; j < 8; ++j) { const f32x4 a = (v[q][j] * r) * gp[j] + sp[j]; u32x2 w; w.x = cvt_pk_bf16(a[0], a[1]); w.y = cvt_pk_bf16(a[2], a[3]); o[64 * j] = w; } }
	v_add_f32_e32 v0, v0, v74
	v_fmamk_f32 v0, v0, 0x3a000000, v203
	v_mul_f32_e32 v70, 0x4f800000, v0
	v_cmp_gt_f32_e32 vcc, s91, v0
	v_pk_mul_f32 v[68:69], v[68:69], v[98:99] op_sel_hi:[1,0]
	v_cvt_pk_bf16_f32 v66, v66, v67
	s_nop 0
	v_cndmask_b32_e32 v0, v0, v70, vcc
	v_sqrt_f32_e32 v70, v0
	v_pk_fma_f32 v[68:69], v[162:163], v[68:69], v[4:5]
	v_add_u32_e32 v71, -1, v70
	v_fma_f32 v72, -v71, v70, v0
	v_cmp_ge_f32_e64 s[0:1], 0, v72
	v_add_u32_e32 v72, 1, v70
	v_cvt_pk_bf16_f32 v67, v68, v69
	global_store_dwordx2 v[100:101], v[66:67], off offset:3584
	v_cndmask_b32_e64 v71, v70, v71, s[0:1]
	v_fma_f32 v70, -v72, v70, v0
	v_cmp_lt_f32_e64 s[0:1], 0, v70
	s_nop 1
	v_cndmask_b32_e64 v70, v71, v72, s[0:1]
	v_mul_f32_e32 v71, 0x37800000, v70
	v_cndmask_b32_e32 v70, v70, v71, vcc
	v_cmp_class_f32_e32 vcc, v0, v204
	s_nop 1
	v_cndmask_b32_e32 v0, v70, v0, vcc
	v_div_scale_f32 v70, s[0:1], v0, v0, 1.0
	v_rcp_f32_e32 v71, v70
	v_readlane_b32 s0, v251, 29
	v_readlane_b32 s1, v251, 30
	v_fma_f32 v66, -v70, v71, 1.0
	v_fmac_f32_e32 v71, v66, v71
	v_div_scale_f32 v66, vcc, 1.0, v0, 1.0
	v_mul_f32_e32 v67, v66, v71
	v_fma_f32 v68, -v70, v67, v66
	v_fmac_f32_e32 v67, v68, v71
	v_fma_f32 v66, -v70, v67, v66
	v_div_fmas_f32 v66, v66, v71, v67
	v_div_fixup_f32 v0, v66, v0, 1.0
	v_lshl_add_u64 v[66:67], v[198:199], 0, s[0:1]
	v_pk_mul_f32 v[62:63], v[62:63], v[0:1] op_sel_hi:[1,0]
	v_pk_mul_f32 v[58:59], v[58:59], v[0:1] op_sel_hi:[1,0]
	v_pk_mul_f32 v[54:55], v[54:55], v[0:1] op_sel_hi:[1,0]
	v_pk_mul_f32 v[50:51], v[50:51], v[0:1] op_sel_hi:[1,0]
	v_pk_mul_f32 v[46:47], v[46:47], v[0:1] op_sel_hi:[1,0]
	v_pk_mul_f32 v[42:43], v[42:43], v[0:1] op_sel_hi:[1,0]
	v_pk_mul_f32 v[38:39], v[38:39], v[0:1] op_sel_hi:[1,0]
	v_pk_mul_f32 v[34:35], v[34:35], v[0:1] op_sel_hi:[1,0]
	v_readlane_b32 s0, v251, 31
	v_pk_mul_f32 v[64:65], v[64:65], v[0:1] op_sel_hi:[1,0]
	v_pk_fma_f32 v[62:63], v[196:197], v[62:63], v[30:31]
	v_pk_mul_f32 v[60:61], v[60:61], v[0:1] op_sel_hi:[1,0]
	v_pk_fma_f32 v[58:59], v[192:193], v[58:59], v[26:27]
	v_pk_mul_f32 v[56:57], v[56:57], v[0:1] op_sel_hi:[1,0]
	v_pk_fma_f32 v[54:55], v[188:189], v[54:55], v[22:23]
	v_pk_mul_f32 v[52:53], v[52:53], v[0:1] op_sel_hi:[1,0]
	v_pk_fma_f32 v[50:51], v[184:185], v[50:51], v[18:19]
	v_pk_mul_f32 v[48:49], v[48:49], v[0:1] op_sel_hi:[1,0]
	v_pk_fma_f32 v[46:47], v[176:177], v[46:47], v[14:15]
	v_pk_mul_f32 v[44:45], v[44:45], v[0:1] op_sel_hi:[1,0]
	v_pk_fma_f32 v[42:43], v[172:173], v[42:43], v[10:11]
	v_pk_mul_f32 v[40:41], v[40:41], v[0:1] op_sel_hi:[1,0]
	v_pk_fma_f32 v[38:39], v[168:169], v[38:39], v[6:7]
	v_pk_mul_f32 v[36:37], v[36:37], v[0:1] op_sel_hi:[1,0]
	v_pk_fma_f32 v[34:35], v[164:165], v[34:35], v[2:3]
	v_readlane_b32 s1, v251, 32
	v_pk_fma_f32 v[64:65], v[194:195], v[64:65], v[32:33]
	v_cvt_pk_bf16_f32 v62, v62, v63
	v_pk_fma_f32 v[60:61], v[190:191], v[60:61], v[28:29]
	v_cvt_pk_bf16_f32 v63, v64, v65
	global_store_dwordx2 v[66:67], v[62:63], off
	v_cvt_pk_bf16_f32 v58, v58, v59
	v_cvt_pk_bf16_f32 v59, v60, v61
	global_store_dwordx2 v[66:67], v[58:59], off offset:512
	v_pk_fma_f32 v[56:57], v[186:187], v[56:57], v[24:25]
	v_cvt_pk_bf16_f32 v54, v54, v55
	v_pk_fma_f32 v[52:53], v[182:183], v[52:53], v[20:21]
	v_cvt_pk_bf16_f32 v55, v56, v57
	global_store_dwordx2 v[66:67], v[54:55], off offset:1024
	v_cvt_pk_bf16_f32 v50, v50, v51
	v_cvt_pk_bf16_f32 v51, v52, v53
	global_store_dwordx2 v[66:67], v[50:51], off offset:1536
	v_pk_fma_f32 v[48:49], v[174:175], v[48:49], v[16:17]
	v_cvt_pk_bf16_f32 v46, v46, v47
	v_pk_fma_f32 v[44:45], v[170:171], v[44:45], v[12:13]
	v_cvt_pk_bf16_f32 v47, v48, v49
	global_store_dwordx2 v[66:67], v[46:47], off offset:2048
	v_cvt_pk_bf16_f32 v42, v42, v43
	v_cvt_pk_bf16_f32 v43, v44, v45
	global_store_dwordx2 v[66:67], v[42:43], off offset:2560
	v_pk_fma_f32 v[40:41], v[166:167], v[40:41], v[8:9]
	v_cvt_pk_bf16_f32 v38, v38, v39
	v_pk_fma_f32 v[36:37], v[162:163], v[36:37], v[4:5]
	v_cvt_pk_bf16_f32 v39, v40, v41
	global_store_dwordx2 v[66:67], v[38:39], off offset:3072
	v_cvt_pk_bf16_f32 v34, v34, v35
	v_cvt_pk_bf16_f32 v35, v36, v37
	global_store_dwordx2 v[66:67], v[34:35], off offset:3584
	v_lshl_add_u64 v[98:99], v[200:201], 0, s[0:1]
	global_load_dwordx4 v[158:161], v[98:99], off nt
	global_load_dwordx4 v[154:157], v[98:99], off offset:1024 nt
	global_load_dwordx4 v[150:153], v[98:99], off offset:2048 nt
	v_add_co_u32_e32 v50, vcc, s79, v98
	s_waitcnt vmcnt(2)
	v_mov_b32_e32 v214, v159
	v_addc_co_u32_e32 v51, vcc, 0, v99, vcc
	global_load_dwordx4 v[142:145], v[50:51], off nt
	global_load_dwordx4 v[146:149], v[98:99], off offset:3072 nt
	v_add_co_u32_e32 v46, vcc, s6, v98
	s_waitcnt vmcnt(3)
; __device__ __forceinline__ void norm_rows(const float* x, bf16_t* H, const float* g, const float* modl, int sh_off, int sc_off, int gw, int NGW, int lane, bool stream) {
;     ...
;         for (int k = 0; k < 8; k += 4) {
;             const f32x4* xp = (const f32x4*)(x + (size_t)(rbase + k) * DM) + lane;
;             f32x4 v[4][8]; float s[4] = {0.f, 0.f, 0.f, 0.f};
;             if (stream) { _Pragma("unroll") for (int q = 0; q < 4; ++q) _Pragma("unroll") for (int j = 0; j < 8; ++j) v[q][j] = __builtin_nontemporal_load(xp + q * (DM / 4) + 64 * j); }
;             else { _Pragma("unroll") for (int q = 0; q < 4; ++q) _Pragma("unroll") for (int j = 0; j < 8; ++j) v[q][j] = xp[q * (DM / 4) + 64 * j]; }
; #pragma unroll
;             for (int q = 0; q < 4; ++q)
; #pragma unroll
;                 for (int j = 0; j < 8; ++j) s[q] += (v[q][j][0] * v[q][j][0] + v[q][j][1] * v[q][j][1]) + (v[q][j][2] * v[q][j][2] + v[q][j][3] * v[q][j][3]);
	v_mov_b32_e32 v215, v155
	v_addc_co_u32_e32 v47, vcc, 0, v99, vcc
	global_load_dwordx4 v[34:37], v[46:47], off offset:3072 nt
	global_load_dwordx4 v[38:41], v[46:47], off offset:2048 nt
	global_load_dwordx4 v[138:141], v[50:51], off offset:1024 nt
	global_load_dwordx4 v[42:45], v[46:47], off offset:1024 nt
	s_nop 0
	global_load_dwordx4 v[46:49], v[46:47], off nt
	s_nop 0
	global_load_dwordx4 v[134:137], v[50:51], off offset:2048 nt
	global_load_dwordx4 v[130:133], v[50:51], off offset:3072 nt
	v_add_co_u32_e32 v62, vcc, s7, v98
	v_mov_b32_e32 v200, v158
	s_nop 0
	v_addc_co_u32_e32 v63, vcc, 0, v99, vcc
	v_add_co_u32_e32 v78, vcc, s8, v98
	global_load_dwordx4 v[50:53], v[62:63], off offset:3072 nt
	global_load_dwordx4 v[54:57], v[62:63], off offset:2048 nt
	global_load_dwordx4 v[58:61], v[62:63], off offset:1024 nt
	s_nop 0
	global_load_dwordx4 v[62:65], v[62:63], off nt
	v_addc_co_u32_e32 v79, vcc, 0, v99, vcc
	v_add_co_u32_e32 v100, vcc, s9, v98
	global_load_dwordx4 v[66:69], v[78:79], off offset:3072 nt
	global_load_dwordx4 v[70:73], v[78:79], off offset:2048 nt
	v_addc_co_u32_e32 v101, vcc, 0, v99, vcc
	global_load_dwordx4 v[122:125], v[100:101], off offset:1024 nt
	global_load_dwordx4 v[126:129], v[100:101], off nt
	global_load_dwordx4 v[74:77], v[78:79], off offset:1024 nt
	s_nop 0
	global_load_dwordx4 v[78:81], v[78:79], off nt
	v_add_co_u32_e32 v94, vcc, s4, v98
	v_mov_b32_e32 v201, v154
	s_nop 0
	v_addc_co_u32_e32 v95, vcc, 0, v99, vcc
	global_load_dwordx4 v[82:85], v[94:95], off offset:3072 nt
	global_load_dwordx4 v[86:89], v[94:95], off offset:2048 nt
	global_load_dwordx4 v[90:93], v[94:95], off offset:1024 nt
	s_nop 0
	global_load_dwordx4 v[94:97], v[94:95], off nt
	s_nop 0
	global_load_dwordx4 v[114:117], v[100:101], off offset:3072 nt
	global_load_dwordx4 v[118:121], v[100:101], off offset:2048 nt
	v_add_co_u32_e32 v110, vcc, s5, v98
	v_pk_mul_f32 v[214:215], v[214:215], v[214:215]
	s_nop 0
	v_addc_co_u32_e32 v111, vcc, 0, v99, vcc
	global_load_dwordx4 v[98:101], v[110:111], off offset:3072 nt
	global_load_dwordx4 v[102:105], v[110:111], off offset:2048 nt
	global_load_dwordx4 v[106:109], v[110:111], off offset:1024 nt
	s_nop 0
	global_load_dwordx4 v[110:113], v[110:111], off nt
	v_mov_b32_e32 v216, v161
	v_mov_b32_e32 v217, v157
	v_pk_fma_f32 v[200:201], v[200:201], v[200:201], v[214:215]
	v_mov_b32_e32 v214, v160
	v_mov_b32_e32 v215, v156
	v_pk_mul_f32 v[216:217], v[216:217], v[216:217]
	s_waitcnt vmcnt(28)
	v_mul_f32_e32 v0, v142, v142
	v_pk_fma_f32 v[214:215], v[214:215], v[214:215], v[216:217]
	v_pk_mul_f32 v[216:217], v[150:151], v[150:151]
	v_pk_add_f32 v[200:201], v[200:201], v[214:215]
	v_pk_mul_f32 v[214:215], v[152:153], v[152:153]
	v_pk_add_f32 v[200:201], v[200:201], v[200:201] op_sel:[0,1] op_sel_hi:[1,0]
	v_pk_mov_b32 v[218:219], v[216:217], v[214:215] op_sel:[1,0]
	v_mov_b32_e32 v217, v215
	v_pk_add_f32 v[214:215], v[218:219], v[216:217]
	v_mul_f32_e32 v216, v143, v143
	v_pk_add_f32 v[214:215], v[214:215], v[214:215] op_sel:[0,1] op_sel_hi:[1,0]
	v_mov_b32_e32 v201, v0
	v_mov_b32_e32 v215, v216
	s_waitcnt vmcnt(27)
	v_mul_f32_e32 v0, v147, v147
	v_mul_f32_e32 v217, v144, v144
	v_pk_add_f32 v[200:201], v[200:201], v[214:215]
	v_pk_fma_f32 v[214:215], v[146:147], v[146:147], v[0:1] op_sel_hi:[1,1,0]
	v_mul_f32_e32 v0, v149, v149
	v_mul_f32_e32 v218, v145, v145
	v_mov_b32_e32 v215, v217
	v_pk_fma_f32 v[216:217], v[148:149], v[148:149], v[0:1] op_sel_hi:[1,1,0]
	s_waitcnt vmcnt(20)
	v_mul_f32_e32 v0, v130, v130
	v_mov_b32_e32 v217, v218
	v_pk_add_f32 v[214:215], v[214:215], v[216:217]
	v_pk_mul_f32 v[216:217], v[138:139], v[138:139]
	v_pk_add_f32 v[200:201], v[200:201], v[214:215]
	v_pk_mul_f32 v[214:215], v[140:141], v[140:141]
	v_pk_add_f32 v[200:201], v[200:201], v[200:201] op_sel:[0,1] op_sel_hi:[1,0]
	v_pk_mov_b32 v[218:219], v[216:217], v[214:215] op_sel:[1,0]
	v_mov_b32_e32 v217, v215
	v_pk_add_f32 v[214:215], v[218:219], v[216:217]
	v_mul_f32_e32 v216, v131, v131
	v_pk_add_f32 v[214:215], v[214:215], v[214:215] op_sel:[0,1] op_sel_hi:[1,0]
	v_mov_b32_e32 v201, v0
	v_mov_b32_e32 v215, v216
	v_mul_f32_e32 v0, v135, v135
	v_mul_f32_e32 v217, v132, v132
	v_pk_add_f32 v[200:201], v[200:201], v[214:215]
	v_pk_fma_f32 v[214:215], v[134:135], v[134:135], v[0:1] op_sel_hi:[1,1,0]
	v_mul_f32_e32 v0, v137, v137
	v_mul_f32_e32 v218, v133, v133
	v_mov_b32_e32 v215, v217
	v_pk_fma_f32 v[216:217], v[136:137], v[136:137], v[0:1] op_sel_hi:[1,1,0]
	s_waitcnt vmcnt(5)
	v_mul_f32_e32 v0, v114, v114
	v_mov_b32_e32 v217, v218
	v_pk_add_f32 v[214:215], v[214:215], v[216:217]
	v_mov_b32_e32 v216, v125
	v_pk_add_f32 v[200:201], v[200:201], v[214:215]
	v_mov_b32_e32 v214, v123
	v_mov_b32_e32 v215, v127
	v_add_f32_e32 v220, v200, v201
	v_mov_b32_e32 v200, v122
	v_mov_b32_e32 v201, v126
	v_pk_mul_f32 v[214:215], v[214:215], v[214:215]
	v_mov_b32_e32 v217, v129
	v_pk_fma_f32 v[200:201], v[200:201], v[200:201], v[214:215]
	v_mov_b32_e32 v214, v124
	v_mov_b32_e32 v215, v128
	v_pk_mul_f32 v[216:217], v[216:217], v[216:217]
	s_nop 0
	v_pk_fma_f32 v[214:215], v[214:215], v[214:215], v[216:217]
	s_waitcnt vmcnt(4)
	v_pk_mul_f32 v[216:217], v[118:119], v[118:119]
	v_pk_add_f32 v[200:201], v[200:201], v[214:215]
	v_pk_mul_f32 v[214:215], v[120:121], v[120:121]
	v_pk_add_f32 v[200:201], v[200:201], v[200:201] op_sel_hi:[0,1]
	v_pk_mov_b32 v[218:219], v[216:217], v[214:215] op_sel:[1,0]
	v_mov_b32_e32 v217, v215
	v_pk_add_f32 v[214:215], v[218:219], v[216:217]
	v_pk_fma_f32 v[216:217], v[114:115], v[114:115], v[0:1] op_sel_hi:[1,1,0]
	v_mul_f32_e32 v0, v116, v116
	v_pk_add_f32 v[214:215], v[214:215], v[214:215] op_sel_hi:[0,1]
	v_pk_fma_f32 v[218:219], v[116:117], v[116:117], v[0:1] op_sel_hi:[1,1,0]
	s_waitcnt vmcnt(0)
; template <int M> __device__ __forceinline__ float swz_xor(float v) { return __builtin_bit_cast(float, __builtin_amdgcn_ds_swizzle(__builtin_bit_cast(int, v), (M << 10) | 0x1F)); }
; __device__ __forceinline__ float wave_sum(float v) {
;     v += swz_xor<1>(v); v += swz_xor<2>(v); v += swz_xor<4>(v); v += swz_xor<8>(v); v += swz_xor<16>(v);
;     return v + __shfl_xor(v, 32);
; }
; __device__ __forceinline__ void norm_rows(const float* x, bf16_t* H, const float* g, const float* modl, int sh_off, int sc_off, int gw, int NGW, int lane, bool stream) {
;     ...
; #pragma unroll
;             for (int q = 0; q < 4; ++q)
; #pragma unroll
;                 for (int j = 0; j < 8; ++j) s[q] += (v[q][j][0] * v[q][j][0] + v[q][j][1] * v[q][j][1]) + (v[q][j][2] * v[q][j][2] + v[q][j][3] * v[q][j][3]);
; #pragma unroll
;             for (int q = 0; q < 4; ++q) { const float r = 1.0f / sqrtf(wave_sum(s[q]) * (1.0f / DM) + EPS);
	v_mul_f32_e32 v216, v110, v110
	v_mul_f32_e32 v218, v111, v111
	v_mul_f32_e32 v214, v112, v112
	v_mul_f32_e32 v200, v113, v113
	v_pk_add_f32 v[216:217], v[216:217], v[218:219]
	v_pk_add_f32 v[200:201], v[214:215], v[200:201]
	v_pk_mul_f32 v[214:215], v[108:109], v[108:109]
	v_pk_add_f32 v[200:201], v[216:217], v[200:201]
	v_pk_mul_f32 v[216:217], v[106:107], v[106:107]
	v_mul_f32_e32 v0, v102, v102
	v_pk_mov_b32 v[218:219], v[216:217], v[214:215] op_sel:[1,0]
	v_mov_b32_e32 v217, v215
	v_pk_add_f32 v[214:215], v[218:219], v[216:217]
	v_pk_fma_f32 v[216:217], v[102:103], v[102:103], v[0:1] op_sel_hi:[1,1,0]
	v_mul_f32_e32 v0, v104, v104
	v_pk_add_f32 v[200:201], v[200:201], v[200:201] op_sel_hi:[0,1]
	v_pk_add_f32 v[214:215], v[214:215], v[214:215] op_sel_hi:[0,1]
	v_pk_fma_f32 v[218:219], v[104:105], v[104:105], v[0:1] op_sel_hi:[1,1,0]
	v_mul_f32_e32 v216, v98, v98
	v_mul_f32_e32 v218, v99, v99
	v_mul_f32_e32 v214, v100, v100
	v_mul_f32_e32 v200, v101, v101
	v_pk_add_f32 v[216:217], v[216:217], v[218:219]
	v_pk_add_f32 v[200:201], v[214:215], v[200:201]
	v_mov_b32_e32 v214, v91
	v_pk_add_f32 v[200:201], v[216:217], v[200:201]
	v_mov_b32_e32 v215, v95
	v_add_f32_e32 v221, v200, v201
	v_mov_b32_e32 v200, v90
	v_mov_b32_e32 v201, v94
	v_pk_mul_f32 v[214:215], v[214:215], v[214:215]
	v_mov_b32_e32 v216, v93
	v_mov_b32_e32 v217, v97
	v_pk_fma_f32 v[200:201], v[200:201], v[200:201], v[214:215]
	v_mov_b32_e32 v214, v92
	v_mov_b32_e32 v215, v96
	v_pk_mul_f32 v[216:217], v[216:217], v[216:217]
	v_mul_f32_e32 v0, v82, v82
	v_pk_fma_f32 v[214:215], v[214:215], v[214:215], v[216:217]
	v_pk_mul_f32 v[216:217], v[86:87], v[86:87]
	v_pk_add_f32 v[200:201], v[200:201], v[214:215]
	v_pk_mul_f32 v[214:215], v[88:89], v[88:89]
	v_pk_add_f32 v[200:201], v[200:201], v[200:201] op_sel_hi:[0,1]
	v_pk_mov_b32 v[218:219], v[216:217], v[214:215] op_sel:[1,0]
	v_mov_b32_e32 v217, v215
	v_pk_add_f32 v[214:215], v[218:219], v[216:217]
	v_pk_fma_f32 v[216:217], v[82:83], v[82:83], v[0:1] op_sel_hi:[1,1,0]
	v_mul_f32_e32 v0, v84, v84
	v_pk_add_f32 v[214:215], v[214:215], v[214:215] op_sel_hi:[0,1]
	v_pk_fma_f32 v[218:219], v[84:85], v[84:85], v[0:1] op_sel_hi:[1,1,0]
	v_mul_f32_e32 v216, v78, v78
	v_mul_f32_e32 v218, v79, v79
	v_mul_f32_e32 v214, v80, v80
	v_mul_f32_e32 v200, v81, v81
	v_pk_add_f32 v[216:217], v[216:217], v[218:219]
	v_pk_add_f32 v[200:201], v[214:215], v[200:201]
	v_pk_mul_f32 v[214:215], v[76:77], v[76:77]
	v_pk_add_f32 v[200:201], v[216:217], v[200:201]
	v_pk_mul_f32 v[216:217], v[74:75], v[74:75]
	v_mul_f32_e32 v0, v70, v70
	v_pk_mov_b32 v[218:219], v[216:217], v[214:215] op_sel:[1,0]
	v_mov_b32_e32 v217, v215
	v_pk_add_f32 v[214:215], v[218:219], v[216:217]
	v_pk_fma_f32 v[216:217], v[70:71], v[70:71], v[0:1] op_sel_hi:[1,1,0]
	v_mul_f32_e32 v0, v72, v72
	v_pk_add_f32 v[200:201], v[200:201], v[200:201] op_sel_hi:[0,1]
	v_pk_add_f32 v[214:215], v[214:215], v[214:215] op_sel_hi:[0,1]
	v_pk_fma_f32 v[218:219], v[72:73], v[72:73], v[0:1] op_sel_hi:[1,1,0]
	v_mul_f32_e32 v216, v66, v66
	v_mul_f32_e32 v218, v67, v67
	v_mul_f32_e32 v214, v68, v68
	v_mul_f32_e32 v200, v69, v69
	v_pk_add_f32 v[216:217], v[216:217], v[218:219]
	v_pk_add_f32 v[200:201], v[214:215], v[200:201]
	v_mov_b32_e32 v214, v59
	v_pk_add_f32 v[200:201], v[216:217], v[200:201]
	v_mov_b32_e32 v215, v63
	v_add_f32_e32 v222, v200, v201
	v_mov_b32_e32 v200, v58
	v_mov_b32_e32 v201, v62
	v_pk_mul_f32 v[214:215], v[214:215], v[214:215]
	v_mov_b32_e32 v216, v61
	v_mov_b32_e32 v217, v65
	v_pk_fma_f32 v[200:201], v[200:201], v[200:201], v[214:215]
	v_mov_b32_e32 v214, v60
	v_mov_b32_e32 v215, v64
	v_pk_mul_f32 v[216:217], v[216:217], v[216:217]
	v_mul_f32_e32 v0, v50, v50
	v_pk_fma_f32 v[214:215], v[214:215], v[214:215], v[216:217]
	v_pk_mul_f32 v[216:217], v[54:55], v[54:55]
	v_pk_add_f32 v[200:201], v[200:201], v[214:215]
	v_pk_mul_f32 v[214:215], v[56:57], v[56:57]
	v_pk_add_f32 v[200:201], v[200:201], v[200:201] op_sel_hi:[0,1]
	ds_swizzle_b32 v200, v220 offset:swizzle(SWAP,1)
	v_pk_mov_b32 v[218:219], v[216:217], v[214:215] op_sel:[1,0]
	v_mov_b32_e32 v217, v215
	v_pk_add_f32 v[214:215], v[218:219], v[216:217]
	v_pk_fma_f32 v[216:217], v[50:51], v[50:51], v[0:1] op_sel_hi:[1,1,0]
	v_mul_f32_e32 v0, v52, v52
	v_pk_fma_f32 v[218:219], v[52:53], v[52:53], v[0:1] op_sel_hi:[1,1,0]
	s_waitcnt lgkmcnt(0)
	v_add_f32_e32 v0, v220, v200
	ds_swizzle_b32 v220, v0 offset:swizzle(SWAP,2)
	v_pk_add_f32 v[214:215], v[214:215], v[214:215] op_sel_hi:[0,1]
	v_mul_f32_e32 v216, v46, v46
	v_mul_f32_e32 v218, v47, v47
	v_mul_f32_e32 v214, v48, v48
	s_waitcnt lgkmcnt(0)
	v_add_f32_e32 v0, v0, v220
	ds_swizzle_b32 v220, v0 offset:swizzle(SWAP,4)
	v_mul_f32_e32 v200, v49, v49
	v_pk_add_f32 v[216:217], v[216:217], v[218:219]
	v_pk_add_f32 v[200:201], v[214:215], v[200:201]
	v_pk_mul_f32 v[214:215], v[44:45], v[44:45]
	v_pk_add_f32 v[200:201], v[216:217], v[200:201]
	s_waitcnt lgkmcnt(0)
	v_add_f32_e32 v0, v0, v220
	v_pk_add_f32 v[200:201], v[200:201], v[200:201] op_sel_hi:[0,1]
	ds_swizzle_b32 v200, v0 offset:swizzle(SWAP,8)
	v_pk_mul_f32 v[216:217], v[42:43], v[42:43]
	s_waitcnt lgkmcnt(0)
	v_add_f32_e32 v200, v0, v200
	ds_swizzle_b32 v220, v200 offset:swizzle(SWAP,16)
	v_pk_mov_b32 v[218:219], v[216:217], v[214:215] op_sel:[1,0]
	v_mov_b32_e32 v217, v215
	v_pk_add_f32 v[214:215], v[218:219], v[216:217]
	v_mul_f32_e32 v0, v38, v38
	v_pk_add_f32 v[214:215], v[214:215], v[214:215] op_sel_hi:[0,1]
	s_waitcnt lgkmcnt(0)
	v_add_f32_e32 v200, v200, v220
	ds_bpermute_b32 v214, v213, v200
	v_pk_fma_f32 v[216:217], v[38:39], v[38:39], v[0:1] op_sel_hi:[1,1,0]
	v_mul_f32_e32 v0, v40, v40
	v_pk_fma_f32 v[218:219], v[40:41], v[40:41], v[0:1] op_sel_hi:[1,1,0]
	v_mul_f32_e32 v216, v34, v34
	s_waitcnt lgkmcnt(0)
; __device__ __forceinline__ unsigned cvt_pk_bf16(float lo, float hi) { unsigned r; asm volatile("v_cvt_pk_bf16_f32 %0, %1, %2" : "=v"(r) : "v"(lo), "v"(hi)); return r; }
; template <int M> __device__ __forceinline__ float swz_xor(float v) { return __builtin_bit_cast(float, __builtin_amdgcn_ds_swizzle(__builtin_bit_cast(int, v), (M << 10) | 0x1F)); }
; __device__ __forceinline__ float wave_sum(float v) {
;     v += swz_xor<1>(v); v += swz_xor<2>(v); v += swz_xor<4>(v); v += swz_xor<8>(v); v += swz_xor<16>(v);
;     return v + __shfl_xor(v, 32);
; }
; __device__ __forceinline__ void norm_rows(const float* x, bf16_t* H, const float* g, const float* modl, int sh_off, int sc_off, int gw, int NGW, int lane, bool stream) {
;     ...
;             for (int q = 0; q < 4; ++q) { const float r = 1.0f / sqrtf(wave_sum(s[q]) * (1.0f / DM) + EPS);
;                 u32x2* o = (u32x2*)(H + (size_t)(rbase + k + q) * DM) + lane;
; #pragma unroll
;                 for (int j = 0; j < 8; ++j) { const f32x4 a = (v[q][j] * r) * gp[j] + sp[j]; u32x2 w; w.x = cvt_pk_bf16(a[0], a[1]); w.y = cvt_pk_bf16(a[2], a[3]); o[64 * j] = w; } }
	v_add_f32_e32 v0, v200, v214
	v_fmamk_f32 v0, v0, 0x3a000000, v203
	v_mul_f32_e32 v200, 0x4f800000, v0
	v_cmp_gt_f32_e32 vcc, s91, v0
	v_mul_f32_e32 v218, v35, v35
	v_pk_add_f32 v[216:217], v[216:217], v[218:219]
	v_cndmask_b32_e32 v0, v0, v200, vcc
	v_sqrt_f32_e32 v220, v0
	v_mul_f32_e32 v214, v36, v36
	v_mul_f32_e32 v200, v37, v37
	v_pk_add_f32 v[200:201], v[214:215], v[200:201]
	v_add_u32_e32 v218, -1, v220
	v_fma_f32 v219, -v218, v220, v0
	v_cmp_ge_f32_e64 s[0:1], 0, v219
	v_add_u32_e32 v219, 1, v220
	v_pk_add_f32 v[200:201], v[216:217], v[200:201]
	v_cndmask_b32_e64 v218, v220, v218, s[0:1]
	v_fma_f32 v220, -v219, v220, v0
	v_cmp_lt_f32_e64 s[0:1], 0, v220
	v_add_f32_e32 v214, v200, v201
	s_nop 0
	v_cndmask_b32_e64 v218, v218, v219, s[0:1]
	v_mul_f32_e32 v219, 0x37800000, v218
	v_cndmask_b32_e32 v218, v218, v219, vcc
	v_cmp_class_f32_e32 vcc, v0, v204
	s_nop 1
	v_cndmask_b32_e32 v0, v218, v0, vcc
	v_div_scale_f32 v218, s[0:1], v0, v0, 1.0
	v_rcp_f32_e32 v219, v218
	v_readlane_b32 s0, v251, 33
	v_readlane_b32 s1, v251, 34
	v_fma_f32 v200, -v218, v219, 1.0
	v_fmac_f32_e32 v219, v200, v219
	v_div_scale_f32 v200, vcc, 1.0, v0, 1.0
	v_mul_f32_e32 v201, v200, v219
	v_fma_f32 v215, -v218, v201, v200
	v_fmac_f32_e32 v201, v215, v219
	v_fma_f32 v200, -v218, v201, v200
	v_div_fmas_f32 v200, v200, v219, v201
	v_div_fixup_f32 v0, v200, v0, 1.0
	v_pk_mul_f32 v[158:159], v[158:159], v[0:1] op_sel_hi:[1,0]
	v_pk_mul_f32 v[154:155], v[154:155], v[0:1] op_sel_hi:[1,0]
	v_pk_mul_f32 v[150:151], v[150:151], v[0:1] op_sel_hi:[1,0]
	v_lshl_add_u64 v[200:201], v[198:199], 0, s[0:1]
	v_pk_mul_f32 v[160:161], v[160:161], v[0:1] op_sel_hi:[1,0]
	v_pk_fma_f32 v[158:159], v[196:197], v[158:159], v[30:31]
	v_pk_mul_f32 v[156:157], v[156:157], v[0:1] op_sel_hi:[1,0]
	v_pk_fma_f32 v[154:155], v[192:193], v[154:155], v[26:27]
	v_pk_fma_f32 v[150:151], v[188:189], v[150:151], v[22:23]
	v_pk_fma_f32 v[160:161], v[194:195], v[160:161], v[32:33]
	v_cvt_pk_bf16_f32 v158, v158, v159
	v_pk_fma_f32 v[156:157], v[190:191], v[156:157], v[28:29]
	v_cvt_pk_bf16_f32 v159, v160, v161
	global_store_dwordx2 v[200:201], v[158:159], off
	v_cvt_pk_bf16_f32 v154, v154, v155
	v_cvt_pk_bf16_f32 v155, v156, v157
	global_store_dwordx2 v[200:201], v[154:155], off offset:512
	v_pk_mul_f32 v[152:153], v[152:153], v[0:1] op_sel_hi:[1,0]
	v_cvt_pk_bf16_f32 v150, v150, v151
	v_pk_mul_f32 v[146:147], v[146:147], v[0:1] op_sel_hi:[1,0]
	v_pk_fma_f32 v[152:153], v[186:187], v[152:153], v[24:25]
	v_pk_fma_f32 v[146:147], v[184:185], v[146:147], v[18:19]
	v_cvt_pk_bf16_f32 v151, v152, v153
	global_store_dwordx2 v[200:201], v[150:151], off offset:1024
	ds_swizzle_b32 v150, v221 offset:swizzle(SWAP,1)
	v_pk_mul_f32 v[148:149], v[148:149], v[0:1] op_sel_hi:[1,0]
	v_cvt_pk_bf16_f32 v146, v146, v147
	v_pk_mul_f32 v[142:143], v[142:143], v[0:1] op_sel_hi:[1,0]
	v_pk_fma_f32 v[148:149], v[182:183], v[148:149], v[20:21]
	v_pk_mul_f32 v[144:145], v[144:145], v[0:1] op_sel_hi:[1,0]
	v_cvt_pk_bf16_f32 v147, v148, v149
	global_store_dwordx2 v[200:201], v[146:147], off offset:1536
	s_waitcnt lgkmcnt(0)
	v_add_f32_e32 v146, v221, v150
	ds_swizzle_b32 v147, v146 offset:swizzle(SWAP,2)
	v_pk_fma_f32 v[144:145], v[174:175], v[144:145], v[16:17]
	v_pk_fma_f32 v[142:143], v[176:177], v[142:143], v[14:15]
	v_pk_mul_f32 v[138:139], v[138:139], v[0:1] op_sel_hi:[1,0]
	v_cvt_pk_bf16_f32 v142, v142, v143
	v_cvt_pk_bf16_f32 v143, v144, v145
	s_waitcnt lgkmcnt(0)
	v_add_f32_e32 v144, v146, v147
	ds_swizzle_b32 v145, v144 offset:swizzle(SWAP,4)
	global_store_dwordx2 v[200:201], v[142:143], off offset:2048
	v_pk_fma_f32 v[138:139], v[172:173], v[138:139], v[10:11]
	v_pk_mul_f32 v[140:141], v[140:141], v[0:1] op_sel_hi:[1,0]
	v_cvt_pk_bf16_f32 v138, v138, v139
	s_waitcnt lgkmcnt(0)
	v_add_f32_e32 v142, v144, v145
	ds_swizzle_b32 v143, v142 offset:swizzle(SWAP,8)
	v_pk_fma_f32 v[140:141], v[170:171], v[140:141], v[12:13]
	v_pk_mul_f32 v[134:135], v[134:135], v[0:1] op_sel_hi:[1,0]
	v_cvt_pk_bf16_f32 v139, v140, v141
	global_store_dwordx2 v[200:201], v[138:139], off offset:2560
	s_waitcnt lgkmcnt(0)
	v_add_f32_e32 v138, v142, v143
	ds_swizzle_b32 v139, v138 offset:swizzle(SWAP,16)
	v_pk_fma_f32 v[134:135], v[168:169], v[134:135], v[6:7]
	v_pk_mul_f32 v[136:137], v[136:137], v[0:1] op_sel_hi:[1,0]
	v_cvt_pk_bf16_f32 v134, v134, v135
	v_pk_mul_f32 v[130:131], v[130:131], v[0:1] op_sel_hi:[1,0]
	s_waitcnt lgkmcnt(0)
	v_add_f32_e32 v138, v138, v139
	ds_bpermute_b32 v139, v213, v138
	v_pk_fma_f32 v[136:137], v[166:167], v[136:137], v[8:9]
	v_pk_mul_f32 v[132:133], v[132:133], v[0:1] op_sel_hi:[1,0]
	v_cvt_pk_bf16_f32 v135, v136, v137
	global_store_dwordx2 v[200:201], v[134:135], off offset:3072
	s_waitcnt lgkmcnt(0)
; __device__ __forceinline__ unsigned cvt_pk_bf16(float lo, float hi) { unsigned r; asm volatile("v_cvt_pk_bf16_f32 %0, %1, %2" : "=v"(r) : "v"(lo), "v"(hi)); return r; }
; template <int M> __device__ __forceinline__ float swz_xor(float v) { return __builtin_bit_cast(float, __builtin_amdgcn_ds_swizzle(__builtin_bit_cast(int, v), (M << 10) | 0x1F)); }
; __device__ __forceinline__ float wave_sum(float v) {
;     v += swz_xor<1>(v); v += swz_xor<2>(v); v += swz_xor<4>(v); v += swz_xor<8>(v); v += swz_xor<16>(v);
;     return v + __shfl_xor(v, 32);
; }
; __device__ __forceinline__ void norm_rows(const float* x, bf16_t* H, const float* g, const float* modl, int sh_off, int sc_off, int gw, int NGW, int lane, bool stream) {
;     ...
;             for (int q = 0; q < 4; ++q) { const float r = 1.0f / sqrtf(wave_sum(s[q]) * (1.0f / DM) + EPS);
;                 u32x2* o = (u32x2*)(H + (size_t)(rbase + k + q) * DM) + lane;
; #pragma unroll
;                 for (int j = 0; j < 8; ++j) { const f32x4 a = (v[q][j] * r) * gp[j] + sp[j]; u32x2 w; w.x = cvt_pk_bf16(a[0], a[1]); w.y = cvt_pk_bf16(a[2], a[3]); o[64 * j] = w; } }
	v_add_f32_e32 v134, v138, v139
	v_fmamk_f32 v134, v134, 0x3a000000, v203
	v_mul_f32_e32 v135, 0x4f800000, v134
	v_cmp_gt_f32_e32 vcc, s91, v134
	v_pk_fma_f32 v[130:131], v[164:165], v[130:131], v[2:3]
	v_pk_fma_f32 v[132:133], v[162:163], v[132:133], v[4:5]
	v_cndmask_b32_e32 v134, v134, v135, vcc
	v_sqrt_f32_e32 v135, v134
	v_cvt_pk_bf16_f32 v130, v130, v131
	v_cvt_pk_bf16_f32 v131, v132, v133
	global_store_dwordx2 v[200:201], v[130:131], off offset:3584
	v_add_u32_e32 v0, -1, v135
	v_fma_f32 v136, -v0, v135, v134
	v_cmp_ge_f32_e64 s[0:1], 0, v136
	v_add_u32_e32 v136, 1, v135
	s_nop 0
	v_cndmask_b32_e64 v0, v135, v0, s[0:1]
	v_fma_f32 v135, -v136, v135, v134
	v_cmp_lt_f32_e64 s[0:1], 0, v135
	s_nop 1
	v_cndmask_b32_e64 v0, v0, v136, s[0:1]
	v_mul_f32_e32 v135, 0x37800000, v0
	v_cndmask_b32_e32 v0, v0, v135, vcc
	v_cmp_class_f32_e32 vcc, v134, v204
	s_nop 1
	v_cndmask_b32_e32 v0, v0, v134, vcc
	v_div_scale_f32 v134, s[0:1], v0, v0, 1.0
	v_rcp_f32_e32 v135, v134
	v_readlane_b32 s0, v251, 35
	v_readlane_b32 s1, v251, 36
	v_fma_f32 v130, -v134, v135, 1.0
	v_fmac_f32_e32 v135, v130, v135
	v_div_scale_f32 v130, vcc, 1.0, v0, 1.0
	v_mul_f32_e32 v131, v130, v135
	v_fma_f32 v132, -v134, v131, v130
	v_fmac_f32_e32 v131, v132, v135
	v_fma_f32 v130, -v134, v131, v130
	v_div_fmas_f32 v130, v130, v135, v131
	v_div_fixup_f32 v0, v130, v0, 1.0
	v_pk_mul_f32 v[126:127], v[126:127], v[0:1] op_sel_hi:[1,0]
	v_pk_mul_f32 v[122:123], v[122:123], v[0:1] op_sel_hi:[1,0]
	v_pk_mul_f32 v[118:119], v[118:119], v[0:1] op_sel_hi:[1,0]
	v_lshl_add_u64 v[130:131], v[198:199], 0, s[0:1]
	v_pk_mul_f32 v[128:129], v[128:129], v[0:1] op_sel_hi:[1,0]
	v_pk_fma_f32 v[126:127], v[196:197], v[126:127], v[30:31]
	v_pk_mul_f32 v[124:125], v[124:125], v[0:1] op_sel_hi:[1,0]
	v_pk_fma_f32 v[122:123], v[192:193], v[122:123], v[26:27]
	v_pk_fma_f32 v[118:119], v[188:189], v[118:119], v[22:23]
	v_pk_fma_f32 v[128:129], v[194:195], v[128:129], v[32:33]
	v_cvt_pk_bf16_f32 v126, v126, v127
	v_pk_fma_f32 v[124:125], v[190:191], v[124:125], v[28:29]
	v_cvt_pk_bf16_f32 v127, v128, v129
	global_store_dwordx2 v[130:131], v[126:127], off
	v_cvt_pk_bf16_f32 v122, v122, v123
	v_cvt_pk_bf16_f32 v123, v124, v125
	global_store_dwordx2 v[130:131], v[122:123], off offset:512
	v_pk_mul_f32 v[120:121], v[120:121], v[0:1] op_sel_hi:[1,0]
	v_cvt_pk_bf16_f32 v118, v118, v119
	v_pk_mul_f32 v[114:115], v[114:115], v[0:1] op_sel_hi:[1,0]
	v_pk_fma_f32 v[120:121], v[186:187], v[120:121], v[24:25]
	v_pk_fma_f32 v[114:115], v[184:185], v[114:115], v[18:19]
	v_cvt_pk_bf16_f32 v119, v120, v121
	global_store_dwordx2 v[130:131], v[118:119], off offset:1024
	ds_swizzle_b32 v118, v222 offset:swizzle(SWAP,1)
	v_pk_mul_f32 v[116:117], v[116:117], v[0:1] op_sel_hi:[1,0]
	v_cvt_pk_bf16_f32 v114, v114, v115
	v_pk_mul_f32 v[110:111], v[110:111], v[0:1] op_sel_hi:[1,0]
	v_pk_fma_f32 v[116:117], v[182:183], v[116:117], v[20:21]
	v_pk_mul_f32 v[112:113], v[112:113], v[0:1] op_sel_hi:[1,0]
	v_cvt_pk_bf16_f32 v115, v116, v117
	global_store_dwordx2 v[130:131], v[114:115], off offset:1536
	s_waitcnt lgkmcnt(0)
	v_add_f32_e32 v114, v222, v118
	ds_swizzle_b32 v115, v114 offset:swizzle(SWAP,2)
	v_pk_fma_f32 v[112:113], v[174:175], v[112:113], v[16:17]
	v_pk_fma_f32 v[110:111], v[176:177], v[110:111], v[14:15]
	v_pk_mul_f32 v[106:107], v[106:107], v[0:1] op_sel_hi:[1,0]
	v_cvt_pk_bf16_f32 v110, v110, v111
	v_cvt_pk_bf16_f32 v111, v112, v113
	s_waitcnt lgkmcnt(0)
	v_add_f32_e32 v112, v114, v115
	ds_swizzle_b32 v113, v112 offset:swizzle(SWAP,4)
	global_store_dwordx2 v[130:131], v[110:111], off offset:2048
	v_pk_fma_f32 v[106:107], v[172:173], v[106:107], v[10:11]
	v_pk_mul_f32 v[108:109], v[108:109], v[0:1] op_sel_hi:[1,0]
	v_cvt_pk_bf16_f32 v106, v106, v107
	s_waitcnt lgkmcnt(0)
	v_add_f32_e32 v110, v112, v113
	ds_swizzle_b32 v111, v110 offset:swizzle(SWAP,8)
	v_pk_fma_f32 v[108:109], v[170:171], v[108:109], v[12:13]
	v_pk_mul_f32 v[102:103], v[102:103], v[0:1] op_sel_hi:[1,0]
	v_cvt_pk_bf16_f32 v107, v108, v109
	global_store_dwordx2 v[130:131], v[106:107], off offset:2560
	s_waitcnt lgkmcnt(0)
	v_add_f32_e32 v106, v110, v111
	ds_swizzle_b32 v107, v106 offset:swizzle(SWAP,16)
	v_pk_fma_f32 v[102:103], v[168:169], v[102:103], v[6:7]
	v_pk_mul_f32 v[104:105], v[104:105], v[0:1] op_sel_hi:[1,0]
	v_cvt_pk_bf16_f32 v102, v102, v103
	v_pk_mul_f32 v[98:99], v[98:99], v[0:1] op_sel_hi:[1,0]
	s_waitcnt lgkmcnt(0)
	v_add_f32_e32 v106, v106, v107
	ds_bpermute_b32 v107, v213, v106
	v_pk_fma_f32 v[104:105], v[166:167], v[104:105], v[8:9]
	v_pk_mul_f32 v[100:101], v[100:101], v[0:1] op_sel_hi:[1,0]
	v_cvt_pk_bf16_f32 v103, v104, v105
	global_store_dwordx2 v[130:131], v[102:103], off offset:3072
	s_waitcnt lgkmcnt(0)
; __device__ __forceinline__ unsigned cvt_pk_bf16(float lo, float hi) { unsigned r; asm volatile("v_cvt_pk_bf16_f32 %0, %1, %2" : "=v"(r) : "v"(lo), "v"(hi)); return r; }
; template <int M> __device__ __forceinline__ float swz_xor(float v) { return __builtin_bit_cast(float, __builtin_amdgcn_ds_swizzle(__builtin_bit_cast(int, v), (M << 10) | 0x1F)); }
; __device__ __forceinline__ float wave_sum(float v) {
;     v += swz_xor<1>(v); v += swz_xor<2>(v); v += swz_xor<4>(v); v += swz_xor<8>(v); v += swz_xor<16>(v);
;     return v + __shfl_xor(v, 32);
; }
; __device__ __forceinline__ void norm_rows(const float* x, bf16_t* H, const float* g, const float* modl, int sh_off, int sc_off, int gw, int NGW, int lane, bool stream) {
;     ...
;             for (int q = 0; q < 4; ++q) { const float r = 1.0f / sqrtf(wave_sum(s[q]) * (1.0f / DM) + EPS);
;                 u32x2* o = (u32x2*)(H + (size_t)(rbase + k + q) * DM) + lane;
; #pragma unroll
;                 for (int j = 0; j < 8; ++j) { const f32x4 a = (v[q][j] * r) * gp[j] + sp[j]; u32x2 w; w.x = cvt_pk_bf16(a[0], a[1]); w.y = cvt_pk_bf16(a[2], a[3]); o[64 * j] = w; } }
	v_add_f32_e32 v102, v106, v107
	v_fmamk_f32 v102, v102, 0x3a000000, v203
	v_mul_f32_e32 v103, 0x4f800000, v102
	v_cmp_gt_f32_e32 vcc, s91, v102
	v_pk_fma_f32 v[98:99], v[164:165], v[98:99], v[2:3]
	v_pk_fma_f32 v[100:101], v[162:163], v[100:101], v[4:5]
	v_cndmask_b32_e32 v102, v102, v103, vcc
	v_sqrt_f32_e32 v103, v102
	v_cvt_pk_bf16_f32 v98, v98, v99
	v_cvt_pk_bf16_f32 v99, v100, v101
	global_store_dwordx2 v[130:131], v[98:99], off offset:3584
	v_add_u32_e32 v0, -1, v103
	v_fma_f32 v104, -v0, v103, v102
	v_cmp_ge_f32_e64 s[0:1], 0, v104
	v_add_u32_e32 v104, 1, v103
	s_nop 0
	v_cndmask_b32_e64 v0, v103, v0, s[0:1]
	v_fma_f32 v103, -v104, v103, v102
	v_cmp_lt_f32_e64 s[0:1], 0, v103
	s_nop 1
	v_cndmask_b32_e64 v0, v0, v104, s[0:1]
	v_mul_f32_e32 v103, 0x37800000, v0
	v_cndmask_b32_e32 v0, v0, v103, vcc
	v_cmp_class_f32_e32 vcc, v102, v204
	s_nop 1
	v_cndmask_b32_e32 v0, v0, v102, vcc
	v_div_scale_f32 v102, s[0:1], v0, v0, 1.0
	v_rcp_f32_e32 v103, v102
	v_readlane_b32 s0, v251, 37
	v_readlane_b32 s1, v251, 38
	v_fma_f32 v98, -v102, v103, 1.0
	v_fmac_f32_e32 v103, v98, v103
	v_div_scale_f32 v98, vcc, 1.0, v0, 1.0
	v_mul_f32_e32 v99, v98, v103
	v_fma_f32 v100, -v102, v99, v98
	v_fmac_f32_e32 v99, v100, v103
	v_fma_f32 v98, -v102, v99, v98
	v_div_fmas_f32 v98, v98, v103, v99
	v_div_fixup_f32 v0, v98, v0, 1.0
	v_pk_mul_f32 v[94:95], v[94:95], v[0:1] op_sel_hi:[1,0]
	v_pk_mul_f32 v[90:91], v[90:91], v[0:1] op_sel_hi:[1,0]
	v_pk_mul_f32 v[86:87], v[86:87], v[0:1] op_sel_hi:[1,0]
	v_lshl_add_u64 v[98:99], v[198:199], 0, s[0:1]
	v_pk_mul_f32 v[96:97], v[96:97], v[0:1] op_sel_hi:[1,0]
	v_pk_fma_f32 v[94:95], v[196:197], v[94:95], v[30:31]
	v_pk_mul_f32 v[92:93], v[92:93], v[0:1] op_sel_hi:[1,0]
	v_pk_fma_f32 v[90:91], v[192:193], v[90:91], v[26:27]
	v_pk_fma_f32 v[86:87], v[188:189], v[86:87], v[22:23]
	v_pk_fma_f32 v[96:97], v[194:195], v[96:97], v[32:33]
	v_cvt_pk_bf16_f32 v94, v94, v95
	v_pk_fma_f32 v[92:93], v[190:191], v[92:93], v[28:29]
	v_cvt_pk_bf16_f32 v95, v96, v97
	global_store_dwordx2 v[98:99], v[94:95], off
	v_cvt_pk_bf16_f32 v90, v90, v91
	v_cvt_pk_bf16_f32 v91, v92, v93
	global_store_dwordx2 v[98:99], v[90:91], off offset:512
	v_pk_mul_f32 v[88:89], v[88:89], v[0:1] op_sel_hi:[1,0]
	v_cvt_pk_bf16_f32 v86, v86, v87
	v_pk_mul_f32 v[82:83], v[82:83], v[0:1] op_sel_hi:[1,0]
	v_pk_fma_f32 v[88:89], v[186:187], v[88:89], v[24:25]
	v_pk_fma_f32 v[82:83], v[184:185], v[82:83], v[18:19]
	v_cvt_pk_bf16_f32 v87, v88, v89
	global_store_dwordx2 v[98:99], v[86:87], off offset:1024
	ds_swizzle_b32 v86, v214 offset:swizzle(SWAP,1)
	v_pk_mul_f32 v[84:85], v[84:85], v[0:1] op_sel_hi:[1,0]
	v_cvt_pk_bf16_f32 v82, v82, v83
	v_pk_mul_f32 v[78:79], v[78:79], v[0:1] op_sel_hi:[1,0]
	v_pk_fma_f32 v[84:85], v[182:183], v[84:85], v[20:21]
	v_pk_mul_f32 v[80:81], v[80:81], v[0:1] op_sel_hi:[1,0]
	v_cvt_pk_bf16_f32 v83, v84, v85
	global_store_dwordx2 v[98:99], v[82:83], off offset:1536
	s_waitcnt lgkmcnt(0)
	v_add_f32_e32 v82, v214, v86
	ds_swizzle_b32 v83, v82 offset:swizzle(SWAP,2)
	v_pk_fma_f32 v[80:81], v[174:175], v[80:81], v[16:17]
	v_pk_fma_f32 v[78:79], v[176:177], v[78:79], v[14:15]
	v_pk_mul_f32 v[74:75], v[74:75], v[0:1] op_sel_hi:[1,0]
	v_cvt_pk_bf16_f32 v78, v78, v79
	v_cvt_pk_bf16_f32 v79, v80, v81
	s_waitcnt lgkmcnt(0)
	v_add_f32_e32 v80, v82, v83
	ds_swizzle_b32 v81, v80 offset:swizzle(SWAP,4)
	global_store_dwordx2 v[98:99], v[78:79], off offset:2048
	v_pk_fma_f32 v[74:75], v[172:173], v[74:75], v[10:11]
	v_pk_mul_f32 v[76:77], v[76:77], v[0:1] op_sel_hi:[1,0]
	v_cvt_pk_bf16_f32 v74, v74, v75
	s_waitcnt lgkmcnt(0)
	v_add_f32_e32 v78, v80, v81
	ds_swizzle_b32 v79, v78 offset:swizzle(SWAP,8)
	v_pk_fma_f32 v[76:77], v[170:171], v[76:77], v[12:13]
	v_pk_mul_f32 v[70:71], v[70:71], v[0:1] op_sel_hi:[1,0]
	v_cvt_pk_bf16_f32 v75, v76, v77
	global_store_dwordx2 v[98:99], v[74:75], off offset:2560
	s_waitcnt lgkmcnt(0)
	v_add_f32_e32 v74, v78, v79
	ds_swizzle_b32 v75, v74 offset:swizzle(SWAP,16)
	v_pk_fma_f32 v[70:71], v[168:169], v[70:71], v[6:7]
	v_pk_mul_f32 v[72:73], v[72:73], v[0:1] op_sel_hi:[1,0]
	v_cvt_pk_bf16_f32 v70, v70, v71
	v_pk_mul_f32 v[66:67], v[66:67], v[0:1] op_sel_hi:[1,0]
	s_waitcnt lgkmcnt(0)
; __device__ __forceinline__ unsigned cvt_pk_bf16(float lo, float hi) { unsigned r; asm volatile("v_cvt_pk_bf16_f32 %0, %1, %2" : "=v"(r) : "v"(lo), "v"(hi)); return r; }
; template <int M> __device__ __forceinline__ float swz_xor(float v) { return __builtin_bit_cast(float, __builtin_amdgcn_ds_swizzle(__builtin_bit_cast(int, v), (M << 10) | 0x1F)); }
; __device__ __forceinline__ float wave_sum(float v) {
;     v += swz_xor<1>(v); v += swz_xor<2>(v); v += swz_xor<4>(v); v += swz_xor<8>(v); v += swz_xor<16>(v);
;     return v + __shfl_xor(v, 32);
; }
; __device__ __forceinline__ void norm_rows(const float* x, bf16_t* H, const float* g, const float* modl, int sh_off, int sc_off, int gw, int NGW, int lane, bool stream) {
;     ...
;             for (int q = 0; q < 4; ++q) { const float r = 1.0f / sqrtf(wave_sum(s[q]) * (1.0f / DM) + EPS);
;                 u32x2* o = (u32x2*)(H + (size_t)(rbase + k + q) * DM) + lane;
; #pragma unroll
;                 for (int j = 0; j < 8; ++j) { const f32x4 a = (v[q][j] * r) * gp[j] + sp[j]; u32x2 w; w.x = cvt_pk_bf16(a[0], a[1]); w.y = cvt_pk_bf16(a[2], a[3]); o[64 * j] = w; } }
;         }
	v_add_f32_e32 v74, v74, v75
	ds_bpermute_b32 v75, v213, v74
	v_pk_fma_f32 v[72:73], v[166:167], v[72:73], v[8:9]
	v_pk_mul_f32 v[68:69], v[68:69], v[0:1] op_sel_hi:[1,0]
	v_cvt_pk_bf16_f32 v71, v72, v73
	global_store_dwordx2 v[98:99], v[70:71], off offset:3072
	s_waitcnt lgkmcnt(0)
	v_add_f32_e32 v70, v74, v75
	v_fmamk_f32 v70, v70, 0x3a000000, v203
	v_mul_f32_e32 v71, 0x4f800000, v70
	v_cmp_gt_f32_e32 vcc, s91, v70
	v_pk_fma_f32 v[66:67], v[164:165], v[66:67], v[2:3]
	v_pk_fma_f32 v[68:69], v[162:163], v[68:69], v[4:5]
	v_cndmask_b32_e32 v70, v70, v71, vcc
	v_sqrt_f32_e32 v71, v70
	v_cvt_pk_bf16_f32 v66, v66, v67
	v_cvt_pk_bf16_f32 v67, v68, v69
	global_store_dwordx2 v[98:99], v[66:67], off offset:3584
	v_add_u32_e32 v0, -1, v71
	v_fma_f32 v72, -v0, v71, v70
	v_cmp_ge_f32_e64 s[0:1], 0, v72
	v_add_u32_e32 v72, 1, v71
	s_nop 0
	v_cndmask_b32_e64 v0, v71, v0, s[0:1]
	v_fma_f32 v71, -v72, v71, v70
	v_cmp_lt_f32_e64 s[0:1], 0, v71
	s_nop 1
	v_cndmask_b32_e64 v0, v0, v72, s[0:1]
	v_mul_f32_e32 v71, 0x37800000, v0
	v_cndmask_b32_e32 v0, v0, v71, vcc
	v_cmp_class_f32_e32 vcc, v70, v204
	s_nop 1
	v_cndmask_b32_e32 v0, v0, v70, vcc
	v_div_scale_f32 v70, s[0:1], v0, v0, 1.0
	v_rcp_f32_e32 v71, v70
	v_readlane_b32 s0, v251, 39
	v_readlane_b32 s1, v251, 40
	v_fma_f32 v66, -v70, v71, 1.0
	v_fmac_f32_e32 v71, v66, v71
	v_div_scale_f32 v66, vcc, 1.0, v0, 1.0
	v_mul_f32_e32 v67, v66, v71
	v_fma_f32 v68, -v70, v67, v66
	v_fmac_f32_e32 v67, v68, v71
	v_fma_f32 v66, -v70, v67, v66
	v_div_fmas_f32 v66, v66, v71, v67
	v_div_fixup_f32 v0, v66, v0, 1.0
	v_pk_mul_f32 v[62:63], v[62:63], v[0:1] op_sel_hi:[1,0]
	v_pk_mul_f32 v[64:65], v[64:65], v[0:1] op_sel_hi:[1,0]
	v_pk_fma_f32 v[30:31], v[196:197], v[62:63], v[30:31]
	v_lshl_add_u64 v[66:67], v[198:199], 0, s[0:1]
	v_pk_fma_f32 v[32:33], v[194:195], v[64:65], v[32:33]
	v_cvt_pk_bf16_f32 v30, v30, v31
	s_nop 0
	v_cvt_pk_bf16_f32 v31, v32, v33
	global_store_dwordx2 v[66:67], v[30:31], off
	v_pk_mul_f32 v[30:31], v[58:59], v[0:1] op_sel_hi:[1,0]
	v_pk_mul_f32 v[32:33], v[60:61], v[0:1] op_sel_hi:[1,0]
	v_pk_fma_f32 v[26:27], v[192:193], v[30:31], v[26:27]
	v_pk_fma_f32 v[28:29], v[190:191], v[32:33], v[28:29]
	v_cvt_pk_bf16_f32 v26, v26, v27
	s_nop 0
	v_cvt_pk_bf16_f32 v27, v28, v29
	global_store_dwordx2 v[66:67], v[26:27], off offset:512
	v_pk_mul_f32 v[26:27], v[54:55], v[0:1] op_sel_hi:[1,0]
	v_pk_mul_f32 v[28:29], v[56:57], v[0:1] op_sel_hi:[1,0]
	v_pk_fma_f32 v[22:23], v[188:189], v[26:27], v[22:23]
	v_pk_fma_f32 v[24:25], v[186:187], v[28:29], v[24:25]
	v_cvt_pk_bf16_f32 v22, v22, v23
	s_nop 0
	v_cvt_pk_bf16_f32 v23, v24, v25
	global_store_dwordx2 v[66:67], v[22:23], off offset:1024
	v_pk_mul_f32 v[22:23], v[50:51], v[0:1] op_sel_hi:[1,0]
	v_pk_mul_f32 v[24:25], v[52:53], v[0:1] op_sel_hi:[1,0]
	v_pk_fma_f32 v[18:19], v[184:185], v[22:23], v[18:19]
	v_pk_fma_f32 v[20:21], v[182:183], v[24:25], v[20:21]
	v_cvt_pk_bf16_f32 v18, v18, v19
	s_nop 0
	v_cvt_pk_bf16_f32 v19, v20, v21
	global_store_dwordx2 v[66:67], v[18:19], off offset:1536
	v_pk_mul_f32 v[18:19], v[46:47], v[0:1] op_sel_hi:[1,0]
	v_pk_mul_f32 v[20:21], v[48:49], v[0:1] op_sel_hi:[1,0]
	v_pk_fma_f32 v[14:15], v[176:177], v[18:19], v[14:15]
	v_pk_fma_f32 v[16:17], v[174:175], v[20:21], v[16:17]
	v_cvt_pk_bf16_f32 v14, v14, v15
	s_nop 0
	v_cvt_pk_bf16_f32 v15, v16, v17
	global_store_dwordx2 v[66:67], v[14:15], off offset:2048
	v_pk_mul_f32 v[14:15], v[42:43], v[0:1] op_sel_hi:[1,0]
	v_pk_mul_f32 v[16:17], v[44:45], v[0:1] op_sel_hi:[1,0]
	v_pk_fma_f32 v[10:11], v[172:173], v[14:15], v[10:11]
	v_pk_fma_f32 v[12:13], v[170:171], v[16:17], v[12:13]
	v_cvt_pk_bf16_f32 v10, v10, v11
	s_nop 0
	v_cvt_pk_bf16_f32 v11, v12, v13
	global_store_dwordx2 v[66:67], v[10:11], off offset:2560
	v_pk_mul_f32 v[10:11], v[38:39], v[0:1] op_sel_hi:[1,0]
	v_pk_mul_f32 v[12:13], v[40:41], v[0:1] op_sel_hi:[1,0]
	v_pk_fma_f32 v[6:7], v[168:169], v[10:11], v[6:7]
	v_pk_fma_f32 v[8:9], v[166:167], v[12:13], v[8:9]
	v_cvt_pk_bf16_f32 v6, v6, v7
	s_nop 0
	v_cvt_pk_bf16_f32 v7, v8, v9
	global_store_dwordx2 v[66:67], v[6:7], off offset:3072
	v_pk_mul_f32 v[6:7], v[34:35], v[0:1] op_sel_hi:[1,0]
	v_pk_mul_f32 v[8:9], v[36:37], v[0:1] op_sel_hi:[1,0]
	v_pk_fma_f32 v[2:3], v[164:165], v[6:7], v[2:3]
	v_pk_fma_f32 v[4:5], v[162:163], v[8:9], v[4:5]
	v_cvt_pk_bf16_f32 v2, v2, v3
	s_nop 0
	v_cvt_pk_bf16_f32 v3, v4, v5
	global_store_dwordx2 v[66:67], v[2:3], off offset:3584
